# removed redundant s_setprio 0/1 toggle pairs in the middle of MFMA blocks (priority unchanged); on top of v17
# speedup vs baseline: 1.0017x; 1.0017x over previous
; #define PG8_STAGE(bufoff, gbase, voff) do { _Pragma("unroll") for (int _i = 0; _i < 2; ++_i) \
;         __builtin_amdgcn_global_load_lds((const unsigned*)((const char*)(gbase) + (voff)[_i]), (PG8_LAS unsigned*)(lds + (bufoff) + ldsw + _i * 8192), 16, 0, 0); } while (0)
; #define PG8_LDA(dst, b, h) do { _Pragma("unroll") for (int m = 0; m < 4; ++m) _Pragma("unroll") for (int k = 0; k < 2; ++k) dst[m][k] = *(const PG8_LAS bf16x8*)(lds + PG8_SA(b, h) + aoff + m * 2048 + k * 1024); } while (0)
; #define PG8_LDB(dst, b, h) do { _Pragma("unroll") for (int n = 0; n < 2; ++n) _Pragma("unroll") for (int k = 0; k < 2; ++k) dst[n][k] = *(const PG8_LAS bf16x8*)(lds + PG8_SB(b, h) + boff + n * 2048 + k * 1024); } while (0)
; #define PG8_MMA(ai, bj, At, Bt) do { __builtin_amdgcn_s_setprio(1); _Pragma("unroll") for (int m = 0; m < 4; ++m) _Pragma("unroll") for (int n = 0; n < 2; ++n) _Pragma("unroll") for (int k = 0; k < 2; ++k) \
;         acc[ai][bj][m][n] = __builtin_amdgcn_mfma_f32_16x16x32_bf16(Bt[n][k], At[m][k], acc[ai][bj][m][n], 0, 0, 0); __builtin_amdgcn_s_setprio(0); } while (0)
; #define PG8_WAIT_V(n) asm volatile("s_waitcnt vmcnt(" #n ")" ::: "memory")
; template <class Epi, class Sched, bool ALIGN_EPI = false, bool SP2 = false>
; __device__ __forceinline__ void gemm_phase(PG8_LAS unsigned char* lds, const Gemm g, const Sched& S, const Epi& E) {
;     ...
;         const char* nA = has_next ? (const char*)g.A + (size_t)nxt.pm * tstep : cA; const char* nB = has_next ? (const char*)g.Bt + (size_t)nxt.pn * tstep : cB;
;         for (int t = 0; t < nt; t += 2) {
;             const bool last = (t == nt - 2);
;             const char* a1 = cA + (size_t)(t + 1) * kstep;
;             const char* a2 = last ? nA : cA + (size_t)(t + 2) * kstep; const char* b2 = last ? nB : cB + (size_t)(t + 2) * kstep;
;             const char* a3 = a2 + kstep; const char* b3 = b2 + kstep;
;             if (last && has_next) S.a_ready(nxt);
;             if constexpr (SP2) {
;             PG8_LDB(B0, 0, 0); PG8_LDB(B1, 0, 1); PG8_SCHED; PG8_LDA(At, 0, 0); PG8_STAGE(PG8_SA(1, 1), a1 + hstep, voffA);
;             PG8_WAIT_V(8); PG8_WAIT_L(0); PG8_BAR; PG8_MMA(0, 0, At, B0); PG8_MMA(0, 1, At, B1); PG8_BAR; PG8_SCHED;
;             PG8_LDA(At, 0, 1); PG8_STAGE(PG8_SB(0, 0), b2, voffB); PG8_STAGE(PG8_SB(0, 1), b2 + hstep, voffB); PG8_STAGE(PG8_SA(0, 0), a2, voffA);
.LBB0_224:
	s_ashr_i32 s15, s14, 31
	s_lshl_b64 s[16:17], s[14:15], 19
	s_add_u32 s16, s34, s16
	s_addc_u32 s17, s35, s17
	s_and_b64 s[18:19], s[2:3], exec
	s_cselect_b32 s5, s17, s23
	s_cselect_b32 s15, s16, s22
	s_ashr_i32 s13, s12, 31
	s_lshl_b64 s[18:19], s[12:13], 19
	s_add_u32 s18, s38, s18
	s_addc_u32 s19, s39, s19
	s_and_b64 s[26:27], s[2:3], exec
	s_cselect_b32 s13, s19, s25
	s_cselect_b32 s21, s18, s24
	s_add_u32 s22, s22, 0x40080
	s_addc_u32 s23, s23, 0
	s_add_u32 s49, s24, 0x100
	s_addc_u32 s50, s25, 0
	s_mov_b32 s51, -2
	s_add_u32 s24, s22, 0xfffc0080
	s_addc_u32 s25, s23, -1
	s_add_i32 s52, 0, 0x10000
	s_cmp_eq_u32 s51, 12
	s_cselect_b32 s27, s5, s25
	s_cselect_b32 s26, s15, s24
	v_add_u32_e32 v138, s52, v149
	s_cselect_b32 s25, s13, s50
	s_cselect_b32 s24, s21, s49
	s_add_i32 s55, 0, 0x14000
	ds_read_b128 v[144:147], v138
	ds_read_b128 v[154:157], v138 offset:1024
	ds_read_b128 v[158:161], v138 offset:2048
	ds_read_b128 v[162:165], v138 offset:3072
	v_add_u32_e32 v138, s55, v149
	ds_read_b128 v[166:169], v138
	ds_read_b128 v[170:173], v138 offset:1024
	ds_read_b128 v[174:177], v138 offset:2048
	ds_read_b128 v[178:181], v138 offset:3072
	v_lshl_add_u64 v[138:139], s[22:23], 0, v[136:137]
	s_add_i32 m0, s41, 0xc000
	ds_read_b128 v[182:185], v152
	ds_read_b128 v[186:189], v152 offset:1024
	ds_read_b128 v[190:193], v152 offset:2048
	ds_read_b128 v[194:197], v152 offset:3072
	ds_read_b128 v[198:201], v152 offset:4096
	ds_read_b128 v[202:205], v152 offset:5120
	ds_read_b128 v[224:227], v152 offset:6144
	ds_read_b128 v[228:231], v152 offset:7168
	global_load_lds_dwordx4 v[138:139], off
	v_lshl_add_u64 v[138:139], s[22:23], 0, v[142:143]
	s_add_i32 m0, s41, 0xe000
	s_nop 0
	global_load_lds_dwordx4 v[138:139], off
	s_waitcnt vmcnt(8)
	s_waitcnt lgkmcnt(0)
	s_barrier
	s_setprio 1
	s_waitcnt lgkmcnt(0)
	v_mfma_f32_16x16x32_bf16 v[126:129], v[144:147], v[182:185], 0
	v_mfma_f32_16x16x32_bf16 v[122:125], v[158:161], v[182:185], 0
	v_mfma_f32_16x16x32_bf16 v[110:113], v[144:147], v[190:193], 0
	v_mfma_f32_16x16x32_bf16 v[106:109], v[158:161], v[190:193], 0
	v_mfma_f32_16x16x32_bf16 v[94:97], v[144:147], v[198:201], 0
	v_mfma_f32_16x16x32_bf16 v[90:93], v[158:161], v[198:201], 0
	v_mfma_f32_16x16x32_bf16 v[78:81], v[144:147], v[224:227], 0
	v_mfma_f32_16x16x32_bf16 v[74:77], v[158:161], v[224:227], 0
	v_mfma_f32_16x16x32_bf16 v[126:129], v[154:157], v[186:189], v[126:129]
	v_mfma_f32_16x16x32_bf16 v[122:125], v[162:165], v[186:189], v[122:125]
	v_mfma_f32_16x16x32_bf16 v[110:113], v[154:157], v[194:197], v[110:113]
	v_mfma_f32_16x16x32_bf16 v[106:109], v[162:165], v[194:197], v[106:109]
	v_mfma_f32_16x16x32_bf16 v[94:97], v[154:157], v[202:205], v[94:97]
	v_mfma_f32_16x16x32_bf16 v[90:93], v[162:165], v[202:205], v[90:93]
	v_mfma_f32_16x16x32_bf16 v[78:81], v[154:157], v[228:231], v[78:81]
	v_mfma_f32_16x16x32_bf16 v[74:77], v[162:165], v[228:231], v[74:77]
	v_mfma_f32_16x16x32_bf16 v[118:121], v[166:169], v[182:185], 0
	v_mfma_f32_16x16x32_bf16 v[114:117], v[174:177], v[182:185], 0
	v_mfma_f32_16x16x32_bf16 v[102:105], v[166:169], v[190:193], 0
	v_mfma_f32_16x16x32_bf16 v[98:101], v[174:177], v[190:193], 0
	v_mfma_f32_16x16x32_bf16 v[86:89], v[166:169], v[198:201], 0
	v_mfma_f32_16x16x32_bf16 v[82:85], v[174:177], v[198:201], 0
	v_mfma_f32_16x16x32_bf16 v[70:73], v[166:169], v[224:227], 0
	v_mfma_f32_16x16x32_bf16 v[66:69], v[174:177], v[224:227], 0
	v_mfma_f32_16x16x32_bf16 v[118:121], v[170:173], v[186:189], v[118:121]
	v_mfma_f32_16x16x32_bf16 v[114:117], v[178:181], v[186:189], v[114:117]
	v_mfma_f32_16x16x32_bf16 v[102:105], v[170:173], v[194:197], v[102:105]
	v_mfma_f32_16x16x32_bf16 v[98:101], v[178:181], v[194:197], v[98:101]
	v_mfma_f32_16x16x32_bf16 v[86:89], v[170:173], v[202:205], v[86:89]
	v_mfma_f32_16x16x32_bf16 v[82:85], v[178:181], v[202:205], v[82:85]
	v_mfma_f32_16x16x32_bf16 v[70:73], v[170:173], v[228:231], v[70:73]
	v_mfma_f32_16x16x32_bf16 v[66:69], v[178:181], v[228:231], v[66:69]
	s_setprio 0
	s_barrier
	s_add_i32 s52, s52, s31
	v_lshl_add_u64 v[138:139], s[24:25], 0, v[0:1]
	s_mov_b32 m0, s52
	ds_read_b128 v[182:185], v152 offset:16384
	ds_read_b128 v[186:189], v152 offset:17408
	ds_read_b128 v[190:193], v152 offset:18432
	ds_read_b128 v[194:197], v152 offset:19456
	ds_read_b128 v[198:201], v152 offset:20480
	ds_read_b128 v[202:205], v152 offset:21504
	ds_read_b128 v[224:227], v152 offset:22528
	ds_read_b128 v[228:231], v152 offset:23552
	global_load_lds_dwordx4 v[138:139], off
	s_add_i32 m0, s52, 0x2000
	s_add_u32 s52, s24, 0x40000
	v_lshl_add_u64 v[140:141], s[24:25], 0, v[134:135]
	s_addc_u32 s53, s25, 0
	s_add_i32 s55, s55, s31
	global_load_lds_dwordx4 v[140:141], off
	v_lshl_add_u64 v[232:233], s[52:53], 0, v[0:1]
	s_mov_b32 m0, s55
	v_lshl_add_u64 v[234:235], s[26:27], 0, v[132:133]
	global_load_lds_dwordx4 v[232:233], off
	v_lshl_add_u64 v[232:233], s[52:53], 0, v[134:135]
	s_add_i32 m0, s55, 0x2000
	s_nop 0
	global_load_lds_dwordx4 v[232:233], off
	v_lshl_add_u64 v[232:233], s[26:27], 0, v[130:131]
	s_mov_b32 m0, s41
	s_nop 0
	global_load_lds_dwordx4 v[232:233], off
	s_mov_b32 m0, s42
	s_nop 0
	global_load_lds_dwordx4 v[234:235], off
	s_waitcnt vmcnt(8)
	s_waitcnt lgkmcnt(0)
	s_barrier
; #define PG8_STAGE(bufoff, gbase, voff) do { _Pragma("unroll") for (int _i = 0; _i < 2; ++_i) \
;         __builtin_amdgcn_global_load_lds((const unsigned*)((const char*)(gbase) + (voff)[_i]), (PG8_LAS unsigned*)(lds + (bufoff) + ldsw + _i * 8192), 16, 0, 0); } while (0)
; #define PG8_LDA(dst, b, h) do { _Pragma("unroll") for (int m = 0; m < 4; ++m) _Pragma("unroll") for (int k = 0; k < 2; ++k) dst[m][k] = *(const PG8_LAS bf16x8*)(lds + PG8_SA(b, h) + aoff + m * 2048 + k * 1024); } while (0)
; #define PG8_LDB(dst, b, h) do { _Pragma("unroll") for (int n = 0; n < 2; ++n) _Pragma("unroll") for (int k = 0; k < 2; ++k) dst[n][k] = *(const PG8_LAS bf16x8*)(lds + PG8_SB(b, h) + boff + n * 2048 + k * 1024); } while (0)
; #define PG8_MMA(ai, bj, At, Bt) do { __builtin_amdgcn_s_setprio(1); _Pragma("unroll") for (int m = 0; m < 4; ++m) _Pragma("unroll") for (int n = 0; n < 2; ++n) _Pragma("unroll") for (int k = 0; k < 2; ++k) \
;         acc[ai][bj][m][n] = __builtin_amdgcn_mfma_f32_16x16x32_bf16(Bt[n][k], At[m][k], acc[ai][bj][m][n], 0, 0, 0); __builtin_amdgcn_s_setprio(0); } while (0)
; #define PG8_WAIT_V(n) asm volatile("s_waitcnt vmcnt(" #n ")" ::: "memory")
; #define PG8_WAIT_L(n) asm volatile("s_waitcnt lgkmcnt(" #n ")" ::: "memory")
; #define PG8_BAR __builtin_amdgcn_s_barrier()
; #define PG8_SCHED __builtin_amdgcn_sched_barrier(0)
; template <class Epi, class Sched, bool ALIGN_EPI = false, bool SP2 = false>
; __device__ __forceinline__ void gemm_phase(PG8_LAS unsigned char* lds, const Gemm g, const Sched& S, const Epi& E) {
;     ...
;             PG8_LDA(At, 0, 1); PG8_STAGE(PG8_SB(0, 0), b2, voffB); PG8_STAGE(PG8_SB(0, 1), b2 + hstep, voffB); PG8_STAGE(PG8_SA(0, 0), a2, voffA);
;             PG8_WAIT_V(8); PG8_WAIT_L(0); PG8_BAR; PG8_MMA(1, 0, At, B0); PG8_MMA(1, 1, At, B1); PG8_BAR; PG8_SCHED;
;             PG8_LDB(B0, 1, 0); PG8_LDB(B1, 1, 1); PG8_SCHED; PG8_LDA(At, 1, 0); PG8_STAGE(PG8_SA(0, 1), a2 + hstep, voffA);
;             PG8_WAIT_V(8); PG8_WAIT_L(0); PG8_BAR; PG8_MMA(0, 0, At, B0); PG8_MMA(0, 1, At, B1); PG8_BAR; PG8_SCHED;
	s_setprio 1
	s_waitcnt lgkmcnt(0)
	v_mfma_f32_16x16x32_bf16 v[62:65], v[144:147], v[182:185], 0
	v_mfma_f32_16x16x32_bf16 v[58:61], v[158:161], v[182:185], 0
	v_mfma_f32_16x16x32_bf16 v[46:49], v[144:147], v[190:193], 0
	v_mfma_f32_16x16x32_bf16 v[42:45], v[158:161], v[190:193], 0
	v_mfma_f32_16x16x32_bf16 v[30:33], v[144:147], v[198:201], 0
	v_mfma_f32_16x16x32_bf16 v[26:29], v[158:161], v[198:201], 0
	v_mfma_f32_16x16x32_bf16 v[14:17], v[144:147], v[224:227], 0
	v_mfma_f32_16x16x32_bf16 v[10:13], v[158:161], v[224:227], 0
	v_mfma_f32_16x16x32_bf16 v[62:65], v[154:157], v[186:189], v[62:65]
	v_mfma_f32_16x16x32_bf16 v[58:61], v[162:165], v[186:189], v[58:61]
	v_mfma_f32_16x16x32_bf16 v[46:49], v[154:157], v[194:197], v[46:49]
	v_mfma_f32_16x16x32_bf16 v[42:45], v[162:165], v[194:197], v[42:45]
	v_mfma_f32_16x16x32_bf16 v[30:33], v[154:157], v[202:205], v[30:33]
	v_mfma_f32_16x16x32_bf16 v[26:29], v[162:165], v[202:205], v[26:29]
	v_mfma_f32_16x16x32_bf16 v[14:17], v[154:157], v[228:231], v[14:17]
	v_mfma_f32_16x16x32_bf16 v[10:13], v[162:165], v[228:231], v[10:13]
	v_mfma_f32_16x16x32_bf16 v[54:57], v[166:169], v[182:185], 0
	v_mfma_f32_16x16x32_bf16 v[50:53], v[174:177], v[182:185], 0
	v_mfma_f32_16x16x32_bf16 v[38:41], v[166:169], v[190:193], 0
	v_mfma_f32_16x16x32_bf16 v[34:37], v[174:177], v[190:193], 0
	v_mfma_f32_16x16x32_bf16 v[22:25], v[166:169], v[198:201], 0
	v_mfma_f32_16x16x32_bf16 v[18:21], v[174:177], v[198:201], 0
	v_mfma_f32_16x16x32_bf16 v[6:9], v[166:169], v[224:227], 0
	v_mfma_f32_16x16x32_bf16 v[2:5], v[174:177], v[224:227], 0
	v_mfma_f32_16x16x32_bf16 v[54:57], v[170:173], v[186:189], v[54:57]
	v_mfma_f32_16x16x32_bf16 v[50:53], v[178:181], v[186:189], v[50:53]
	v_mfma_f32_16x16x32_bf16 v[38:41], v[170:173], v[194:197], v[38:41]
	v_mfma_f32_16x16x32_bf16 v[34:37], v[178:181], v[194:197], v[34:37]
	v_mfma_f32_16x16x32_bf16 v[22:25], v[170:173], v[202:205], v[22:25]
	v_mfma_f32_16x16x32_bf16 v[18:21], v[178:181], v[202:205], v[18:21]
	v_mfma_f32_16x16x32_bf16 v[6:9], v[170:173], v[228:231], v[6:9]
	v_mfma_f32_16x16x32_bf16 v[2:5], v[178:181], v[228:231], v[2:5]
	s_setprio 0
	s_barrier
	s_add_i32 s52, 0, 0x18000
	v_add_u32_e32 v153, s52, v149
	s_add_i32 s53, 0, 0x1c000
	ds_read_b128 v[144:147], v153
	ds_read_b128 v[154:157], v153 offset:1024
	ds_read_b128 v[158:161], v153 offset:2048
	ds_read_b128 v[162:165], v153 offset:3072
	v_add_u32_e32 v153, s53, v149
	ds_read_b128 v[166:169], v153
	ds_read_b128 v[170:173], v153 offset:1024
	ds_read_b128 v[174:177], v153 offset:2048
	ds_read_b128 v[178:181], v153 offset:3072
	s_add_u32 s26, s26, 0x40000
	s_addc_u32 s27, s27, 0
	s_mov_b32 m0, s43
	v_lshl_add_u64 v[236:237], s[26:27], 0, v[130:131]
	ds_read_b128 v[182:185], v152 offset:32768
	ds_read_b128 v[186:189], v152 offset:33792
	ds_read_b128 v[190:193], v152 offset:34816
	ds_read_b128 v[194:197], v152 offset:35840
	ds_read_b128 v[198:201], v152 offset:36864
	ds_read_b128 v[202:205], v152 offset:37888
	ds_read_b128 v[224:227], v152 offset:38912
	ds_read_b128 v[228:231], v152 offset:39936
	global_load_lds_dwordx4 v[236:237], off
	v_lshl_add_u64 v[236:237], s[26:27], 0, v[132:133]
	s_mov_b32 m0, s44
	s_nop 0
	global_load_lds_dwordx4 v[236:237], off
	s_waitcnt vmcnt(8)
	s_waitcnt lgkmcnt(0)
	s_barrier
	s_setprio 1
	s_waitcnt lgkmcnt(0)
	v_mfma_f32_16x16x32_bf16 v[126:129], v[144:147], v[182:185], v[126:129]
	v_mfma_f32_16x16x32_bf16 v[122:125], v[158:161], v[182:185], v[122:125]
	v_mfma_f32_16x16x32_bf16 v[110:113], v[144:147], v[190:193], v[110:113]
	v_mfma_f32_16x16x32_bf16 v[106:109], v[158:161], v[190:193], v[106:109]
	v_mfma_f32_16x16x32_bf16 v[94:97], v[144:147], v[198:201], v[94:97]
	v_mfma_f32_16x16x32_bf16 v[90:93], v[158:161], v[198:201], v[90:93]
	v_mfma_f32_16x16x32_bf16 v[78:81], v[144:147], v[224:227], v[78:81]
	v_mfma_f32_16x16x32_bf16 v[74:77], v[158:161], v[224:227], v[74:77]
	v_mfma_f32_16x16x32_bf16 v[126:129], v[154:157], v[186:189], v[126:129]
	v_mfma_f32_16x16x32_bf16 v[122:125], v[162:165], v[186:189], v[122:125]
	v_mfma_f32_16x16x32_bf16 v[110:113], v[154:157], v[194:197], v[110:113]
	v_mfma_f32_16x16x32_bf16 v[106:109], v[162:165], v[194:197], v[106:109]
	v_mfma_f32_16x16x32_bf16 v[94:97], v[154:157], v[202:205], v[94:97]
	v_mfma_f32_16x16x32_bf16 v[90:93], v[162:165], v[202:205], v[90:93]
	v_mfma_f32_16x16x32_bf16 v[78:81], v[154:157], v[228:231], v[78:81]
	v_mfma_f32_16x16x32_bf16 v[74:77], v[162:165], v[228:231], v[74:77]
	v_mfma_f32_16x16x32_bf16 v[118:121], v[166:169], v[182:185], v[118:121]
	v_mfma_f32_16x16x32_bf16 v[114:117], v[174:177], v[182:185], v[114:117]
	v_mfma_f32_16x16x32_bf16 v[102:105], v[166:169], v[190:193], v[102:105]
	v_mfma_f32_16x16x32_bf16 v[98:101], v[174:177], v[190:193], v[98:101]
	v_mfma_f32_16x16x32_bf16 v[86:89], v[166:169], v[198:201], v[86:89]
	v_mfma_f32_16x16x32_bf16 v[82:85], v[174:177], v[198:201], v[82:85]
	v_mfma_f32_16x16x32_bf16 v[70:73], v[166:169], v[224:227], v[70:73]
	v_mfma_f32_16x16x32_bf16 v[66:69], v[174:177], v[224:227], v[66:69]
	v_mfma_f32_16x16x32_bf16 v[118:121], v[170:173], v[186:189], v[118:121]
	v_mfma_f32_16x16x32_bf16 v[114:117], v[178:181], v[186:189], v[114:117]
	v_mfma_f32_16x16x32_bf16 v[102:105], v[170:173], v[194:197], v[102:105]
	v_mfma_f32_16x16x32_bf16 v[98:101], v[178:181], v[194:197], v[98:101]
	v_mfma_f32_16x16x32_bf16 v[86:89], v[170:173], v[202:205], v[86:89]
	v_mfma_f32_16x16x32_bf16 v[82:85], v[178:181], v[202:205], v[82:85]
	v_mfma_f32_16x16x32_bf16 v[70:73], v[170:173], v[228:231], v[70:73]
	v_mfma_f32_16x16x32_bf16 v[66:69], v[178:181], v[228:231], v[66:69]
	s_setprio 0
	s_barrier
; #define PG8_STAGE(bufoff, gbase, voff) do { _Pragma("unroll") for (int _i = 0; _i < 2; ++_i) \
;         __builtin_amdgcn_global_load_lds((const unsigned*)((const char*)(gbase) + (voff)[_i]), (PG8_LAS unsigned*)(lds + (bufoff) + ldsw + _i * 8192), 16, 0, 0); } while (0)
; #define PG8_LDA(dst, b, h) do { _Pragma("unroll") for (int m = 0; m < 4; ++m) _Pragma("unroll") for (int k = 0; k < 2; ++k) dst[m][k] = *(const PG8_LAS bf16x8*)(lds + PG8_SA(b, h) + aoff + m * 2048 + k * 1024); } while (0)
; #define PG8_LDB(dst, b, h) do { _Pragma("unroll") for (int n = 0; n < 2; ++n) _Pragma("unroll") for (int k = 0; k < 2; ++k) dst[n][k] = *(const PG8_LAS bf16x8*)(lds + PG8_SB(b, h) + boff + n * 2048 + k * 1024); } while (0)
; #define PG8_MMA(ai, bj, At, Bt) do { __builtin_amdgcn_s_setprio(1); _Pragma("unroll") for (int m = 0; m < 4; ++m) _Pragma("unroll") for (int n = 0; n < 2; ++n) _Pragma("unroll") for (int k = 0; k < 2; ++k) \
;         acc[ai][bj][m][n] = __builtin_amdgcn_mfma_f32_16x16x32_bf16(Bt[n][k], At[m][k], acc[ai][bj][m][n], 0, 0, 0); __builtin_amdgcn_s_setprio(0); } while (0)
; #define PG8_WAIT_V(n) asm volatile("s_waitcnt vmcnt(" #n ")" ::: "memory")
; template <class Epi, class Sched, bool ALIGN_EPI = false, bool SP2 = false>
; __device__ __forceinline__ void gemm_phase(PG8_LAS unsigned char* lds, const Gemm g, const Sched& S, const Epi& E) {
;     ...
;             PG8_LDB(B0, 0, 0); PG8_LDB(B1, 0, 1); PG8_SCHED; PG8_LDA(At, 0, 0); PG8_STAGE(PG8_SA(1, 1), a1 + hstep, voffA);
;             PG8_WAIT_V(8); PG8_WAIT_L(0); PG8_BAR; PG8_MMA(0, 0, At, B0); PG8_MMA(0, 1, At, B1); PG8_BAR; PG8_SCHED;
;             PG8_LDA(At, 0, 1); PG8_STAGE(PG8_SB(0, 0), b2, voffB); PG8_STAGE(PG8_SB(0, 1), b2 + hstep, voffB); PG8_STAGE(PG8_SA(0, 0), a2, voffA);
;             PG8_WAIT_V(8); PG8_WAIT_L(0); PG8_BAR; PG8_MMA(1, 0, At, B0); PG8_MMA(1, 1, At, B1); PG8_BAR; PG8_SCHED;
;             PG8_LDB(B0, 1, 0); PG8_LDB(B1, 1, 1); PG8_SCHED; PG8_LDA(At, 1, 0); PG8_STAGE(PG8_SA(0, 1), a2 + hstep, voffA);
;             PG8_WAIT_V(8); PG8_WAIT_L(0); PG8_BAR; PG8_MMA(0, 0, At, B0); PG8_MMA(0, 1, At, B1); PG8_BAR; PG8_SCHED;
;             PG8_LDA(At, 1, 1); PG8_STAGE(PG8_SB(1, 0), b3, voffB); PG8_STAGE(PG8_SB(1, 1), b3 + hstep, voffB); PG8_STAGE(PG8_SA(1, 0), a3, voffA);
;             PG8_WAIT_V(8); PG8_WAIT_L(0); PG8_BAR; PG8_MMA(1, 0, At, B0); PG8_MMA(1, 1, At, B1); PG8_BAR; PG8_SCHED;
	s_add_i32 s26, s52, s31
	v_lshl_add_u64 v[138:139], v[138:139], 0, s[86:87]
	s_mov_b32 m0, s26
	ds_read_b128 v[182:185], v152 offset:49152
	ds_read_b128 v[186:189], v152 offset:50176
	ds_read_b128 v[190:193], v152 offset:51200
	ds_read_b128 v[194:197], v152 offset:52224
	ds_read_b128 v[198:201], v152 offset:53248
	ds_read_b128 v[202:205], v152 offset:54272
	ds_read_b128 v[224:227], v152 offset:55296
	ds_read_b128 v[228:231], v152 offset:56320
	global_load_lds_dwordx4 v[138:139], off
	s_add_i32 m0, s26, 0x2000
	s_add_u32 s24, s24, 0x40080
	v_lshl_add_u64 v[138:139], v[140:141], 0, s[86:87]
	s_addc_u32 s25, s25, 0
	s_add_i32 s26, s53, s31
	global_load_lds_dwordx4 v[138:139], off
	v_lshl_add_u64 v[138:139], s[24:25], 0, v[0:1]
	s_mov_b32 m0, s26
	s_nop 0
	global_load_lds_dwordx4 v[138:139], off
	v_lshl_add_u64 v[138:139], s[24:25], 0, v[134:135]
	s_add_i32 m0, s26, 0x2000
	s_nop 0
	global_load_lds_dwordx4 v[138:139], off
	v_lshl_add_u64 v[138:139], v[232:233], 0, s[86:87]
	s_mov_b32 m0, s45
	s_nop 0
	global_load_lds_dwordx4 v[138:139], off
	v_lshl_add_u64 v[138:139], v[234:235], 0, s[86:87]
	s_mov_b32 m0, s46
	s_nop 0
	global_load_lds_dwordx4 v[138:139], off
	s_waitcnt vmcnt(8)
	s_waitcnt lgkmcnt(0)
	s_barrier
	s_setprio 1
	s_waitcnt lgkmcnt(0)
	v_mfma_f32_16x16x32_bf16 v[62:65], v[144:147], v[182:185], v[62:65]
	v_mfma_f32_16x16x32_bf16 v[58:61], v[158:161], v[182:185], v[58:61]
	v_mfma_f32_16x16x32_bf16 v[46:49], v[144:147], v[190:193], v[46:49]
	v_mfma_f32_16x16x32_bf16 v[42:45], v[158:161], v[190:193], v[42:45]
	v_mfma_f32_16x16x32_bf16 v[30:33], v[144:147], v[198:201], v[30:33]
	v_mfma_f32_16x16x32_bf16 v[26:29], v[158:161], v[198:201], v[26:29]
	v_mfma_f32_16x16x32_bf16 v[14:17], v[144:147], v[224:227], v[14:17]
	v_mfma_f32_16x16x32_bf16 v[10:13], v[158:161], v[224:227], v[10:13]
	v_mfma_f32_16x16x32_bf16 v[62:65], v[154:157], v[186:189], v[62:65]
	v_mfma_f32_16x16x32_bf16 v[58:61], v[162:165], v[186:189], v[58:61]
	v_mfma_f32_16x16x32_bf16 v[46:49], v[154:157], v[194:197], v[46:49]
	v_mfma_f32_16x16x32_bf16 v[42:45], v[162:165], v[194:197], v[42:45]
	v_mfma_f32_16x16x32_bf16 v[30:33], v[154:157], v[202:205], v[30:33]
	v_mfma_f32_16x16x32_bf16 v[26:29], v[162:165], v[202:205], v[26:29]
	v_mfma_f32_16x16x32_bf16 v[14:17], v[154:157], v[228:231], v[14:17]
	v_mfma_f32_16x16x32_bf16 v[10:13], v[162:165], v[228:231], v[10:13]
	v_mfma_f32_16x16x32_bf16 v[54:57], v[166:169], v[182:185], v[54:57]
	v_mfma_f32_16x16x32_bf16 v[50:53], v[174:177], v[182:185], v[50:53]
	v_mfma_f32_16x16x32_bf16 v[38:41], v[166:169], v[190:193], v[38:41]
	v_mfma_f32_16x16x32_bf16 v[34:37], v[174:177], v[190:193], v[34:37]
	v_mfma_f32_16x16x32_bf16 v[22:25], v[166:169], v[198:201], v[22:25]
	v_mfma_f32_16x16x32_bf16 v[18:21], v[174:177], v[198:201], v[18:21]
	v_mfma_f32_16x16x32_bf16 v[6:9], v[166:169], v[224:227], v[6:9]
	v_mfma_f32_16x16x32_bf16 v[2:5], v[174:177], v[224:227], v[2:5]
	v_mfma_f32_16x16x32_bf16 v[54:57], v[170:173], v[186:189], v[54:57]
	v_mfma_f32_16x16x32_bf16 v[50:53], v[178:181], v[186:189], v[50:53]
	v_mfma_f32_16x16x32_bf16 v[38:41], v[170:173], v[194:197], v[38:41]
	v_mfma_f32_16x16x32_bf16 v[34:37], v[178:181], v[194:197], v[34:37]
	v_mfma_f32_16x16x32_bf16 v[22:25], v[170:173], v[202:205], v[22:25]
	v_mfma_f32_16x16x32_bf16 v[18:21], v[178:181], v[202:205], v[18:21]
	v_mfma_f32_16x16x32_bf16 v[6:9], v[170:173], v[228:231], v[6:9]
	v_mfma_f32_16x16x32_bf16 v[2:5], v[178:181], v[228:231], v[2:5]
	s_setprio 0
	s_barrier
	s_add_i32 s51, s51, 2
	s_add_u32 s22, s22, 0x100
	s_addc_u32 s23, s23, 0
	s_add_u32 s49, s49, 0x100
	s_addc_u32 s50, s50, 0
	s_cmp_gt_u32 s51, 13
	s_cbranch_scc1 .Lpeel_exit_sw
.LBB0_225:
	s_add_u32 s24, s22, 0xfffc0080
	s_addc_u32 s25, s23, -1
	s_add_i32 s52, 0, 0x10000
	s_cmp_eq_u32 s51, 12
	s_cselect_b32 s27, s5, s25
	s_cselect_b32 s26, s15, s24
	v_add_u32_e32 v138, s52, v149
	s_cselect_b32 s25, s13, s50
	s_cselect_b32 s24, s21, s49
	s_add_i32 s55, 0, 0x14000
	ds_read_b128 v[144:147], v138
	ds_read_b128 v[154:157], v138 offset:1024
	ds_read_b128 v[158:161], v138 offset:2048
	ds_read_b128 v[162:165], v138 offset:3072
	v_add_u32_e32 v138, s55, v149
	ds_read_b128 v[166:169], v138
	ds_read_b128 v[170:173], v138 offset:1024
	ds_read_b128 v[174:177], v138 offset:2048
	ds_read_b128 v[178:181], v138 offset:3072
	v_lshl_add_u64 v[138:139], s[22:23], 0, v[136:137]
	s_add_i32 m0, s41, 0xc000
	ds_read_b128 v[182:185], v152
	ds_read_b128 v[186:189], v152 offset:1024
	ds_read_b128 v[190:193], v152 offset:2048
	ds_read_b128 v[194:197], v152 offset:3072
	ds_read_b128 v[198:201], v152 offset:4096
	ds_read_b128 v[202:205], v152 offset:5120
	ds_read_b128 v[224:227], v152 offset:6144
	ds_read_b128 v[228:231], v152 offset:7168
	global_load_lds_dwordx4 v[138:139], off
	v_lshl_add_u64 v[138:139], s[22:23], 0, v[142:143]
	s_add_i32 m0, s41, 0xe000
	s_nop 0
	global_load_lds_dwordx4 v[138:139], off
	s_waitcnt vmcnt(8)
	s_waitcnt lgkmcnt(0)
	s_barrier
; #define PG8_STAGE(bufoff, gbase, voff) do { _Pragma("unroll") for (int _i = 0; _i < 2; ++_i) \
;         __builtin_amdgcn_global_load_lds((const unsigned*)((const char*)(gbase) + (voff)[_i]), (PG8_LAS unsigned*)(lds + (bufoff) + ldsw + _i * 8192), 16, 0, 0); } while (0)
; #define PG8_LDA(dst, b, h) do { _Pragma("unroll") for (int m = 0; m < 4; ++m) _Pragma("unroll") for (int k = 0; k < 2; ++k) dst[m][k] = *(const PG8_LAS bf16x8*)(lds + PG8_SA(b, h) + aoff + m * 2048 + k * 1024); } while (0)
; #define PG8_LDB(dst, b, h) do { _Pragma("unroll") for (int n = 0; n < 2; ++n) _Pragma("unroll") for (int k = 0; k < 2; ++k) dst[n][k] = *(const PG8_LAS bf16x8*)(lds + PG8_SB(b, h) + boff + n * 2048 + k * 1024); } while (0)
; #define PG8_MMA(ai, bj, At, Bt) do { __builtin_amdgcn_s_setprio(1); _Pragma("unroll") for (int m = 0; m < 4; ++m) _Pragma("unroll") for (int n = 0; n < 2; ++n) _Pragma("unroll") for (int k = 0; k < 2; ++k) \
;         acc[ai][bj][m][n] = __builtin_amdgcn_mfma_f32_16x16x32_bf16(Bt[n][k], At[m][k], acc[ai][bj][m][n], 0, 0, 0); __builtin_amdgcn_s_setprio(0); } while (0)
; #define PG8_WAIT_V(n) asm volatile("s_waitcnt vmcnt(" #n ")" ::: "memory")
; #define PG8_WAIT_L(n) asm volatile("s_waitcnt lgkmcnt(" #n ")" ::: "memory")
; #define PG8_BAR __builtin_amdgcn_s_barrier()
; #define PG8_SCHED __builtin_amdgcn_sched_barrier(0)
; template <class Epi, class Sched, bool ALIGN_EPI = false, bool SP2 = false>
; __device__ __forceinline__ void gemm_phase(PG8_LAS unsigned char* lds, const Gemm g, const Sched& S, const Epi& E) {
;     ...
;             PG8_LDB(B0, 0, 0); PG8_LDB(B1, 0, 1); PG8_SCHED; PG8_LDA(At, 0, 0); PG8_STAGE(PG8_SA(1, 1), a1 + hstep, voffA);
;             PG8_WAIT_V(8); PG8_WAIT_L(0); PG8_BAR; PG8_MMA(0, 0, At, B0); PG8_MMA(0, 1, At, B1); PG8_BAR; PG8_SCHED;
;             PG8_LDA(At, 0, 1); PG8_STAGE(PG8_SB(0, 0), b2, voffB); PG8_STAGE(PG8_SB(0, 1), b2 + hstep, voffB); PG8_STAGE(PG8_SA(0, 0), a2, voffA);
;             PG8_WAIT_V(8); PG8_WAIT_L(0); PG8_BAR; PG8_MMA(1, 0, At, B0); PG8_MMA(1, 1, At, B1); PG8_BAR; PG8_SCHED;
	s_setprio 1
	s_waitcnt lgkmcnt(0)
	v_mfma_f32_16x16x32_bf16 v[126:129], v[144:147], v[182:185], v[126:129]
	v_mfma_f32_16x16x32_bf16 v[122:125], v[158:161], v[182:185], v[122:125]
	v_mfma_f32_16x16x32_bf16 v[110:113], v[144:147], v[190:193], v[110:113]
	v_mfma_f32_16x16x32_bf16 v[106:109], v[158:161], v[190:193], v[106:109]
	v_mfma_f32_16x16x32_bf16 v[94:97], v[144:147], v[198:201], v[94:97]
	v_mfma_f32_16x16x32_bf16 v[90:93], v[158:161], v[198:201], v[90:93]
	v_mfma_f32_16x16x32_bf16 v[78:81], v[144:147], v[224:227], v[78:81]
	v_mfma_f32_16x16x32_bf16 v[74:77], v[158:161], v[224:227], v[74:77]
	v_mfma_f32_16x16x32_bf16 v[126:129], v[154:157], v[186:189], v[126:129]
	v_mfma_f32_16x16x32_bf16 v[122:125], v[162:165], v[186:189], v[122:125]
	v_mfma_f32_16x16x32_bf16 v[110:113], v[154:157], v[194:197], v[110:113]
	v_mfma_f32_16x16x32_bf16 v[106:109], v[162:165], v[194:197], v[106:109]
	v_mfma_f32_16x16x32_bf16 v[94:97], v[154:157], v[202:205], v[94:97]
	v_mfma_f32_16x16x32_bf16 v[90:93], v[162:165], v[202:205], v[90:93]
	v_mfma_f32_16x16x32_bf16 v[78:81], v[154:157], v[228:231], v[78:81]
	v_mfma_f32_16x16x32_bf16 v[74:77], v[162:165], v[228:231], v[74:77]
	v_mfma_f32_16x16x32_bf16 v[118:121], v[166:169], v[182:185], v[118:121]
	v_mfma_f32_16x16x32_bf16 v[114:117], v[174:177], v[182:185], v[114:117]
	v_mfma_f32_16x16x32_bf16 v[102:105], v[166:169], v[190:193], v[102:105]
	v_mfma_f32_16x16x32_bf16 v[98:101], v[174:177], v[190:193], v[98:101]
	v_mfma_f32_16x16x32_bf16 v[86:89], v[166:169], v[198:201], v[86:89]
	v_mfma_f32_16x16x32_bf16 v[82:85], v[174:177], v[198:201], v[82:85]
	v_mfma_f32_16x16x32_bf16 v[70:73], v[166:169], v[224:227], v[70:73]
	v_mfma_f32_16x16x32_bf16 v[66:69], v[174:177], v[224:227], v[66:69]
	v_mfma_f32_16x16x32_bf16 v[118:121], v[170:173], v[186:189], v[118:121]
	v_mfma_f32_16x16x32_bf16 v[114:117], v[178:181], v[186:189], v[114:117]
	v_mfma_f32_16x16x32_bf16 v[102:105], v[170:173], v[194:197], v[102:105]
	v_mfma_f32_16x16x32_bf16 v[98:101], v[178:181], v[194:197], v[98:101]
	v_mfma_f32_16x16x32_bf16 v[86:89], v[170:173], v[202:205], v[86:89]
	v_mfma_f32_16x16x32_bf16 v[82:85], v[178:181], v[202:205], v[82:85]
	v_mfma_f32_16x16x32_bf16 v[70:73], v[170:173], v[228:231], v[70:73]
	v_mfma_f32_16x16x32_bf16 v[66:69], v[178:181], v[228:231], v[66:69]
	s_setprio 0
	s_barrier
	s_add_i32 s52, s52, s31
	v_lshl_add_u64 v[138:139], s[24:25], 0, v[0:1]
	s_mov_b32 m0, s52
	ds_read_b128 v[182:185], v152 offset:16384
	ds_read_b128 v[186:189], v152 offset:17408
	ds_read_b128 v[190:193], v152 offset:18432
	ds_read_b128 v[194:197], v152 offset:19456
	ds_read_b128 v[198:201], v152 offset:20480
	ds_read_b128 v[202:205], v152 offset:21504
	ds_read_b128 v[224:227], v152 offset:22528
	ds_read_b128 v[228:231], v152 offset:23552
	global_load_lds_dwordx4 v[138:139], off
	s_add_i32 m0, s52, 0x2000
	s_add_u32 s52, s24, 0x40000
	v_lshl_add_u64 v[140:141], s[24:25], 0, v[134:135]
	s_addc_u32 s53, s25, 0
	s_add_i32 s55, s55, s31
	global_load_lds_dwordx4 v[140:141], off
	v_lshl_add_u64 v[232:233], s[52:53], 0, v[0:1]
	s_mov_b32 m0, s55
	v_lshl_add_u64 v[234:235], s[26:27], 0, v[132:133]
	global_load_lds_dwordx4 v[232:233], off
	v_lshl_add_u64 v[232:233], s[52:53], 0, v[134:135]
	s_add_i32 m0, s55, 0x2000
	s_nop 0
	global_load_lds_dwordx4 v[232:233], off
	v_lshl_add_u64 v[232:233], s[26:27], 0, v[130:131]
	s_mov_b32 m0, s41
	s_nop 0
	global_load_lds_dwordx4 v[232:233], off
	s_mov_b32 m0, s42
	s_nop 0
	global_load_lds_dwordx4 v[234:235], off
	s_waitcnt vmcnt(8)
	s_waitcnt lgkmcnt(0)
	s_barrier
	s_setprio 1
	s_waitcnt lgkmcnt(0)
	v_mfma_f32_16x16x32_bf16 v[62:65], v[144:147], v[182:185], v[62:65]
	v_mfma_f32_16x16x32_bf16 v[58:61], v[158:161], v[182:185], v[58:61]
	v_mfma_f32_16x16x32_bf16 v[46:49], v[144:147], v[190:193], v[46:49]
	v_mfma_f32_16x16x32_bf16 v[42:45], v[158:161], v[190:193], v[42:45]
	v_mfma_f32_16x16x32_bf16 v[30:33], v[144:147], v[198:201], v[30:33]
	v_mfma_f32_16x16x32_bf16 v[26:29], v[158:161], v[198:201], v[26:29]
	v_mfma_f32_16x16x32_bf16 v[14:17], v[144:147], v[224:227], v[14:17]
	v_mfma_f32_16x16x32_bf16 v[10:13], v[158:161], v[224:227], v[10:13]
	v_mfma_f32_16x16x32_bf16 v[62:65], v[154:157], v[186:189], v[62:65]
	v_mfma_f32_16x16x32_bf16 v[58:61], v[162:165], v[186:189], v[58:61]
	v_mfma_f32_16x16x32_bf16 v[46:49], v[154:157], v[194:197], v[46:49]
	v_mfma_f32_16x16x32_bf16 v[42:45], v[162:165], v[194:197], v[42:45]
	v_mfma_f32_16x16x32_bf16 v[30:33], v[154:157], v[202:205], v[30:33]
	v_mfma_f32_16x16x32_bf16 v[26:29], v[162:165], v[202:205], v[26:29]
	v_mfma_f32_16x16x32_bf16 v[14:17], v[154:157], v[228:231], v[14:17]
	v_mfma_f32_16x16x32_bf16 v[10:13], v[162:165], v[228:231], v[10:13]
	v_mfma_f32_16x16x32_bf16 v[54:57], v[166:169], v[182:185], v[54:57]
	v_mfma_f32_16x16x32_bf16 v[50:53], v[174:177], v[182:185], v[50:53]
	v_mfma_f32_16x16x32_bf16 v[38:41], v[166:169], v[190:193], v[38:41]
	v_mfma_f32_16x16x32_bf16 v[34:37], v[174:177], v[190:193], v[34:37]
	v_mfma_f32_16x16x32_bf16 v[22:25], v[166:169], v[198:201], v[22:25]
	v_mfma_f32_16x16x32_bf16 v[18:21], v[174:177], v[198:201], v[18:21]
	v_mfma_f32_16x16x32_bf16 v[6:9], v[166:169], v[224:227], v[6:9]
	v_mfma_f32_16x16x32_bf16 v[2:5], v[174:177], v[224:227], v[2:5]
	v_mfma_f32_16x16x32_bf16 v[54:57], v[170:173], v[186:189], v[54:57]
	v_mfma_f32_16x16x32_bf16 v[50:53], v[178:181], v[186:189], v[50:53]
	v_mfma_f32_16x16x32_bf16 v[38:41], v[170:173], v[194:197], v[38:41]
	v_mfma_f32_16x16x32_bf16 v[34:37], v[178:181], v[194:197], v[34:37]
	v_mfma_f32_16x16x32_bf16 v[22:25], v[170:173], v[202:205], v[22:25]
	v_mfma_f32_16x16x32_bf16 v[18:21], v[178:181], v[202:205], v[18:21]
	v_mfma_f32_16x16x32_bf16 v[6:9], v[170:173], v[228:231], v[6:9]
	v_mfma_f32_16x16x32_bf16 v[2:5], v[178:181], v[228:231], v[2:5]
	s_setprio 0
	s_barrier
; #define PG8_STAGE(bufoff, gbase, voff) do { _Pragma("unroll") for (int _i = 0; _i < 2; ++_i) \
;         __builtin_amdgcn_global_load_lds((const unsigned*)((const char*)(gbase) + (voff)[_i]), (PG8_LAS unsigned*)(lds + (bufoff) + ldsw + _i * 8192), 16, 0, 0); } while (0)
; #define PG8_LDA(dst, b, h) do { _Pragma("unroll") for (int m = 0; m < 4; ++m) _Pragma("unroll") for (int k = 0; k < 2; ++k) dst[m][k] = *(const PG8_LAS bf16x8*)(lds + PG8_SA(b, h) + aoff + m * 2048 + k * 1024); } while (0)
; #define PG8_LDB(dst, b, h) do { _Pragma("unroll") for (int n = 0; n < 2; ++n) _Pragma("unroll") for (int k = 0; k < 2; ++k) dst[n][k] = *(const PG8_LAS bf16x8*)(lds + PG8_SB(b, h) + boff + n * 2048 + k * 1024); } while (0)
; #define PG8_MMA(ai, bj, At, Bt) do { __builtin_amdgcn_s_setprio(1); _Pragma("unroll") for (int m = 0; m < 4; ++m) _Pragma("unroll") for (int n = 0; n < 2; ++n) _Pragma("unroll") for (int k = 0; k < 2; ++k) \
;         acc[ai][bj][m][n] = __builtin_amdgcn_mfma_f32_16x16x32_bf16(Bt[n][k], At[m][k], acc[ai][bj][m][n], 0, 0, 0); __builtin_amdgcn_s_setprio(0); } while (0)
; #define PG8_WAIT_V(n) asm volatile("s_waitcnt vmcnt(" #n ")" ::: "memory")
; #define PG8_WAIT_L(n) asm volatile("s_waitcnt lgkmcnt(" #n ")" ::: "memory")
; #define PG8_BAR __builtin_amdgcn_s_barrier()
; #define PG8_SCHED __builtin_amdgcn_sched_barrier(0)
; template <class Epi, class Sched, bool ALIGN_EPI = false, bool SP2 = false>
; __device__ __forceinline__ void gemm_phase(PG8_LAS unsigned char* lds, const Gemm g, const Sched& S, const Epi& E) {
;     ...
;             PG8_LDB(B0, 1, 0); PG8_LDB(B1, 1, 1); PG8_SCHED; PG8_LDA(At, 1, 0); PG8_STAGE(PG8_SA(0, 1), a2 + hstep, voffA);
;             PG8_WAIT_V(8); PG8_WAIT_L(0); PG8_BAR; PG8_MMA(0, 0, At, B0); PG8_MMA(0, 1, At, B1); PG8_BAR; PG8_SCHED;
	s_add_i32 s52, 0, 0x18000
	v_add_u32_e32 v153, s52, v149
	s_add_i32 s53, 0, 0x1c000
	ds_read_b128 v[144:147], v153
	ds_read_b128 v[154:157], v153 offset:1024
	ds_read_b128 v[158:161], v153 offset:2048
	ds_read_b128 v[162:165], v153 offset:3072
	v_add_u32_e32 v153, s53, v149
	ds_read_b128 v[166:169], v153
	ds_read_b128 v[170:173], v153 offset:1024
	ds_read_b128 v[174:177], v153 offset:2048
	ds_read_b128 v[178:181], v153 offset:3072
	s_add_u32 s26, s26, 0x40000
	s_addc_u32 s27, s27, 0
	s_mov_b32 m0, s43
	v_lshl_add_u64 v[236:237], s[26:27], 0, v[130:131]
	ds_read_b128 v[182:185], v152 offset:32768
	ds_read_b128 v[186:189], v152 offset:33792
	ds_read_b128 v[190:193], v152 offset:34816
	ds_read_b128 v[194:197], v152 offset:35840
	ds_read_b128 v[198:201], v152 offset:36864
	ds_read_b128 v[202:205], v152 offset:37888
	ds_read_b128 v[224:227], v152 offset:38912
	ds_read_b128 v[228:231], v152 offset:39936
	global_load_lds_dwordx4 v[236:237], off
	v_lshl_add_u64 v[236:237], s[26:27], 0, v[132:133]
	s_mov_b32 m0, s44
	s_nop 0
	global_load_lds_dwordx4 v[236:237], off
	s_waitcnt vmcnt(8)
	s_waitcnt lgkmcnt(0)
	s_barrier
	s_setprio 1
	s_waitcnt lgkmcnt(0)
	v_mfma_f32_16x16x32_bf16 v[126:129], v[144:147], v[182:185], v[126:129]
	v_mfma_f32_16x16x32_bf16 v[122:125], v[158:161], v[182:185], v[122:125]
	v_mfma_f32_16x16x32_bf16 v[110:113], v[144:147], v[190:193], v[110:113]
	v_mfma_f32_16x16x32_bf16 v[106:109], v[158:161], v[190:193], v[106:109]
	v_mfma_f32_16x16x32_bf16 v[94:97], v[144:147], v[198:201], v[94:97]
	v_mfma_f32_16x16x32_bf16 v[90:93], v[158:161], v[198:201], v[90:93]
	v_mfma_f32_16x16x32_bf16 v[78:81], v[144:147], v[224:227], v[78:81]
	v_mfma_f32_16x16x32_bf16 v[74:77], v[158:161], v[224:227], v[74:77]
	v_mfma_f32_16x16x32_bf16 v[126:129], v[154:157], v[186:189], v[126:129]
	v_mfma_f32_16x16x32_bf16 v[122:125], v[162:165], v[186:189], v[122:125]
	v_mfma_f32_16x16x32_bf16 v[110:113], v[154:157], v[194:197], v[110:113]
	v_mfma_f32_16x16x32_bf16 v[106:109], v[162:165], v[194:197], v[106:109]
	v_mfma_f32_16x16x32_bf16 v[94:97], v[154:157], v[202:205], v[94:97]
	v_mfma_f32_16x16x32_bf16 v[90:93], v[162:165], v[202:205], v[90:93]
	v_mfma_f32_16x16x32_bf16 v[78:81], v[154:157], v[228:231], v[78:81]
	v_mfma_f32_16x16x32_bf16 v[74:77], v[162:165], v[228:231], v[74:77]
	v_mfma_f32_16x16x32_bf16 v[118:121], v[166:169], v[182:185], v[118:121]
	v_mfma_f32_16x16x32_bf16 v[114:117], v[174:177], v[182:185], v[114:117]
	v_mfma_f32_16x16x32_bf16 v[102:105], v[166:169], v[190:193], v[102:105]
	v_mfma_f32_16x16x32_bf16 v[98:101], v[174:177], v[190:193], v[98:101]
	v_mfma_f32_16x16x32_bf16 v[86:89], v[166:169], v[198:201], v[86:89]
	v_mfma_f32_16x16x32_bf16 v[82:85], v[174:177], v[198:201], v[82:85]
	v_mfma_f32_16x16x32_bf16 v[70:73], v[166:169], v[224:227], v[70:73]
	v_mfma_f32_16x16x32_bf16 v[66:69], v[174:177], v[224:227], v[66:69]
	v_mfma_f32_16x16x32_bf16 v[118:121], v[170:173], v[186:189], v[118:121]
	v_mfma_f32_16x16x32_bf16 v[114:117], v[178:181], v[186:189], v[114:117]
	v_mfma_f32_16x16x32_bf16 v[102:105], v[170:173], v[194:197], v[102:105]
	v_mfma_f32_16x16x32_bf16 v[98:101], v[178:181], v[194:197], v[98:101]
	v_mfma_f32_16x16x32_bf16 v[86:89], v[170:173], v[202:205], v[86:89]
	v_mfma_f32_16x16x32_bf16 v[82:85], v[178:181], v[202:205], v[82:85]
	v_mfma_f32_16x16x32_bf16 v[70:73], v[170:173], v[228:231], v[70:73]
	v_mfma_f32_16x16x32_bf16 v[66:69], v[178:181], v[228:231], v[66:69]
	s_setprio 0
	s_barrier
; #define PG8_STAGE(bufoff, gbase, voff) do { _Pragma("unroll") for (int _i = 0; _i < 2; ++_i) \
;         __builtin_amdgcn_global_load_lds((const unsigned*)((const char*)(gbase) + (voff)[_i]), (PG8_LAS unsigned*)(lds + (bufoff) + ldsw + _i * 8192), 16, 0, 0); } while (0)
; #define PG8_LDA(dst, b, h) do { _Pragma("unroll") for (int m = 0; m < 4; ++m) _Pragma("unroll") for (int k = 0; k < 2; ++k) dst[m][k] = *(const PG8_LAS bf16x8*)(lds + PG8_SA(b, h) + aoff + m * 2048 + k * 1024); } while (0)
; #define PG8_MMA(ai, bj, At, Bt) do { __builtin_amdgcn_s_setprio(1); _Pragma("unroll") for (int m = 0; m < 4; ++m) _Pragma("unroll") for (int n = 0; n < 2; ++n) _Pragma("unroll") for (int k = 0; k < 2; ++k) \
;         acc[ai][bj][m][n] = __builtin_amdgcn_mfma_f32_16x16x32_bf16(Bt[n][k], At[m][k], acc[ai][bj][m][n], 0, 0, 0); __builtin_amdgcn_s_setprio(0); } while (0)
; #define PG8_WAIT_V(n) asm volatile("s_waitcnt vmcnt(" #n ")" ::: "memory")
; #define PG8_WAIT_L(n) asm volatile("s_waitcnt lgkmcnt(" #n ")" ::: "memory")
; #define PG8_BAR __builtin_amdgcn_s_barrier()
; #define PG8_SCHED __builtin_amdgcn_sched_barrier(0)
; template <class Epi, class Sched, bool ALIGN_EPI = false, bool SP2 = false>
; __device__ __forceinline__ void gemm_phase(PG8_LAS unsigned char* lds, const Gemm g, const Sched& S, const Epi& E) {
;     ...
;             PG8_LDA(At, 1, 1); PG8_STAGE(PG8_SB(1, 0), b3, voffB); PG8_STAGE(PG8_SB(1, 1), b3 + hstep, voffB); PG8_STAGE(PG8_SA(1, 0), a3, voffA);
;             PG8_WAIT_V(8); PG8_WAIT_L(0); PG8_BAR; PG8_MMA(1, 0, At, B0); PG8_MMA(1, 1, At, B1); PG8_BAR; PG8_SCHED;
	s_add_i32 s26, s52, s31
	v_lshl_add_u64 v[138:139], v[138:139], 0, s[86:87]
	s_mov_b32 m0, s26
	ds_read_b128 v[182:185], v152 offset:49152
	ds_read_b128 v[186:189], v152 offset:50176
	ds_read_b128 v[190:193], v152 offset:51200
	ds_read_b128 v[194:197], v152 offset:52224
	ds_read_b128 v[198:201], v152 offset:53248
	ds_read_b128 v[202:205], v152 offset:54272
	ds_read_b128 v[224:227], v152 offset:55296
	ds_read_b128 v[228:231], v152 offset:56320
	global_load_lds_dwordx4 v[138:139], off
	s_add_i32 m0, s26, 0x2000
	s_add_u32 s24, s24, 0x40080
	v_lshl_add_u64 v[138:139], v[140:141], 0, s[86:87]
	s_addc_u32 s25, s25, 0
	s_add_i32 s26, s53, s31
	global_load_lds_dwordx4 v[138:139], off
	v_lshl_add_u64 v[138:139], s[24:25], 0, v[0:1]
	s_mov_b32 m0, s26
	s_nop 0
	global_load_lds_dwordx4 v[138:139], off
	v_lshl_add_u64 v[138:139], s[24:25], 0, v[134:135]
	s_add_i32 m0, s26, 0x2000
	s_nop 0
	global_load_lds_dwordx4 v[138:139], off
	v_lshl_add_u64 v[138:139], v[232:233], 0, s[86:87]
	s_mov_b32 m0, s45
	s_nop 0
	global_load_lds_dwordx4 v[138:139], off
	v_lshl_add_u64 v[138:139], v[234:235], 0, s[86:87]
	s_mov_b32 m0, s46
	s_nop 0
	global_load_lds_dwordx4 v[138:139], off
	s_waitcnt vmcnt(8)
	s_waitcnt lgkmcnt(0)
	s_barrier
	s_setprio 1
	s_waitcnt lgkmcnt(0)
	v_mfma_f32_16x16x32_bf16 v[62:65], v[144:147], v[182:185], v[62:65]
	v_mfma_f32_16x16x32_bf16 v[58:61], v[158:161], v[182:185], v[58:61]
	v_mfma_f32_16x16x32_bf16 v[46:49], v[144:147], v[190:193], v[46:49]
	v_mfma_f32_16x16x32_bf16 v[42:45], v[158:161], v[190:193], v[42:45]
	v_mfma_f32_16x16x32_bf16 v[30:33], v[144:147], v[198:201], v[30:33]
	v_mfma_f32_16x16x32_bf16 v[26:29], v[158:161], v[198:201], v[26:29]
	v_mfma_f32_16x16x32_bf16 v[14:17], v[144:147], v[224:227], v[14:17]
	v_mfma_f32_16x16x32_bf16 v[10:13], v[158:161], v[224:227], v[10:13]
	v_mfma_f32_16x16x32_bf16 v[62:65], v[154:157], v[186:189], v[62:65]
	v_mfma_f32_16x16x32_bf16 v[58:61], v[162:165], v[186:189], v[58:61]
	v_mfma_f32_16x16x32_bf16 v[46:49], v[154:157], v[194:197], v[46:49]
	v_mfma_f32_16x16x32_bf16 v[42:45], v[162:165], v[194:197], v[42:45]
	v_mfma_f32_16x16x32_bf16 v[30:33], v[154:157], v[202:205], v[30:33]
	v_mfma_f32_16x16x32_bf16 v[26:29], v[162:165], v[202:205], v[26:29]
	v_mfma_f32_16x16x32_bf16 v[14:17], v[154:157], v[228:231], v[14:17]
	v_mfma_f32_16x16x32_bf16 v[10:13], v[162:165], v[228:231], v[10:13]
	v_mfma_f32_16x16x32_bf16 v[54:57], v[166:169], v[182:185], v[54:57]
	v_mfma_f32_16x16x32_bf16 v[50:53], v[174:177], v[182:185], v[50:53]
	v_mfma_f32_16x16x32_bf16 v[38:41], v[166:169], v[190:193], v[38:41]
	v_mfma_f32_16x16x32_bf16 v[34:37], v[174:177], v[190:193], v[34:37]
	v_mfma_f32_16x16x32_bf16 v[22:25], v[166:169], v[198:201], v[22:25]
	v_mfma_f32_16x16x32_bf16 v[18:21], v[174:177], v[198:201], v[18:21]
	v_mfma_f32_16x16x32_bf16 v[6:9], v[166:169], v[224:227], v[6:9]
	v_mfma_f32_16x16x32_bf16 v[2:5], v[174:177], v[224:227], v[2:5]
	v_mfma_f32_16x16x32_bf16 v[54:57], v[170:173], v[186:189], v[54:57]
	v_mfma_f32_16x16x32_bf16 v[50:53], v[178:181], v[186:189], v[50:53]
	v_mfma_f32_16x16x32_bf16 v[38:41], v[170:173], v[194:197], v[38:41]
	v_mfma_f32_16x16x32_bf16 v[34:37], v[178:181], v[194:197], v[34:37]
	v_mfma_f32_16x16x32_bf16 v[22:25], v[170:173], v[202:205], v[22:25]
	v_mfma_f32_16x16x32_bf16 v[18:21], v[178:181], v[202:205], v[18:21]
	v_mfma_f32_16x16x32_bf16 v[6:9], v[170:173], v[228:231], v[6:9]
	v_mfma_f32_16x16x32_bf16 v[2:5], v[178:181], v[228:231], v[2:5]
	s_setprio 0
	s_barrier
	s_add_i32 s51, s51, 2
	s_add_u32 s22, s22, 0x100
	s_addc_u32 s23, s23, 0
	s_add_u32 s49, s49, 0x100
	s_addc_u32 s50, s50, 0
	s_cmp_gt_u32 s51, 13
	s_cbranch_scc0 .LBB0_225

; #define PG8_STAGE(bufoff, gbase, voff) do { _Pragma("unroll") for (int _i = 0; _i < 2; ++_i) \
;         __builtin_amdgcn_global_load_lds((const unsigned*)((const char*)(gbase) + (voff)[_i]), (PG8_LAS unsigned*)(lds + (bufoff) + ldsw + _i * 8192), 16, 0, 0); } while (0)
; #define PG8_LDA(dst, b, h) do { _Pragma("unroll") for (int m = 0; m < 4; ++m) _Pragma("unroll") for (int k = 0; k < 2; ++k) dst[m][k] = *(const PG8_LAS bf16x8*)(lds + PG8_SA(b, h) + aoff + m * 2048 + k * 1024); } while (0)
; #define PG8_LDB(dst, b, h) do { _Pragma("unroll") for (int n = 0; n < 2; ++n) _Pragma("unroll") for (int k = 0; k < 2; ++k) dst[n][k] = *(const PG8_LAS bf16x8*)(lds + PG8_SB(b, h) + boff + n * 2048 + k * 1024); } while (0)
; #define PG8_MMA(ai, bj, At, Bt) do { __builtin_amdgcn_s_setprio(1); _Pragma("unroll") for (int m = 0; m < 4; ++m) _Pragma("unroll") for (int n = 0; n < 2; ++n) _Pragma("unroll") for (int k = 0; k < 2; ++k) \
;         acc[ai][bj][m][n] = __builtin_amdgcn_mfma_f32_16x16x32_bf16(Bt[n][k], At[m][k], acc[ai][bj][m][n], 0, 0, 0); __builtin_amdgcn_s_setprio(0); } while (0)
; #define PG8_WAIT_V(n) asm volatile("s_waitcnt vmcnt(" #n ")" ::: "memory")
; #define PG8_WAIT_L(n) asm volatile("s_waitcnt lgkmcnt(" #n ")" ::: "memory")
; #define PG8_BAR __builtin_amdgcn_s_barrier()
; #define PG8_SCHED __builtin_amdgcn_sched_barrier(0)
; template <class Epi, class Sched, bool ALIGN_EPI = false, bool SP2 = false>
; __device__ __forceinline__ void gemm_phase(PG8_LAS unsigned char* lds, const Gemm g, const Sched& S, const Epi& E) {
;     ...
;             PG8_LDB(B0, 0, 0); PG8_LDB(B1, 0, 1); PG8_SCHED; PG8_LDA(At, 0, 0); PG8_STAGE(PG8_SA(1, 1), a1 + hstep, voffA);
;             PG8_WAIT_V(8); PG8_WAIT_L(0); PG8_BAR; PG8_MMA(0, 0, At, B0); PG8_MMA(0, 1, At, B1); PG8_BAR; PG8_SCHED;
;             PG8_LDA(At, 0, 1); PG8_STAGE(PG8_SB(0, 0), b2, voffB); PG8_STAGE(PG8_SB(0, 1), b2 + hstep, voffB); PG8_STAGE(PG8_SA(0, 0), a2, voffA);
.LBB0_362:
	s_add_u32 s16, s14, 0x100
	s_addc_u32 s17, s15, 0
	s_add_i32 s50, 0, 0x10000
	s_cmp_eq_u32 s49, 40
	s_cselect_b32 s21, s7, s17
	s_cselect_b32 s20, s6, s16
	v_add_u32_e32 v138, s50, v149
	s_cselect_b32 s19, s13, s48
	s_cselect_b32 s18, s12, s47
	s_add_i32 s51, 0, 0x14000
	ds_read_b128 v[144:147], v138
	ds_read_b128 v[152:155], v138 offset:1024
	ds_read_b128 v[156:159], v138 offset:2048
	ds_read_b128 v[160:163], v138 offset:3072
	v_add_u32_e32 v138, s51, v149
	ds_read_b128 v[164:167], v138
	ds_read_b128 v[168:171], v138 offset:1024
	ds_read_b128 v[172:175], v138 offset:2048
	ds_read_b128 v[176:179], v138 offset:3072
	v_lshl_add_u64 v[138:139], s[14:15], 0, v[136:137]
	s_add_i32 m0, s26, 0xc000
	ds_read_b128 v[180:183], v151
	ds_read_b128 v[184:187], v151 offset:1024
	ds_read_b128 v[188:191], v151 offset:2048
	ds_read_b128 v[192:195], v151 offset:3072
	ds_read_b128 v[196:199], v151 offset:4096
	ds_read_b128 v[200:203], v151 offset:5120
	ds_read_b128 v[224:227], v151 offset:6144
	ds_read_b128 v[228:231], v151 offset:7168
	global_load_lds_dwordx4 v[138:139], off
	v_lshl_add_u64 v[138:139], s[14:15], 0, v[142:143]
	s_add_i32 m0, s26, 0xe000
	s_nop 0
	global_load_lds_dwordx4 v[138:139], off
	s_waitcnt vmcnt(8)
	s_waitcnt lgkmcnt(0)
	s_barrier
	s_setprio 1
	s_waitcnt lgkmcnt(0)
	v_mfma_f32_16x16x32_bf16 v[126:129], v[144:147], v[180:183], v[126:129]
	v_mfma_f32_16x16x32_bf16 v[122:125], v[156:159], v[180:183], v[122:125]
	v_mfma_f32_16x16x32_bf16 v[110:113], v[144:147], v[188:191], v[110:113]
	v_mfma_f32_16x16x32_bf16 v[106:109], v[156:159], v[188:191], v[106:109]
	v_mfma_f32_16x16x32_bf16 v[94:97], v[144:147], v[196:199], v[94:97]
	v_mfma_f32_16x16x32_bf16 v[90:93], v[156:159], v[196:199], v[90:93]
	v_mfma_f32_16x16x32_bf16 v[78:81], v[144:147], v[224:227], v[78:81]
	v_mfma_f32_16x16x32_bf16 v[74:77], v[156:159], v[224:227], v[74:77]
	v_mfma_f32_16x16x32_bf16 v[126:129], v[152:155], v[184:187], v[126:129]
	v_mfma_f32_16x16x32_bf16 v[122:125], v[160:163], v[184:187], v[122:125]
	v_mfma_f32_16x16x32_bf16 v[110:113], v[152:155], v[192:195], v[110:113]
	v_mfma_f32_16x16x32_bf16 v[106:109], v[160:163], v[192:195], v[106:109]
	v_mfma_f32_16x16x32_bf16 v[94:97], v[152:155], v[200:203], v[94:97]
	v_mfma_f32_16x16x32_bf16 v[90:93], v[160:163], v[200:203], v[90:93]
	v_mfma_f32_16x16x32_bf16 v[78:81], v[152:155], v[228:231], v[78:81]
	v_mfma_f32_16x16x32_bf16 v[74:77], v[160:163], v[228:231], v[74:77]
	v_mfma_f32_16x16x32_bf16 v[118:121], v[164:167], v[180:183], v[118:121]
	v_mfma_f32_16x16x32_bf16 v[114:117], v[172:175], v[180:183], v[114:117]
	v_mfma_f32_16x16x32_bf16 v[102:105], v[164:167], v[188:191], v[102:105]
	v_mfma_f32_16x16x32_bf16 v[98:101], v[172:175], v[188:191], v[98:101]
	v_mfma_f32_16x16x32_bf16 v[86:89], v[164:167], v[196:199], v[86:89]
	v_mfma_f32_16x16x32_bf16 v[82:85], v[172:175], v[196:199], v[82:85]
	v_mfma_f32_16x16x32_bf16 v[70:73], v[164:167], v[224:227], v[70:73]
	v_mfma_f32_16x16x32_bf16 v[66:69], v[172:175], v[224:227], v[66:69]
	v_mfma_f32_16x16x32_bf16 v[118:121], v[168:171], v[184:187], v[118:121]
	v_mfma_f32_16x16x32_bf16 v[114:117], v[176:179], v[184:187], v[114:117]
	v_mfma_f32_16x16x32_bf16 v[102:105], v[168:171], v[192:195], v[102:105]
	v_mfma_f32_16x16x32_bf16 v[98:101], v[176:179], v[192:195], v[98:101]
	v_mfma_f32_16x16x32_bf16 v[86:89], v[168:171], v[200:203], v[86:89]
	v_mfma_f32_16x16x32_bf16 v[82:85], v[176:179], v[200:203], v[82:85]
	v_mfma_f32_16x16x32_bf16 v[70:73], v[168:171], v[228:231], v[70:73]
	v_mfma_f32_16x16x32_bf16 v[66:69], v[176:179], v[228:231], v[66:69]
	s_setprio 0
	s_barrier
	s_add_i32 s14, s50, s23
	v_lshl_add_u64 v[138:139], s[18:19], 0, v[0:1]
	s_mov_b32 m0, s14
	ds_read_b128 v[180:183], v151 offset:16384
	ds_read_b128 v[184:187], v151 offset:17408
	ds_read_b128 v[188:191], v151 offset:18432
	ds_read_b128 v[192:195], v151 offset:19456
	ds_read_b128 v[196:199], v151 offset:20480
	ds_read_b128 v[200:203], v151 offset:21504
	ds_read_b128 v[224:227], v151 offset:22528
	ds_read_b128 v[228:231], v151 offset:23552
	global_load_lds_dwordx4 v[138:139], off
	s_add_i32 m0, s14, 0x2000
	s_add_u32 s14, s18, 0xb0000
	v_lshl_add_u64 v[140:141], s[18:19], 0, v[134:135]
	s_addc_u32 s15, s19, 0
	s_add_i32 s50, s51, s23
	global_load_lds_dwordx4 v[140:141], off
	v_lshl_add_u64 v[204:205], s[14:15], 0, v[0:1]
	s_mov_b32 m0, s50
	v_lshl_add_u64 v[232:233], s[20:21], 0, v[132:133]
	global_load_lds_dwordx4 v[204:205], off
	v_lshl_add_u64 v[204:205], s[14:15], 0, v[134:135]
	s_add_i32 m0, s50, 0x2000
	s_nop 0
	global_load_lds_dwordx4 v[204:205], off
	v_lshl_add_u64 v[204:205], s[20:21], 0, v[130:131]
	s_mov_b32 m0, s26
	s_nop 0
	global_load_lds_dwordx4 v[204:205], off
	s_mov_b32 m0, s27
	s_nop 0
	global_load_lds_dwordx4 v[232:233], off
	s_waitcnt vmcnt(8)
	s_waitcnt lgkmcnt(0)
	s_barrier
; #define PG8_STAGE(bufoff, gbase, voff) do { _Pragma("unroll") for (int _i = 0; _i < 2; ++_i) \
;         __builtin_amdgcn_global_load_lds((const unsigned*)((const char*)(gbase) + (voff)[_i]), (PG8_LAS unsigned*)(lds + (bufoff) + ldsw + _i * 8192), 16, 0, 0); } while (0)
; #define PG8_LDA(dst, b, h) do { _Pragma("unroll") for (int m = 0; m < 4; ++m) _Pragma("unroll") for (int k = 0; k < 2; ++k) dst[m][k] = *(const PG8_LAS bf16x8*)(lds + PG8_SA(b, h) + aoff + m * 2048 + k * 1024); } while (0)
; #define PG8_LDB(dst, b, h) do { _Pragma("unroll") for (int n = 0; n < 2; ++n) _Pragma("unroll") for (int k = 0; k < 2; ++k) dst[n][k] = *(const PG8_LAS bf16x8*)(lds + PG8_SB(b, h) + boff + n * 2048 + k * 1024); } while (0)
; #define PG8_MMA(ai, bj, At, Bt) do { __builtin_amdgcn_s_setprio(1); _Pragma("unroll") for (int m = 0; m < 4; ++m) _Pragma("unroll") for (int n = 0; n < 2; ++n) _Pragma("unroll") for (int k = 0; k < 2; ++k) \
;         acc[ai][bj][m][n] = __builtin_amdgcn_mfma_f32_16x16x32_bf16(Bt[n][k], At[m][k], acc[ai][bj][m][n], 0, 0, 0); __builtin_amdgcn_s_setprio(0); } while (0)
; #define PG8_WAIT_V(n) asm volatile("s_waitcnt vmcnt(" #n ")" ::: "memory")
; #define PG8_WAIT_L(n) asm volatile("s_waitcnt lgkmcnt(" #n ")" ::: "memory")
; #define PG8_BAR __builtin_amdgcn_s_barrier()
; #define PG8_SCHED __builtin_amdgcn_sched_barrier(0)
; template <class Epi, class Sched, bool ALIGN_EPI = false, bool SP2 = false>
; __device__ __forceinline__ void gemm_phase(PG8_LAS unsigned char* lds, const Gemm g, const Sched& S, const Epi& E) {
;     ...
;             PG8_WAIT_V(8); PG8_WAIT_L(0); PG8_BAR; PG8_MMA(1, 0, At, B0); PG8_MMA(1, 1, At, B1); PG8_BAR; PG8_SCHED;
;             PG8_LDB(B0, 1, 0); PG8_LDB(B1, 1, 1); PG8_SCHED; PG8_LDA(At, 1, 0); PG8_STAGE(PG8_SA(0, 1), a2 + hstep, voffA);
;             PG8_WAIT_V(8); PG8_WAIT_L(0); PG8_BAR; PG8_MMA(0, 0, At, B0); PG8_MMA(0, 1, At, B1); PG8_BAR; PG8_SCHED;
	s_setprio 1
	s_waitcnt lgkmcnt(0)
	v_mfma_f32_16x16x32_bf16 v[62:65], v[144:147], v[180:183], v[62:65]
	v_mfma_f32_16x16x32_bf16 v[58:61], v[156:159], v[180:183], v[58:61]
	v_mfma_f32_16x16x32_bf16 v[46:49], v[144:147], v[188:191], v[46:49]
	v_mfma_f32_16x16x32_bf16 v[42:45], v[156:159], v[188:191], v[42:45]
	v_mfma_f32_16x16x32_bf16 v[30:33], v[144:147], v[196:199], v[30:33]
	v_mfma_f32_16x16x32_bf16 v[26:29], v[156:159], v[196:199], v[26:29]
	v_mfma_f32_16x16x32_bf16 v[14:17], v[144:147], v[224:227], v[14:17]
	v_mfma_f32_16x16x32_bf16 v[10:13], v[156:159], v[224:227], v[10:13]
	v_mfma_f32_16x16x32_bf16 v[62:65], v[152:155], v[184:187], v[62:65]
	v_mfma_f32_16x16x32_bf16 v[58:61], v[160:163], v[184:187], v[58:61]
	v_mfma_f32_16x16x32_bf16 v[46:49], v[152:155], v[192:195], v[46:49]
	v_mfma_f32_16x16x32_bf16 v[42:45], v[160:163], v[192:195], v[42:45]
	v_mfma_f32_16x16x32_bf16 v[30:33], v[152:155], v[200:203], v[30:33]
	v_mfma_f32_16x16x32_bf16 v[26:29], v[160:163], v[200:203], v[26:29]
	v_mfma_f32_16x16x32_bf16 v[14:17], v[152:155], v[228:231], v[14:17]
	v_mfma_f32_16x16x32_bf16 v[10:13], v[160:163], v[228:231], v[10:13]
	v_mfma_f32_16x16x32_bf16 v[54:57], v[164:167], v[180:183], v[54:57]
	v_mfma_f32_16x16x32_bf16 v[50:53], v[172:175], v[180:183], v[50:53]
	v_mfma_f32_16x16x32_bf16 v[38:41], v[164:167], v[188:191], v[38:41]
	v_mfma_f32_16x16x32_bf16 v[34:37], v[172:175], v[188:191], v[34:37]
	v_mfma_f32_16x16x32_bf16 v[22:25], v[164:167], v[196:199], v[22:25]
	v_mfma_f32_16x16x32_bf16 v[18:21], v[172:175], v[196:199], v[18:21]
	v_mfma_f32_16x16x32_bf16 v[6:9], v[164:167], v[224:227], v[6:9]
	v_mfma_f32_16x16x32_bf16 v[2:5], v[172:175], v[224:227], v[2:5]
	v_mfma_f32_16x16x32_bf16 v[54:57], v[168:171], v[184:187], v[54:57]
	v_mfma_f32_16x16x32_bf16 v[50:53], v[176:179], v[184:187], v[50:53]
	v_mfma_f32_16x16x32_bf16 v[38:41], v[168:171], v[192:195], v[38:41]
	v_mfma_f32_16x16x32_bf16 v[34:37], v[176:179], v[192:195], v[34:37]
	v_mfma_f32_16x16x32_bf16 v[22:25], v[168:171], v[200:203], v[22:25]
	v_mfma_f32_16x16x32_bf16 v[18:21], v[176:179], v[200:203], v[18:21]
	v_mfma_f32_16x16x32_bf16 v[6:9], v[168:171], v[228:231], v[6:9]
	v_mfma_f32_16x16x32_bf16 v[2:5], v[176:179], v[228:231], v[2:5]
	s_setprio 0
	s_barrier
	s_add_i32 s50, 0, 0x18000
	s_add_i32 s51, 0, 0x1c000
	v_add_u32_e32 v160, s50, v149
	v_add_u32_e32 v176, s51, v149
	ds_read_b128 v[144:147], v160
	ds_read_b128 v[152:155], v160 offset:1024
	ds_read_b128 v[156:159], v160 offset:2048
	ds_read_b128 v[160:163], v160 offset:3072
	ds_read_b128 v[164:167], v176
	ds_read_b128 v[168:171], v176 offset:1024
	ds_read_b128 v[172:175], v176 offset:2048
	ds_read_b128 v[176:179], v176 offset:3072
	s_add_u32 s14, s20, 0xb0000
	s_addc_u32 s15, s21, 0
	s_mov_b32 m0, s29
	v_lshl_add_u64 v[234:235], s[14:15], 0, v[130:131]
	ds_read_b128 v[180:183], v151 offset:32768
	ds_read_b128 v[184:187], v151 offset:33792
	ds_read_b128 v[188:191], v151 offset:34816
	ds_read_b128 v[192:195], v151 offset:35840
	ds_read_b128 v[196:199], v151 offset:36864
	ds_read_b128 v[200:203], v151 offset:37888
	ds_read_b128 v[224:227], v151 offset:38912
	ds_read_b128 v[228:231], v151 offset:39936
	global_load_lds_dwordx4 v[234:235], off
	v_lshl_add_u64 v[234:235], s[14:15], 0, v[132:133]
	s_mov_b32 m0, s30
	s_nop 0
	global_load_lds_dwordx4 v[234:235], off
	s_waitcnt vmcnt(8)
	s_waitcnt lgkmcnt(0)
	s_barrier
	s_setprio 1
	s_waitcnt lgkmcnt(0)
	v_mfma_f32_16x16x32_bf16 v[126:129], v[144:147], v[180:183], v[126:129]
	v_mfma_f32_16x16x32_bf16 v[122:125], v[156:159], v[180:183], v[122:125]
	v_mfma_f32_16x16x32_bf16 v[110:113], v[144:147], v[188:191], v[110:113]
	v_mfma_f32_16x16x32_bf16 v[106:109], v[156:159], v[188:191], v[106:109]
	v_mfma_f32_16x16x32_bf16 v[94:97], v[144:147], v[196:199], v[94:97]
	v_mfma_f32_16x16x32_bf16 v[90:93], v[156:159], v[196:199], v[90:93]
	v_mfma_f32_16x16x32_bf16 v[78:81], v[144:147], v[224:227], v[78:81]
	v_mfma_f32_16x16x32_bf16 v[74:77], v[156:159], v[224:227], v[74:77]
	v_mfma_f32_16x16x32_bf16 v[126:129], v[152:155], v[184:187], v[126:129]
	v_mfma_f32_16x16x32_bf16 v[122:125], v[160:163], v[184:187], v[122:125]
	v_mfma_f32_16x16x32_bf16 v[110:113], v[152:155], v[192:195], v[110:113]
	v_mfma_f32_16x16x32_bf16 v[106:109], v[160:163], v[192:195], v[106:109]
	v_mfma_f32_16x16x32_bf16 v[94:97], v[152:155], v[200:203], v[94:97]
	v_mfma_f32_16x16x32_bf16 v[90:93], v[160:163], v[200:203], v[90:93]
	v_mfma_f32_16x16x32_bf16 v[78:81], v[152:155], v[228:231], v[78:81]
	v_mfma_f32_16x16x32_bf16 v[74:77], v[160:163], v[228:231], v[74:77]
	v_mfma_f32_16x16x32_bf16 v[118:121], v[164:167], v[180:183], v[118:121]
	v_mfma_f32_16x16x32_bf16 v[114:117], v[172:175], v[180:183], v[114:117]
	v_mfma_f32_16x16x32_bf16 v[102:105], v[164:167], v[188:191], v[102:105]
	v_mfma_f32_16x16x32_bf16 v[98:101], v[172:175], v[188:191], v[98:101]
	v_mfma_f32_16x16x32_bf16 v[86:89], v[164:167], v[196:199], v[86:89]
	v_mfma_f32_16x16x32_bf16 v[82:85], v[172:175], v[196:199], v[82:85]
	v_mfma_f32_16x16x32_bf16 v[70:73], v[164:167], v[224:227], v[70:73]
	v_mfma_f32_16x16x32_bf16 v[66:69], v[172:175], v[224:227], v[66:69]
	v_mfma_f32_16x16x32_bf16 v[118:121], v[168:171], v[184:187], v[118:121]
	v_mfma_f32_16x16x32_bf16 v[114:117], v[176:179], v[184:187], v[114:117]
	v_mfma_f32_16x16x32_bf16 v[102:105], v[168:171], v[192:195], v[102:105]
	v_mfma_f32_16x16x32_bf16 v[98:101], v[176:179], v[192:195], v[98:101]
	v_mfma_f32_16x16x32_bf16 v[86:89], v[168:171], v[200:203], v[86:89]
	v_mfma_f32_16x16x32_bf16 v[82:85], v[176:179], v[200:203], v[82:85]
	v_mfma_f32_16x16x32_bf16 v[70:73], v[168:171], v[228:231], v[70:73]
	v_mfma_f32_16x16x32_bf16 v[66:69], v[176:179], v[228:231], v[66:69]
	s_setprio 0
	s_barrier
; #define PG8_STAGE(bufoff, gbase, voff) do { _Pragma("unroll") for (int _i = 0; _i < 2; ++_i) \
;         __builtin_amdgcn_global_load_lds((const unsigned*)((const char*)(gbase) + (voff)[_i]), (PG8_LAS unsigned*)(lds + (bufoff) + ldsw + _i * 8192), 16, 0, 0); } while (0)
; #define PG8_LDA(dst, b, h) do { _Pragma("unroll") for (int m = 0; m < 4; ++m) _Pragma("unroll") for (int k = 0; k < 2; ++k) dst[m][k] = *(const PG8_LAS bf16x8*)(lds + PG8_SA(b, h) + aoff + m * 2048 + k * 1024); } while (0)
; #define PG8_MMA(ai, bj, At, Bt) do { __builtin_amdgcn_s_setprio(1); _Pragma("unroll") for (int m = 0; m < 4; ++m) _Pragma("unroll") for (int n = 0; n < 2; ++n) _Pragma("unroll") for (int k = 0; k < 2; ++k) \
;         acc[ai][bj][m][n] = __builtin_amdgcn_mfma_f32_16x16x32_bf16(Bt[n][k], At[m][k], acc[ai][bj][m][n], 0, 0, 0); __builtin_amdgcn_s_setprio(0); } while (0)
; #define PG8_WAIT_V(n) asm volatile("s_waitcnt vmcnt(" #n ")" ::: "memory")
; #define PG8_WAIT_L(n) asm volatile("s_waitcnt lgkmcnt(" #n ")" ::: "memory")
; #define PG8_BAR __builtin_amdgcn_s_barrier()
; #define PG8_SCHED __builtin_amdgcn_sched_barrier(0)
; template <class Epi, class Sched, bool ALIGN_EPI = false, bool SP2 = false>
; __device__ __forceinline__ void gemm_phase(PG8_LAS unsigned char* lds, const Gemm g, const Sched& S, const Epi& E) {
;     ...
;             PG8_LDA(At, 1, 1); PG8_STAGE(PG8_SB(1, 0), b3, voffB); PG8_STAGE(PG8_SB(1, 1), b3 + hstep, voffB); PG8_STAGE(PG8_SA(1, 0), a3, voffA);
;             PG8_WAIT_V(8); PG8_WAIT_L(0); PG8_BAR; PG8_MMA(1, 0, At, B0); PG8_MMA(1, 1, At, B1); PG8_BAR; PG8_SCHED;
;     __device__ __forceinline__ void operator()(const f32x4 (&acc)[2][2][4][2], const Unit& u, int wr, int wc, int fr, int fq) const {
;     ...
;                 const int row = row0 + ai * 128 + m * 16; float p = 0.f;
; #pragma unroll
;                 for (int bj = 0; bj < 2; ++bj) {
;                     const size_t off = (size_t)row * D + col0 + bj * 128;
;                     const u32x4 xx = *(const u32x4*)(xb + off);
	s_add_i32 s14, s50, s23
	v_lshl_add_u64 v[138:139], v[138:139], 0, s[86:87]
	s_mov_b32 m0, s14
	ds_read_b128 v[180:183], v151 offset:49152
	ds_read_b128 v[184:187], v151 offset:50176
	ds_read_b128 v[188:191], v151 offset:51200
	ds_read_b128 v[192:195], v151 offset:52224
	ds_read_b128 v[196:199], v151 offset:53248
	ds_read_b128 v[200:203], v151 offset:54272
	ds_read_b128 v[224:227], v151 offset:55296
	ds_read_b128 v[228:231], v151 offset:56320
	global_load_lds_dwordx4 v[138:139], off
	s_add_i32 m0, s14, 0x2000
	s_add_u32 s14, s18, 0xb0080
	v_lshl_add_u64 v[138:139], v[140:141], 0, s[86:87]
	s_addc_u32 s15, s19, 0
	s_add_i32 s18, s51, s23
	global_load_lds_dwordx4 v[138:139], off
	v_lshl_add_u64 v[138:139], s[14:15], 0, v[0:1]
	s_mov_b32 m0, s18
	s_nop 0
	global_load_lds_dwordx4 v[138:139], off
	v_lshl_add_u64 v[138:139], s[14:15], 0, v[134:135]
	s_add_i32 m0, s18, 0x2000
	s_nop 0
	global_load_lds_dwordx4 v[138:139], off
	v_lshl_add_u64 v[138:139], v[204:205], 0, s[86:87]
	s_mov_b32 m0, s38
	s_nop 0
	global_load_lds_dwordx4 v[138:139], off
	v_lshl_add_u64 v[138:139], v[232:233], 0, s[86:87]
	s_mov_b32 m0, s39
	s_nop 0
	global_load_lds_dwordx4 v[138:139], off
	s_waitcnt vmcnt(8)
	s_waitcnt lgkmcnt(0)
	s_barrier
	s_setprio 1
	s_waitcnt lgkmcnt(0)
	v_mfma_f32_16x16x32_bf16 v[62:65], v[144:147], v[180:183], v[62:65]
	v_mfma_f32_16x16x32_bf16 v[58:61], v[156:159], v[180:183], v[58:61]
	v_mfma_f32_16x16x32_bf16 v[46:49], v[144:147], v[188:191], v[46:49]
	v_mfma_f32_16x16x32_bf16 v[42:45], v[156:159], v[188:191], v[42:45]
	v_mfma_f32_16x16x32_bf16 v[30:33], v[144:147], v[196:199], v[30:33]
	v_mfma_f32_16x16x32_bf16 v[26:29], v[156:159], v[196:199], v[26:29]
	v_mfma_f32_16x16x32_bf16 v[14:17], v[144:147], v[224:227], v[14:17]
	v_mfma_f32_16x16x32_bf16 v[10:13], v[156:159], v[224:227], v[10:13]
	v_mfma_f32_16x16x32_bf16 v[62:65], v[152:155], v[184:187], v[62:65]
	v_mfma_f32_16x16x32_bf16 v[58:61], v[160:163], v[184:187], v[58:61]
	v_mfma_f32_16x16x32_bf16 v[46:49], v[152:155], v[192:195], v[46:49]
	v_mfma_f32_16x16x32_bf16 v[42:45], v[160:163], v[192:195], v[42:45]
	v_mfma_f32_16x16x32_bf16 v[30:33], v[152:155], v[200:203], v[30:33]
	v_mfma_f32_16x16x32_bf16 v[26:29], v[160:163], v[200:203], v[26:29]
	v_mfma_f32_16x16x32_bf16 v[14:17], v[152:155], v[228:231], v[14:17]
	v_mfma_f32_16x16x32_bf16 v[10:13], v[160:163], v[228:231], v[10:13]
	v_mfma_f32_16x16x32_bf16 v[54:57], v[164:167], v[180:183], v[54:57]
	v_mfma_f32_16x16x32_bf16 v[50:53], v[172:175], v[180:183], v[50:53]
	v_mfma_f32_16x16x32_bf16 v[38:41], v[164:167], v[188:191], v[38:41]
	v_mfma_f32_16x16x32_bf16 v[34:37], v[172:175], v[188:191], v[34:37]
	v_mfma_f32_16x16x32_bf16 v[22:25], v[164:167], v[196:199], v[22:25]
	v_mfma_f32_16x16x32_bf16 v[18:21], v[172:175], v[196:199], v[18:21]
	v_mfma_f32_16x16x32_bf16 v[6:9], v[164:167], v[224:227], v[6:9]
	v_mfma_f32_16x16x32_bf16 v[2:5], v[172:175], v[224:227], v[2:5]
	v_mfma_f32_16x16x32_bf16 v[54:57], v[168:171], v[184:187], v[54:57]
	v_mfma_f32_16x16x32_bf16 v[50:53], v[176:179], v[184:187], v[50:53]
	v_mfma_f32_16x16x32_bf16 v[38:41], v[168:171], v[192:195], v[38:41]
	v_mfma_f32_16x16x32_bf16 v[34:37], v[176:179], v[192:195], v[34:37]
	v_mfma_f32_16x16x32_bf16 v[22:25], v[168:171], v[200:203], v[22:25]
	v_mfma_f32_16x16x32_bf16 v[18:21], v[176:179], v[200:203], v[18:21]
	v_mfma_f32_16x16x32_bf16 v[6:9], v[168:171], v[228:231], v[6:9]
	v_mfma_f32_16x16x32_bf16 v[2:5], v[176:179], v[228:231], v[2:5]
	s_setprio 0
	s_barrier
	s_add_i32 s49, s49, 2
	s_add_u32 s47, s47, 0x100
	s_addc_u32 s48, s48, 0
	s_cmp_gt_u32 s49, 41
	s_mov_b64 s[14:15], s[16:17]
	s_cbranch_scc0 .LBB0_362
	v_lshl_add_u32 v138, s46, 8, v148
	v_lshl_or_b32 v139, s45, 8, v150
	v_lshlrev_b32_e32 v138, 11, v138
	v_lshl_add_u32 v138, v139, 1, v138
	global_load_dwordx4 v[152:155], v138, s[34:35]
	global_load_dwordx4 v[156:159], v138, s[34:35] offset:256
	v_add_u32_e32 v139, 0x8000, v138
	global_load_dwordx4 v[160:163], v139, s[34:35]
	global_load_dwordx4 v[164:167], v139, s[34:35] offset:256
	v_add_u32_e32 v139, 0x10000, v138
	global_load_dwordx4 v[168:171], v139, s[34:35]
	global_load_dwordx4 v[172:175], v139, s[34:35] offset:256
	v_add_u32_e32 v139, 0x18000, v138
	global_load_dwordx4 v[176:179], v139, s[34:35]
	global_load_dwordx4 v[180:183], v139, s[34:35] offset:256
	v_add_u32_e32 v139, 0x40000, v138
	global_load_dwordx4 v[184:187], v139, s[34:35]
	global_load_dwordx4 v[188:191], v139, s[34:35] offset:256
	v_add_u32_e32 v139, 0x48000, v138
	global_load_dwordx4 v[192:195], v139, s[34:35]
	global_load_dwordx4 v[196:199], v139, s[34:35] offset:256
	v_add_u32_e32 v139, 0x50000, v138
	global_load_dwordx4 v[200:203], v139, s[34:35]
	global_load_dwordx4 v[224:227], v139, s[34:35] offset:256
	v_add_u32_e32 v139, 0x58000, v138
	global_load_dwordx4 v[228:231], v139, s[34:35]
	global_load_dwordx4 v[232:235], v139, s[34:35] offset:256
	s_and_b64 vcc, exec, s[10:11]
	s_cbranch_vccz .LBB0_365
	s_barrier

; #define PG8_STAGE(bufoff, gbase, voff) do { _Pragma("unroll") for (int _i = 0; _i < 2; ++_i) \
;         __builtin_amdgcn_global_load_lds((const unsigned*)((const char*)(gbase) + (voff)[_i]), (PG8_LAS unsigned*)(lds + (bufoff) + ldsw + _i * 8192), 16, 0, 0); } while (0)
; #define PG8_LDA(dst, b, h) do { _Pragma("unroll") for (int m = 0; m < 4; ++m) _Pragma("unroll") for (int k = 0; k < 2; ++k) dst[m][k] = *(const PG8_LAS bf16x8*)(lds + PG8_SA(b, h) + aoff + m * 2048 + k * 1024); } while (0)
; #define PG8_LDB(dst, b, h) do { _Pragma("unroll") for (int n = 0; n < 2; ++n) _Pragma("unroll") for (int k = 0; k < 2; ++k) dst[n][k] = *(const PG8_LAS bf16x8*)(lds + PG8_SB(b, h) + boff + n * 2048 + k * 1024); } while (0)
; #define PG8_MMA(ai, bj, At, Bt) do { __builtin_amdgcn_s_setprio(1); _Pragma("unroll") for (int m = 0; m < 4; ++m) _Pragma("unroll") for (int n = 0; n < 2; ++n) _Pragma("unroll") for (int k = 0; k < 2; ++k) \
;         acc[ai][bj][m][n] = __builtin_amdgcn_mfma_f32_16x16x32_bf16(Bt[n][k], At[m][k], acc[ai][bj][m][n], 0, 0, 0); __builtin_amdgcn_s_setprio(0); } while (0)
; #define PG8_WAIT_V(n) asm volatile("s_waitcnt vmcnt(" #n ")" ::: "memory")
; template <class Epi, class Sched, bool ALIGN_EPI = false, bool SP2 = false>
; __device__ __forceinline__ void gemm_phase(PG8_LAS unsigned char* lds, const Gemm g, const Sched& S, const Epi& E) {
;     ...
;         const char* nA = has_next ? (const char*)g.A + (size_t)nxt.pm * tstep : cA; const char* nB = has_next ? (const char*)g.Bt + (size_t)nxt.pn * tstep : cB;
;         for (int t = 0; t < nt; t += 2) {
;             const bool last = (t == nt - 2);
;             const char* a1 = cA + (size_t)(t + 1) * kstep;
;             const char* a2 = last ? nA : cA + (size_t)(t + 2) * kstep; const char* b2 = last ? nB : cB + (size_t)(t + 2) * kstep;
;             const char* a3 = a2 + kstep; const char* b3 = b2 + kstep;
;             if (last && has_next) S.a_ready(nxt);
;             if constexpr (SP2) {
;             PG8_LDB(B0, 0, 0); PG8_LDB(B1, 0, 1); PG8_SCHED; PG8_LDA(At, 0, 0); PG8_STAGE(PG8_SA(1, 1), a1 + hstep, voffA);
;             PG8_WAIT_V(8); PG8_WAIT_L(0); PG8_BAR; PG8_MMA(0, 0, At, B0); PG8_MMA(0, 1, At, B1); PG8_BAR; PG8_SCHED;
;             PG8_LDA(At, 0, 1); PG8_STAGE(PG8_SB(0, 0), b2, voffB); PG8_STAGE(PG8_SB(0, 1), b2 + hstep, voffB); PG8_STAGE(PG8_SA(0, 0), a2, voffA);
.LBB0_491:
	s_ashr_i32 s15, s14, 31
	s_lshl_b64 s[16:17], s[14:15], 19
	s_add_u32 s16, s34, s16
	s_addc_u32 s17, s35, s17
	s_and_b64 s[18:19], s[2:3], exec
	s_cselect_b32 s5, s17, s9
	s_cselect_b32 s7, s16, s8
	s_ashr_i32 s13, s12, 31
	s_lshl_b64 s[18:19], s[12:13], 19
	s_add_u32 s18, s27, s18
	s_addc_u32 s19, s29, s19
	s_and_b64 s[22:23], s[2:3], exec
	s_cselect_b32 s13, s19, s21
	s_cselect_b32 s15, s18, s20
	s_add_u32 s8, s8, 0x40080
	s_addc_u32 s9, s9, 0
	s_add_u32 s45, s20, 0x100
	s_addc_u32 s46, s21, 0
	s_mov_b32 s47, -2
	s_add_u32 s20, s8, 0xfffc0080
	s_addc_u32 s21, s9, -1
	s_add_i32 s48, 0, 0x10000
	s_cmp_eq_u32 s47, 12
	s_cselect_b32 s23, s5, s21
	s_cselect_b32 s22, s7, s20
	v_add_u32_e32 v138, s48, v161
	s_cselect_b32 s21, s13, s46
	s_cselect_b32 s20, s15, s45
	s_add_i32 s50, 0, 0x14000
	ds_read_b128 v[144:147], v138
	ds_read_b128 v[148:151], v138 offset:1024
	ds_read_b128 v[152:155], v138 offset:2048
	ds_read_b128 v[156:159], v138 offset:3072
	v_add_u32_e32 v138, s50, v161
	ds_read_b128 v[166:169], v138
	ds_read_b128 v[170:173], v138 offset:1024
	ds_read_b128 v[174:177], v138 offset:2048
	ds_read_b128 v[178:181], v138 offset:3072
	v_lshl_add_u64 v[138:139], s[8:9], 0, v[136:137]
	s_add_i32 m0, s30, 0xc000
	ds_read_b128 v[182:185], v164
	ds_read_b128 v[186:189], v164 offset:1024
	ds_read_b128 v[190:193], v164 offset:2048
	ds_read_b128 v[194:197], v164 offset:3072
	ds_read_b128 v[198:201], v164 offset:4096
	ds_read_b128 v[202:205], v164 offset:5120
	ds_read_b128 v[224:227], v164 offset:6144
	ds_read_b128 v[228:231], v164 offset:7168
	global_load_lds_dwordx4 v[138:139], off
	v_lshl_add_u64 v[138:139], s[8:9], 0, v[142:143]
	s_add_i32 m0, s30, 0xe000
	s_nop 0
	global_load_lds_dwordx4 v[138:139], off
	s_waitcnt vmcnt(8)
	s_waitcnt lgkmcnt(0)
	s_barrier
	s_setprio 1
	s_waitcnt lgkmcnt(0)
	v_mfma_f32_16x16x32_bf16 v[126:129], v[144:147], v[182:185], 0
	v_mfma_f32_16x16x32_bf16 v[122:125], v[152:155], v[182:185], 0
	v_mfma_f32_16x16x32_bf16 v[110:113], v[144:147], v[190:193], 0
	v_mfma_f32_16x16x32_bf16 v[106:109], v[152:155], v[190:193], 0
	v_mfma_f32_16x16x32_bf16 v[94:97], v[144:147], v[198:201], 0
	v_mfma_f32_16x16x32_bf16 v[90:93], v[152:155], v[198:201], 0
	v_mfma_f32_16x16x32_bf16 v[78:81], v[144:147], v[224:227], 0
	v_mfma_f32_16x16x32_bf16 v[74:77], v[152:155], v[224:227], 0
	v_mfma_f32_16x16x32_bf16 v[126:129], v[148:151], v[186:189], v[126:129]
	v_mfma_f32_16x16x32_bf16 v[122:125], v[156:159], v[186:189], v[122:125]
	v_mfma_f32_16x16x32_bf16 v[110:113], v[148:151], v[194:197], v[110:113]
	v_mfma_f32_16x16x32_bf16 v[106:109], v[156:159], v[194:197], v[106:109]
	v_mfma_f32_16x16x32_bf16 v[94:97], v[148:151], v[202:205], v[94:97]
	v_mfma_f32_16x16x32_bf16 v[90:93], v[156:159], v[202:205], v[90:93]
	v_mfma_f32_16x16x32_bf16 v[78:81], v[148:151], v[228:231], v[78:81]
	v_mfma_f32_16x16x32_bf16 v[74:77], v[156:159], v[228:231], v[74:77]
	v_mfma_f32_16x16x32_bf16 v[118:121], v[166:169], v[182:185], 0
	v_mfma_f32_16x16x32_bf16 v[114:117], v[174:177], v[182:185], 0
	v_mfma_f32_16x16x32_bf16 v[102:105], v[166:169], v[190:193], 0
	v_mfma_f32_16x16x32_bf16 v[98:101], v[174:177], v[190:193], 0
	v_mfma_f32_16x16x32_bf16 v[86:89], v[166:169], v[198:201], 0
	v_mfma_f32_16x16x32_bf16 v[82:85], v[174:177], v[198:201], 0
	v_mfma_f32_16x16x32_bf16 v[70:73], v[166:169], v[224:227], 0
	v_mfma_f32_16x16x32_bf16 v[66:69], v[174:177], v[224:227], 0
	v_mfma_f32_16x16x32_bf16 v[118:121], v[170:173], v[186:189], v[118:121]
	v_mfma_f32_16x16x32_bf16 v[114:117], v[178:181], v[186:189], v[114:117]
	v_mfma_f32_16x16x32_bf16 v[102:105], v[170:173], v[194:197], v[102:105]
	v_mfma_f32_16x16x32_bf16 v[98:101], v[178:181], v[194:197], v[98:101]
	v_mfma_f32_16x16x32_bf16 v[86:89], v[170:173], v[202:205], v[86:89]
	v_mfma_f32_16x16x32_bf16 v[82:85], v[178:181], v[202:205], v[82:85]
	v_mfma_f32_16x16x32_bf16 v[70:73], v[170:173], v[228:231], v[70:73]
	v_mfma_f32_16x16x32_bf16 v[66:69], v[178:181], v[228:231], v[66:69]
	s_setprio 0
	s_barrier
	s_add_i32 s48, s48, s26
	v_lshl_add_u64 v[138:139], s[20:21], 0, v[0:1]
	s_mov_b32 m0, s48
	ds_read_b128 v[182:185], v164 offset:16384
	ds_read_b128 v[186:189], v164 offset:17408
	ds_read_b128 v[190:193], v164 offset:18432
	ds_read_b128 v[194:197], v164 offset:19456
	ds_read_b128 v[198:201], v164 offset:20480
	ds_read_b128 v[202:205], v164 offset:21504
	ds_read_b128 v[224:227], v164 offset:22528
	ds_read_b128 v[228:231], v164 offset:23552
	global_load_lds_dwordx4 v[138:139], off
	s_add_i32 m0, s48, 0x2000
	s_add_u32 s48, s20, 0x40000
	v_lshl_add_u64 v[140:141], s[20:21], 0, v[134:135]
	s_addc_u32 s49, s21, 0
	s_add_i32 s50, s50, s26
	global_load_lds_dwordx4 v[140:141], off
	v_lshl_add_u64 v[232:233], s[48:49], 0, v[0:1]
	s_mov_b32 m0, s50
	v_lshl_add_u64 v[234:235], s[22:23], 0, v[132:133]
	global_load_lds_dwordx4 v[232:233], off
	v_lshl_add_u64 v[232:233], s[48:49], 0, v[134:135]
	s_add_i32 m0, s50, 0x2000
	s_nop 0
	global_load_lds_dwordx4 v[232:233], off
	v_lshl_add_u64 v[232:233], s[22:23], 0, v[130:131]
	s_mov_b32 m0, s30
	s_nop 0
	global_load_lds_dwordx4 v[232:233], off
	s_mov_b32 m0, s31
	s_nop 0
	global_load_lds_dwordx4 v[234:235], off
	s_waitcnt vmcnt(8)
	s_waitcnt lgkmcnt(0)
	s_barrier
; #define PG8_STAGE(bufoff, gbase, voff) do { _Pragma("unroll") for (int _i = 0; _i < 2; ++_i) \
;         __builtin_amdgcn_global_load_lds((const unsigned*)((const char*)(gbase) + (voff)[_i]), (PG8_LAS unsigned*)(lds + (bufoff) + ldsw + _i * 8192), 16, 0, 0); } while (0)
; #define PG8_LDA(dst, b, h) do { _Pragma("unroll") for (int m = 0; m < 4; ++m) _Pragma("unroll") for (int k = 0; k < 2; ++k) dst[m][k] = *(const PG8_LAS bf16x8*)(lds + PG8_SA(b, h) + aoff + m * 2048 + k * 1024); } while (0)
; #define PG8_LDB(dst, b, h) do { _Pragma("unroll") for (int n = 0; n < 2; ++n) _Pragma("unroll") for (int k = 0; k < 2; ++k) dst[n][k] = *(const PG8_LAS bf16x8*)(lds + PG8_SB(b, h) + boff + n * 2048 + k * 1024); } while (0)
; #define PG8_MMA(ai, bj, At, Bt) do { __builtin_amdgcn_s_setprio(1); _Pragma("unroll") for (int m = 0; m < 4; ++m) _Pragma("unroll") for (int n = 0; n < 2; ++n) _Pragma("unroll") for (int k = 0; k < 2; ++k) \
;         acc[ai][bj][m][n] = __builtin_amdgcn_mfma_f32_16x16x32_bf16(Bt[n][k], At[m][k], acc[ai][bj][m][n], 0, 0, 0); __builtin_amdgcn_s_setprio(0); } while (0)
; #define PG8_WAIT_V(n) asm volatile("s_waitcnt vmcnt(" #n ")" ::: "memory")
; #define PG8_WAIT_L(n) asm volatile("s_waitcnt lgkmcnt(" #n ")" ::: "memory")
; #define PG8_BAR __builtin_amdgcn_s_barrier()
; #define PG8_SCHED __builtin_amdgcn_sched_barrier(0)
; template <class Epi, class Sched, bool ALIGN_EPI = false, bool SP2 = false>
; __device__ __forceinline__ void gemm_phase(PG8_LAS unsigned char* lds, const Gemm g, const Sched& S, const Epi& E) {
;     ...
;             PG8_LDA(At, 0, 1); PG8_STAGE(PG8_SB(0, 0), b2, voffB); PG8_STAGE(PG8_SB(0, 1), b2 + hstep, voffB); PG8_STAGE(PG8_SA(0, 0), a2, voffA);
;             PG8_WAIT_V(8); PG8_WAIT_L(0); PG8_BAR; PG8_MMA(1, 0, At, B0); PG8_MMA(1, 1, At, B1); PG8_BAR; PG8_SCHED;
;             PG8_LDB(B0, 1, 0); PG8_LDB(B1, 1, 1); PG8_SCHED; PG8_LDA(At, 1, 0); PG8_STAGE(PG8_SA(0, 1), a2 + hstep, voffA);
;             PG8_WAIT_V(8); PG8_WAIT_L(0); PG8_BAR; PG8_MMA(0, 0, At, B0); PG8_MMA(0, 1, At, B1); PG8_BAR; PG8_SCHED;
	s_setprio 1
	s_waitcnt lgkmcnt(0)
	v_mfma_f32_16x16x32_bf16 v[62:65], v[144:147], v[182:185], 0
	v_mfma_f32_16x16x32_bf16 v[58:61], v[152:155], v[182:185], 0
	v_mfma_f32_16x16x32_bf16 v[46:49], v[144:147], v[190:193], 0
	v_mfma_f32_16x16x32_bf16 v[42:45], v[152:155], v[190:193], 0
	v_mfma_f32_16x16x32_bf16 v[30:33], v[144:147], v[198:201], 0
	v_mfma_f32_16x16x32_bf16 v[26:29], v[152:155], v[198:201], 0
	v_mfma_f32_16x16x32_bf16 v[14:17], v[144:147], v[224:227], 0
	v_mfma_f32_16x16x32_bf16 v[10:13], v[152:155], v[224:227], 0
	v_mfma_f32_16x16x32_bf16 v[62:65], v[148:151], v[186:189], v[62:65]
	v_mfma_f32_16x16x32_bf16 v[58:61], v[156:159], v[186:189], v[58:61]
	v_mfma_f32_16x16x32_bf16 v[46:49], v[148:151], v[194:197], v[46:49]
	v_mfma_f32_16x16x32_bf16 v[42:45], v[156:159], v[194:197], v[42:45]
	v_mfma_f32_16x16x32_bf16 v[30:33], v[148:151], v[202:205], v[30:33]
	v_mfma_f32_16x16x32_bf16 v[26:29], v[156:159], v[202:205], v[26:29]
	v_mfma_f32_16x16x32_bf16 v[14:17], v[148:151], v[228:231], v[14:17]
	v_mfma_f32_16x16x32_bf16 v[10:13], v[156:159], v[228:231], v[10:13]
	v_mfma_f32_16x16x32_bf16 v[54:57], v[166:169], v[182:185], 0
	v_mfma_f32_16x16x32_bf16 v[50:53], v[174:177], v[182:185], 0
	v_mfma_f32_16x16x32_bf16 v[38:41], v[166:169], v[190:193], 0
	v_mfma_f32_16x16x32_bf16 v[34:37], v[174:177], v[190:193], 0
	v_mfma_f32_16x16x32_bf16 v[22:25], v[166:169], v[198:201], 0
	v_mfma_f32_16x16x32_bf16 v[18:21], v[174:177], v[198:201], 0
	v_mfma_f32_16x16x32_bf16 v[6:9], v[166:169], v[224:227], 0
	v_mfma_f32_16x16x32_bf16 v[2:5], v[174:177], v[224:227], 0
	v_mfma_f32_16x16x32_bf16 v[54:57], v[170:173], v[186:189], v[54:57]
	v_mfma_f32_16x16x32_bf16 v[50:53], v[178:181], v[186:189], v[50:53]
	v_mfma_f32_16x16x32_bf16 v[38:41], v[170:173], v[194:197], v[38:41]
	v_mfma_f32_16x16x32_bf16 v[34:37], v[178:181], v[194:197], v[34:37]
	v_mfma_f32_16x16x32_bf16 v[22:25], v[170:173], v[202:205], v[22:25]
	v_mfma_f32_16x16x32_bf16 v[18:21], v[178:181], v[202:205], v[18:21]
	v_mfma_f32_16x16x32_bf16 v[6:9], v[170:173], v[228:231], v[6:9]
	v_mfma_f32_16x16x32_bf16 v[2:5], v[178:181], v[228:231], v[2:5]
	s_setprio 0
	s_barrier
	s_add_i32 s48, 0, 0x18000
	s_add_i32 s49, 0, 0x1c000
	v_add_u32_e32 v156, s48, v161
	v_add_u32_e32 v165, s49, v161
	ds_read_b128 v[144:147], v156
	ds_read_b128 v[148:151], v156 offset:1024
	ds_read_b128 v[152:155], v156 offset:2048
	ds_read_b128 v[156:159], v156 offset:3072
	ds_read_b128 v[166:169], v165
	ds_read_b128 v[170:173], v165 offset:1024
	ds_read_b128 v[174:177], v165 offset:2048
	ds_read_b128 v[178:181], v165 offset:3072
	s_add_u32 s22, s22, 0x40000
	s_addc_u32 s23, s23, 0
	s_mov_b32 m0, s38
	v_lshl_add_u64 v[236:237], s[22:23], 0, v[130:131]
	ds_read_b128 v[182:185], v164 offset:32768
	ds_read_b128 v[186:189], v164 offset:33792
	ds_read_b128 v[190:193], v164 offset:34816
	ds_read_b128 v[194:197], v164 offset:35840
	ds_read_b128 v[198:201], v164 offset:36864
	ds_read_b128 v[202:205], v164 offset:37888
	ds_read_b128 v[224:227], v164 offset:38912
	ds_read_b128 v[228:231], v164 offset:39936
	global_load_lds_dwordx4 v[236:237], off
	v_lshl_add_u64 v[236:237], s[22:23], 0, v[132:133]
	s_mov_b32 m0, s39
	s_nop 0
	global_load_lds_dwordx4 v[236:237], off
	s_waitcnt vmcnt(8)
	s_waitcnt lgkmcnt(0)
	s_barrier
	s_setprio 1
	s_waitcnt lgkmcnt(0)
	v_mfma_f32_16x16x32_bf16 v[126:129], v[144:147], v[182:185], v[126:129]
	v_mfma_f32_16x16x32_bf16 v[122:125], v[152:155], v[182:185], v[122:125]
	v_mfma_f32_16x16x32_bf16 v[110:113], v[144:147], v[190:193], v[110:113]
	v_mfma_f32_16x16x32_bf16 v[106:109], v[152:155], v[190:193], v[106:109]
	v_mfma_f32_16x16x32_bf16 v[94:97], v[144:147], v[198:201], v[94:97]
	v_mfma_f32_16x16x32_bf16 v[90:93], v[152:155], v[198:201], v[90:93]
	v_mfma_f32_16x16x32_bf16 v[78:81], v[144:147], v[224:227], v[78:81]
	v_mfma_f32_16x16x32_bf16 v[74:77], v[152:155], v[224:227], v[74:77]
	v_mfma_f32_16x16x32_bf16 v[126:129], v[148:151], v[186:189], v[126:129]
	v_mfma_f32_16x16x32_bf16 v[122:125], v[156:159], v[186:189], v[122:125]
	v_mfma_f32_16x16x32_bf16 v[110:113], v[148:151], v[194:197], v[110:113]
	v_mfma_f32_16x16x32_bf16 v[106:109], v[156:159], v[194:197], v[106:109]
	v_mfma_f32_16x16x32_bf16 v[94:97], v[148:151], v[202:205], v[94:97]
	v_mfma_f32_16x16x32_bf16 v[90:93], v[156:159], v[202:205], v[90:93]
	v_mfma_f32_16x16x32_bf16 v[78:81], v[148:151], v[228:231], v[78:81]
	v_mfma_f32_16x16x32_bf16 v[74:77], v[156:159], v[228:231], v[74:77]
	v_mfma_f32_16x16x32_bf16 v[118:121], v[166:169], v[182:185], v[118:121]
	v_mfma_f32_16x16x32_bf16 v[114:117], v[174:177], v[182:185], v[114:117]
	v_mfma_f32_16x16x32_bf16 v[102:105], v[166:169], v[190:193], v[102:105]
	v_mfma_f32_16x16x32_bf16 v[98:101], v[174:177], v[190:193], v[98:101]
	v_mfma_f32_16x16x32_bf16 v[86:89], v[166:169], v[198:201], v[86:89]
	v_mfma_f32_16x16x32_bf16 v[82:85], v[174:177], v[198:201], v[82:85]
	v_mfma_f32_16x16x32_bf16 v[70:73], v[166:169], v[224:227], v[70:73]
	v_mfma_f32_16x16x32_bf16 v[66:69], v[174:177], v[224:227], v[66:69]
	v_mfma_f32_16x16x32_bf16 v[118:121], v[170:173], v[186:189], v[118:121]
	v_mfma_f32_16x16x32_bf16 v[114:117], v[178:181], v[186:189], v[114:117]
	v_mfma_f32_16x16x32_bf16 v[102:105], v[170:173], v[194:197], v[102:105]
	v_mfma_f32_16x16x32_bf16 v[98:101], v[178:181], v[194:197], v[98:101]
	v_mfma_f32_16x16x32_bf16 v[86:89], v[170:173], v[202:205], v[86:89]
	v_mfma_f32_16x16x32_bf16 v[82:85], v[178:181], v[202:205], v[82:85]
	v_mfma_f32_16x16x32_bf16 v[70:73], v[170:173], v[228:231], v[70:73]
	v_mfma_f32_16x16x32_bf16 v[66:69], v[178:181], v[228:231], v[66:69]
	s_setprio 0
	s_barrier
; #define PG8_STAGE(bufoff, gbase, voff) do { _Pragma("unroll") for (int _i = 0; _i < 2; ++_i) \
;         __builtin_amdgcn_global_load_lds((const unsigned*)((const char*)(gbase) + (voff)[_i]), (PG8_LAS unsigned*)(lds + (bufoff) + ldsw + _i * 8192), 16, 0, 0); } while (0)
; #define PG8_LDA(dst, b, h) do { _Pragma("unroll") for (int m = 0; m < 4; ++m) _Pragma("unroll") for (int k = 0; k < 2; ++k) dst[m][k] = *(const PG8_LAS bf16x8*)(lds + PG8_SA(b, h) + aoff + m * 2048 + k * 1024); } while (0)
; #define PG8_LDB(dst, b, h) do { _Pragma("unroll") for (int n = 0; n < 2; ++n) _Pragma("unroll") for (int k = 0; k < 2; ++k) dst[n][k] = *(const PG8_LAS bf16x8*)(lds + PG8_SB(b, h) + boff + n * 2048 + k * 1024); } while (0)
; #define PG8_MMA(ai, bj, At, Bt) do { __builtin_amdgcn_s_setprio(1); _Pragma("unroll") for (int m = 0; m < 4; ++m) _Pragma("unroll") for (int n = 0; n < 2; ++n) _Pragma("unroll") for (int k = 0; k < 2; ++k) \
;         acc[ai][bj][m][n] = __builtin_amdgcn_mfma_f32_16x16x32_bf16(Bt[n][k], At[m][k], acc[ai][bj][m][n], 0, 0, 0); __builtin_amdgcn_s_setprio(0); } while (0)
; #define PG8_WAIT_V(n) asm volatile("s_waitcnt vmcnt(" #n ")" ::: "memory")
; template <class Epi, class Sched, bool ALIGN_EPI = false, bool SP2 = false>
; __device__ __forceinline__ void gemm_phase(PG8_LAS unsigned char* lds, const Gemm g, const Sched& S, const Epi& E) {
;     ...
;             PG8_LDB(B0, 0, 0); PG8_LDB(B1, 0, 1); PG8_SCHED; PG8_LDA(At, 0, 0); PG8_STAGE(PG8_SA(1, 1), a1 + hstep, voffA);
;             PG8_WAIT_V(8); PG8_WAIT_L(0); PG8_BAR; PG8_MMA(0, 0, At, B0); PG8_MMA(0, 1, At, B1); PG8_BAR; PG8_SCHED;
;             PG8_LDA(At, 0, 1); PG8_STAGE(PG8_SB(0, 0), b2, voffB); PG8_STAGE(PG8_SB(0, 1), b2 + hstep, voffB); PG8_STAGE(PG8_SA(0, 0), a2, voffA);
;             PG8_WAIT_V(8); PG8_WAIT_L(0); PG8_BAR; PG8_MMA(1, 0, At, B0); PG8_MMA(1, 1, At, B1); PG8_BAR; PG8_SCHED;
;             PG8_LDB(B0, 1, 0); PG8_LDB(B1, 1, 1); PG8_SCHED; PG8_LDA(At, 1, 0); PG8_STAGE(PG8_SA(0, 1), a2 + hstep, voffA);
;             PG8_WAIT_V(8); PG8_WAIT_L(0); PG8_BAR; PG8_MMA(0, 0, At, B0); PG8_MMA(0, 1, At, B1); PG8_BAR; PG8_SCHED;
;             PG8_LDA(At, 1, 1); PG8_STAGE(PG8_SB(1, 0), b3, voffB); PG8_STAGE(PG8_SB(1, 1), b3 + hstep, voffB); PG8_STAGE(PG8_SA(1, 0), a3, voffA);
;             PG8_WAIT_V(8); PG8_WAIT_L(0); PG8_BAR; PG8_MMA(1, 0, At, B0); PG8_MMA(1, 1, At, B1); PG8_BAR; PG8_SCHED;
	s_add_i32 s22, s48, s26
	v_lshl_add_u64 v[138:139], v[138:139], 0, s[86:87]
	s_mov_b32 m0, s22
	ds_read_b128 v[182:185], v164 offset:49152
	ds_read_b128 v[186:189], v164 offset:50176
	ds_read_b128 v[190:193], v164 offset:51200
	ds_read_b128 v[194:197], v164 offset:52224
	ds_read_b128 v[198:201], v164 offset:53248
	ds_read_b128 v[202:205], v164 offset:54272
	ds_read_b128 v[224:227], v164 offset:55296
	ds_read_b128 v[228:231], v164 offset:56320
	global_load_lds_dwordx4 v[138:139], off
	s_add_i32 m0, s22, 0x2000
	s_add_u32 s20, s20, 0x40080
	v_lshl_add_u64 v[138:139], v[140:141], 0, s[86:87]
	s_addc_u32 s21, s21, 0
	s_add_i32 s22, s49, s26
	global_load_lds_dwordx4 v[138:139], off
	v_lshl_add_u64 v[138:139], s[20:21], 0, v[0:1]
	s_mov_b32 m0, s22
	s_nop 0
	global_load_lds_dwordx4 v[138:139], off
	v_lshl_add_u64 v[138:139], s[20:21], 0, v[134:135]
	s_add_i32 m0, s22, 0x2000
	s_nop 0
	global_load_lds_dwordx4 v[138:139], off
	v_lshl_add_u64 v[138:139], v[232:233], 0, s[86:87]
	s_mov_b32 m0, s41
	s_nop 0
	global_load_lds_dwordx4 v[138:139], off
	v_lshl_add_u64 v[138:139], v[234:235], 0, s[86:87]
	s_mov_b32 m0, s42
	s_nop 0
	global_load_lds_dwordx4 v[138:139], off
	s_waitcnt vmcnt(8)
	s_waitcnt lgkmcnt(0)
	s_barrier
	s_setprio 1
	s_waitcnt lgkmcnt(0)
	v_mfma_f32_16x16x32_bf16 v[62:65], v[144:147], v[182:185], v[62:65]
	v_mfma_f32_16x16x32_bf16 v[58:61], v[152:155], v[182:185], v[58:61]
	v_mfma_f32_16x16x32_bf16 v[46:49], v[144:147], v[190:193], v[46:49]
	v_mfma_f32_16x16x32_bf16 v[42:45], v[152:155], v[190:193], v[42:45]
	v_mfma_f32_16x16x32_bf16 v[30:33], v[144:147], v[198:201], v[30:33]
	v_mfma_f32_16x16x32_bf16 v[26:29], v[152:155], v[198:201], v[26:29]
	v_mfma_f32_16x16x32_bf16 v[14:17], v[144:147], v[224:227], v[14:17]
	v_mfma_f32_16x16x32_bf16 v[10:13], v[152:155], v[224:227], v[10:13]
	v_mfma_f32_16x16x32_bf16 v[62:65], v[148:151], v[186:189], v[62:65]
	v_mfma_f32_16x16x32_bf16 v[58:61], v[156:159], v[186:189], v[58:61]
	v_mfma_f32_16x16x32_bf16 v[46:49], v[148:151], v[194:197], v[46:49]
	v_mfma_f32_16x16x32_bf16 v[42:45], v[156:159], v[194:197], v[42:45]
	v_mfma_f32_16x16x32_bf16 v[30:33], v[148:151], v[202:205], v[30:33]
	v_mfma_f32_16x16x32_bf16 v[26:29], v[156:159], v[202:205], v[26:29]
	v_mfma_f32_16x16x32_bf16 v[14:17], v[148:151], v[228:231], v[14:17]
	v_mfma_f32_16x16x32_bf16 v[10:13], v[156:159], v[228:231], v[10:13]
	v_mfma_f32_16x16x32_bf16 v[54:57], v[166:169], v[182:185], v[54:57]
	v_mfma_f32_16x16x32_bf16 v[50:53], v[174:177], v[182:185], v[50:53]
	v_mfma_f32_16x16x32_bf16 v[38:41], v[166:169], v[190:193], v[38:41]
	v_mfma_f32_16x16x32_bf16 v[34:37], v[174:177], v[190:193], v[34:37]
	v_mfma_f32_16x16x32_bf16 v[22:25], v[166:169], v[198:201], v[22:25]
	v_mfma_f32_16x16x32_bf16 v[18:21], v[174:177], v[198:201], v[18:21]
	v_mfma_f32_16x16x32_bf16 v[6:9], v[166:169], v[224:227], v[6:9]
	v_mfma_f32_16x16x32_bf16 v[2:5], v[174:177], v[224:227], v[2:5]
	v_mfma_f32_16x16x32_bf16 v[54:57], v[170:173], v[186:189], v[54:57]
	v_mfma_f32_16x16x32_bf16 v[50:53], v[178:181], v[186:189], v[50:53]
	v_mfma_f32_16x16x32_bf16 v[38:41], v[170:173], v[194:197], v[38:41]
	v_mfma_f32_16x16x32_bf16 v[34:37], v[178:181], v[194:197], v[34:37]
	v_mfma_f32_16x16x32_bf16 v[22:25], v[170:173], v[202:205], v[22:25]
	v_mfma_f32_16x16x32_bf16 v[18:21], v[178:181], v[202:205], v[18:21]
	v_mfma_f32_16x16x32_bf16 v[6:9], v[170:173], v[228:231], v[6:9]
	v_mfma_f32_16x16x32_bf16 v[2:5], v[178:181], v[228:231], v[2:5]
	s_setprio 0
	s_barrier
	s_add_i32 s47, s47, 2
	s_add_u32 s8, s8, 0x100
	s_addc_u32 s9, s9, 0
	s_add_u32 s45, s45, 0x100
	s_addc_u32 s46, s46, 0
	s_cmp_gt_u32 s47, 13
	s_cbranch_scc1 .Lpeel_exit_pj
.LBB0_492:
	s_add_u32 s20, s8, 0xfffc0080
	s_addc_u32 s21, s9, -1
	s_add_i32 s48, 0, 0x10000
	s_cmp_eq_u32 s47, 12
	s_cselect_b32 s23, s5, s21
	s_cselect_b32 s22, s7, s20
	v_add_u32_e32 v138, s48, v161
	s_cselect_b32 s21, s13, s46
	s_cselect_b32 s20, s15, s45
	s_add_i32 s50, 0, 0x14000
	ds_read_b128 v[144:147], v138
	ds_read_b128 v[148:151], v138 offset:1024
	ds_read_b128 v[152:155], v138 offset:2048
	ds_read_b128 v[156:159], v138 offset:3072
	v_add_u32_e32 v138, s50, v161
	ds_read_b128 v[166:169], v138
	ds_read_b128 v[170:173], v138 offset:1024
	ds_read_b128 v[174:177], v138 offset:2048
	ds_read_b128 v[178:181], v138 offset:3072
	v_lshl_add_u64 v[138:139], s[8:9], 0, v[136:137]
	s_add_i32 m0, s30, 0xc000
	ds_read_b128 v[182:185], v164
	ds_read_b128 v[186:189], v164 offset:1024
	ds_read_b128 v[190:193], v164 offset:2048
	ds_read_b128 v[194:197], v164 offset:3072
	ds_read_b128 v[198:201], v164 offset:4096
	ds_read_b128 v[202:205], v164 offset:5120
	ds_read_b128 v[224:227], v164 offset:6144
	ds_read_b128 v[228:231], v164 offset:7168
	global_load_lds_dwordx4 v[138:139], off
	v_lshl_add_u64 v[138:139], s[8:9], 0, v[142:143]
	s_add_i32 m0, s30, 0xe000
	s_nop 0
	global_load_lds_dwordx4 v[138:139], off
	s_waitcnt vmcnt(8)
	s_waitcnt lgkmcnt(0)
	s_barrier
; #define PG8_STAGE(bufoff, gbase, voff) do { _Pragma("unroll") for (int _i = 0; _i < 2; ++_i) \
;         __builtin_amdgcn_global_load_lds((const unsigned*)((const char*)(gbase) + (voff)[_i]), (PG8_LAS unsigned*)(lds + (bufoff) + ldsw + _i * 8192), 16, 0, 0); } while (0)
; #define PG8_LDA(dst, b, h) do { _Pragma("unroll") for (int m = 0; m < 4; ++m) _Pragma("unroll") for (int k = 0; k < 2; ++k) dst[m][k] = *(const PG8_LAS bf16x8*)(lds + PG8_SA(b, h) + aoff + m * 2048 + k * 1024); } while (0)
; #define PG8_LDB(dst, b, h) do { _Pragma("unroll") for (int n = 0; n < 2; ++n) _Pragma("unroll") for (int k = 0; k < 2; ++k) dst[n][k] = *(const PG8_LAS bf16x8*)(lds + PG8_SB(b, h) + boff + n * 2048 + k * 1024); } while (0)
; #define PG8_MMA(ai, bj, At, Bt) do { __builtin_amdgcn_s_setprio(1); _Pragma("unroll") for (int m = 0; m < 4; ++m) _Pragma("unroll") for (int n = 0; n < 2; ++n) _Pragma("unroll") for (int k = 0; k < 2; ++k) \
;         acc[ai][bj][m][n] = __builtin_amdgcn_mfma_f32_16x16x32_bf16(Bt[n][k], At[m][k], acc[ai][bj][m][n], 0, 0, 0); __builtin_amdgcn_s_setprio(0); } while (0)
; #define PG8_WAIT_V(n) asm volatile("s_waitcnt vmcnt(" #n ")" ::: "memory")
; #define PG8_WAIT_L(n) asm volatile("s_waitcnt lgkmcnt(" #n ")" ::: "memory")
; #define PG8_BAR __builtin_amdgcn_s_barrier()
; #define PG8_SCHED __builtin_amdgcn_sched_barrier(0)
; template <class Epi, class Sched, bool ALIGN_EPI = false, bool SP2 = false>
; __device__ __forceinline__ void gemm_phase(PG8_LAS unsigned char* lds, const Gemm g, const Sched& S, const Epi& E) {
;     ...
;             PG8_LDB(B0, 0, 0); PG8_LDB(B1, 0, 1); PG8_SCHED; PG8_LDA(At, 0, 0); PG8_STAGE(PG8_SA(1, 1), a1 + hstep, voffA);
;             PG8_WAIT_V(8); PG8_WAIT_L(0); PG8_BAR; PG8_MMA(0, 0, At, B0); PG8_MMA(0, 1, At, B1); PG8_BAR; PG8_SCHED;
;             PG8_LDA(At, 0, 1); PG8_STAGE(PG8_SB(0, 0), b2, voffB); PG8_STAGE(PG8_SB(0, 1), b2 + hstep, voffB); PG8_STAGE(PG8_SA(0, 0), a2, voffA);
;             PG8_WAIT_V(8); PG8_WAIT_L(0); PG8_BAR; PG8_MMA(1, 0, At, B0); PG8_MMA(1, 1, At, B1); PG8_BAR; PG8_SCHED;
	s_setprio 1
	s_waitcnt lgkmcnt(0)
	v_mfma_f32_16x16x32_bf16 v[126:129], v[144:147], v[182:185], v[126:129]
	v_mfma_f32_16x16x32_bf16 v[122:125], v[152:155], v[182:185], v[122:125]
	v_mfma_f32_16x16x32_bf16 v[110:113], v[144:147], v[190:193], v[110:113]
	v_mfma_f32_16x16x32_bf16 v[106:109], v[152:155], v[190:193], v[106:109]
	v_mfma_f32_16x16x32_bf16 v[94:97], v[144:147], v[198:201], v[94:97]
	v_mfma_f32_16x16x32_bf16 v[90:93], v[152:155], v[198:201], v[90:93]
	v_mfma_f32_16x16x32_bf16 v[78:81], v[144:147], v[224:227], v[78:81]
	v_mfma_f32_16x16x32_bf16 v[74:77], v[152:155], v[224:227], v[74:77]
	v_mfma_f32_16x16x32_bf16 v[126:129], v[148:151], v[186:189], v[126:129]
	v_mfma_f32_16x16x32_bf16 v[122:125], v[156:159], v[186:189], v[122:125]
	v_mfma_f32_16x16x32_bf16 v[110:113], v[148:151], v[194:197], v[110:113]
	v_mfma_f32_16x16x32_bf16 v[106:109], v[156:159], v[194:197], v[106:109]
	v_mfma_f32_16x16x32_bf16 v[94:97], v[148:151], v[202:205], v[94:97]
	v_mfma_f32_16x16x32_bf16 v[90:93], v[156:159], v[202:205], v[90:93]
	v_mfma_f32_16x16x32_bf16 v[78:81], v[148:151], v[228:231], v[78:81]
	v_mfma_f32_16x16x32_bf16 v[74:77], v[156:159], v[228:231], v[74:77]
	v_mfma_f32_16x16x32_bf16 v[118:121], v[166:169], v[182:185], v[118:121]
	v_mfma_f32_16x16x32_bf16 v[114:117], v[174:177], v[182:185], v[114:117]
	v_mfma_f32_16x16x32_bf16 v[102:105], v[166:169], v[190:193], v[102:105]
	v_mfma_f32_16x16x32_bf16 v[98:101], v[174:177], v[190:193], v[98:101]
	v_mfma_f32_16x16x32_bf16 v[86:89], v[166:169], v[198:201], v[86:89]
	v_mfma_f32_16x16x32_bf16 v[82:85], v[174:177], v[198:201], v[82:85]
	v_mfma_f32_16x16x32_bf16 v[70:73], v[166:169], v[224:227], v[70:73]
	v_mfma_f32_16x16x32_bf16 v[66:69], v[174:177], v[224:227], v[66:69]
	v_mfma_f32_16x16x32_bf16 v[118:121], v[170:173], v[186:189], v[118:121]
	v_mfma_f32_16x16x32_bf16 v[114:117], v[178:181], v[186:189], v[114:117]
	v_mfma_f32_16x16x32_bf16 v[102:105], v[170:173], v[194:197], v[102:105]
	v_mfma_f32_16x16x32_bf16 v[98:101], v[178:181], v[194:197], v[98:101]
	v_mfma_f32_16x16x32_bf16 v[86:89], v[170:173], v[202:205], v[86:89]
	v_mfma_f32_16x16x32_bf16 v[82:85], v[178:181], v[202:205], v[82:85]
	v_mfma_f32_16x16x32_bf16 v[70:73], v[170:173], v[228:231], v[70:73]
	v_mfma_f32_16x16x32_bf16 v[66:69], v[178:181], v[228:231], v[66:69]
	s_setprio 0
	s_barrier
	s_add_i32 s48, s48, s26
	v_lshl_add_u64 v[138:139], s[20:21], 0, v[0:1]
	s_mov_b32 m0, s48
	ds_read_b128 v[182:185], v164 offset:16384
	ds_read_b128 v[186:189], v164 offset:17408
	ds_read_b128 v[190:193], v164 offset:18432
	ds_read_b128 v[194:197], v164 offset:19456
	ds_read_b128 v[198:201], v164 offset:20480
	ds_read_b128 v[202:205], v164 offset:21504
	ds_read_b128 v[224:227], v164 offset:22528
	ds_read_b128 v[228:231], v164 offset:23552
	global_load_lds_dwordx4 v[138:139], off
	s_add_i32 m0, s48, 0x2000
	s_add_u32 s48, s20, 0x40000
	v_lshl_add_u64 v[140:141], s[20:21], 0, v[134:135]
	s_addc_u32 s49, s21, 0
	s_add_i32 s50, s50, s26
	global_load_lds_dwordx4 v[140:141], off
	v_lshl_add_u64 v[232:233], s[48:49], 0, v[0:1]
	s_mov_b32 m0, s50
	v_lshl_add_u64 v[234:235], s[22:23], 0, v[132:133]
	global_load_lds_dwordx4 v[232:233], off
	v_lshl_add_u64 v[232:233], s[48:49], 0, v[134:135]
	s_add_i32 m0, s50, 0x2000
	s_nop 0
	global_load_lds_dwordx4 v[232:233], off
	v_lshl_add_u64 v[232:233], s[22:23], 0, v[130:131]
	s_mov_b32 m0, s30
	s_nop 0
	global_load_lds_dwordx4 v[232:233], off
	s_mov_b32 m0, s31
	s_nop 0
	global_load_lds_dwordx4 v[234:235], off
	s_waitcnt vmcnt(8)
	s_waitcnt lgkmcnt(0)
	s_barrier
	s_setprio 1
	s_waitcnt lgkmcnt(0)
	v_mfma_f32_16x16x32_bf16 v[62:65], v[144:147], v[182:185], v[62:65]
	v_mfma_f32_16x16x32_bf16 v[58:61], v[152:155], v[182:185], v[58:61]
	v_mfma_f32_16x16x32_bf16 v[46:49], v[144:147], v[190:193], v[46:49]
	v_mfma_f32_16x16x32_bf16 v[42:45], v[152:155], v[190:193], v[42:45]
	v_mfma_f32_16x16x32_bf16 v[30:33], v[144:147], v[198:201], v[30:33]
	v_mfma_f32_16x16x32_bf16 v[26:29], v[152:155], v[198:201], v[26:29]
	v_mfma_f32_16x16x32_bf16 v[14:17], v[144:147], v[224:227], v[14:17]
	v_mfma_f32_16x16x32_bf16 v[10:13], v[152:155], v[224:227], v[10:13]
	v_mfma_f32_16x16x32_bf16 v[62:65], v[148:151], v[186:189], v[62:65]
	v_mfma_f32_16x16x32_bf16 v[58:61], v[156:159], v[186:189], v[58:61]
	v_mfma_f32_16x16x32_bf16 v[46:49], v[148:151], v[194:197], v[46:49]
	v_mfma_f32_16x16x32_bf16 v[42:45], v[156:159], v[194:197], v[42:45]
	v_mfma_f32_16x16x32_bf16 v[30:33], v[148:151], v[202:205], v[30:33]
	v_mfma_f32_16x16x32_bf16 v[26:29], v[156:159], v[202:205], v[26:29]
	v_mfma_f32_16x16x32_bf16 v[14:17], v[148:151], v[228:231], v[14:17]
	v_mfma_f32_16x16x32_bf16 v[10:13], v[156:159], v[228:231], v[10:13]
	v_mfma_f32_16x16x32_bf16 v[54:57], v[166:169], v[182:185], v[54:57]
	v_mfma_f32_16x16x32_bf16 v[50:53], v[174:177], v[182:185], v[50:53]
	v_mfma_f32_16x16x32_bf16 v[38:41], v[166:169], v[190:193], v[38:41]
	v_mfma_f32_16x16x32_bf16 v[34:37], v[174:177], v[190:193], v[34:37]
	v_mfma_f32_16x16x32_bf16 v[22:25], v[166:169], v[198:201], v[22:25]
	v_mfma_f32_16x16x32_bf16 v[18:21], v[174:177], v[198:201], v[18:21]
	v_mfma_f32_16x16x32_bf16 v[6:9], v[166:169], v[224:227], v[6:9]
	v_mfma_f32_16x16x32_bf16 v[2:5], v[174:177], v[224:227], v[2:5]
	v_mfma_f32_16x16x32_bf16 v[54:57], v[170:173], v[186:189], v[54:57]
	v_mfma_f32_16x16x32_bf16 v[50:53], v[178:181], v[186:189], v[50:53]
	v_mfma_f32_16x16x32_bf16 v[38:41], v[170:173], v[194:197], v[38:41]
	v_mfma_f32_16x16x32_bf16 v[34:37], v[178:181], v[194:197], v[34:37]
	v_mfma_f32_16x16x32_bf16 v[22:25], v[170:173], v[202:205], v[22:25]
	v_mfma_f32_16x16x32_bf16 v[18:21], v[178:181], v[202:205], v[18:21]
	v_mfma_f32_16x16x32_bf16 v[6:9], v[170:173], v[228:231], v[6:9]
	v_mfma_f32_16x16x32_bf16 v[2:5], v[178:181], v[228:231], v[2:5]
	s_setprio 0
	s_barrier
; #define PG8_STAGE(bufoff, gbase, voff) do { _Pragma("unroll") for (int _i = 0; _i < 2; ++_i) \
;         __builtin_amdgcn_global_load_lds((const unsigned*)((const char*)(gbase) + (voff)[_i]), (PG8_LAS unsigned*)(lds + (bufoff) + ldsw + _i * 8192), 16, 0, 0); } while (0)
; #define PG8_LDA(dst, b, h) do { _Pragma("unroll") for (int m = 0; m < 4; ++m) _Pragma("unroll") for (int k = 0; k < 2; ++k) dst[m][k] = *(const PG8_LAS bf16x8*)(lds + PG8_SA(b, h) + aoff + m * 2048 + k * 1024); } while (0)
; #define PG8_LDB(dst, b, h) do { _Pragma("unroll") for (int n = 0; n < 2; ++n) _Pragma("unroll") for (int k = 0; k < 2; ++k) dst[n][k] = *(const PG8_LAS bf16x8*)(lds + PG8_SB(b, h) + boff + n * 2048 + k * 1024); } while (0)
; #define PG8_MMA(ai, bj, At, Bt) do { __builtin_amdgcn_s_setprio(1); _Pragma("unroll") for (int m = 0; m < 4; ++m) _Pragma("unroll") for (int n = 0; n < 2; ++n) _Pragma("unroll") for (int k = 0; k < 2; ++k) \
;         acc[ai][bj][m][n] = __builtin_amdgcn_mfma_f32_16x16x32_bf16(Bt[n][k], At[m][k], acc[ai][bj][m][n], 0, 0, 0); __builtin_amdgcn_s_setprio(0); } while (0)
; #define PG8_WAIT_V(n) asm volatile("s_waitcnt vmcnt(" #n ")" ::: "memory")
; #define PG8_WAIT_L(n) asm volatile("s_waitcnt lgkmcnt(" #n ")" ::: "memory")
; #define PG8_BAR __builtin_amdgcn_s_barrier()
; #define PG8_SCHED __builtin_amdgcn_sched_barrier(0)
; template <class Epi, class Sched, bool ALIGN_EPI = false, bool SP2 = false>
; __device__ __forceinline__ void gemm_phase(PG8_LAS unsigned char* lds, const Gemm g, const Sched& S, const Epi& E) {
;     ...
;             PG8_LDB(B0, 1, 0); PG8_LDB(B1, 1, 1); PG8_SCHED; PG8_LDA(At, 1, 0); PG8_STAGE(PG8_SA(0, 1), a2 + hstep, voffA);
;             PG8_WAIT_V(8); PG8_WAIT_L(0); PG8_BAR; PG8_MMA(0, 0, At, B0); PG8_MMA(0, 1, At, B1); PG8_BAR; PG8_SCHED;
	s_add_i32 s48, 0, 0x18000
	s_add_i32 s49, 0, 0x1c000
	v_add_u32_e32 v156, s48, v161
	v_add_u32_e32 v165, s49, v161
	ds_read_b128 v[144:147], v156
	ds_read_b128 v[148:151], v156 offset:1024
	ds_read_b128 v[152:155], v156 offset:2048
	ds_read_b128 v[156:159], v156 offset:3072
	ds_read_b128 v[166:169], v165
	ds_read_b128 v[170:173], v165 offset:1024
	ds_read_b128 v[174:177], v165 offset:2048
	ds_read_b128 v[178:181], v165 offset:3072
	s_add_u32 s22, s22, 0x40000
	s_addc_u32 s23, s23, 0
	s_mov_b32 m0, s38
	v_lshl_add_u64 v[236:237], s[22:23], 0, v[130:131]
	ds_read_b128 v[182:185], v164 offset:32768
	ds_read_b128 v[186:189], v164 offset:33792
	ds_read_b128 v[190:193], v164 offset:34816
	ds_read_b128 v[194:197], v164 offset:35840
	ds_read_b128 v[198:201], v164 offset:36864
	ds_read_b128 v[202:205], v164 offset:37888
	ds_read_b128 v[224:227], v164 offset:38912
	ds_read_b128 v[228:231], v164 offset:39936
	global_load_lds_dwordx4 v[236:237], off
	v_lshl_add_u64 v[236:237], s[22:23], 0, v[132:133]
	s_mov_b32 m0, s39
	s_nop 0
	global_load_lds_dwordx4 v[236:237], off
	s_waitcnt vmcnt(8)
	s_waitcnt lgkmcnt(0)
	s_barrier
	s_setprio 1
	s_waitcnt lgkmcnt(0)
	v_mfma_f32_16x16x32_bf16 v[126:129], v[144:147], v[182:185], v[126:129]
	v_mfma_f32_16x16x32_bf16 v[122:125], v[152:155], v[182:185], v[122:125]
	v_mfma_f32_16x16x32_bf16 v[110:113], v[144:147], v[190:193], v[110:113]
	v_mfma_f32_16x16x32_bf16 v[106:109], v[152:155], v[190:193], v[106:109]
	v_mfma_f32_16x16x32_bf16 v[94:97], v[144:147], v[198:201], v[94:97]
	v_mfma_f32_16x16x32_bf16 v[90:93], v[152:155], v[198:201], v[90:93]
	v_mfma_f32_16x16x32_bf16 v[78:81], v[144:147], v[224:227], v[78:81]
	v_mfma_f32_16x16x32_bf16 v[74:77], v[152:155], v[224:227], v[74:77]
	v_mfma_f32_16x16x32_bf16 v[126:129], v[148:151], v[186:189], v[126:129]
	v_mfma_f32_16x16x32_bf16 v[122:125], v[156:159], v[186:189], v[122:125]
	v_mfma_f32_16x16x32_bf16 v[110:113], v[148:151], v[194:197], v[110:113]
	v_mfma_f32_16x16x32_bf16 v[106:109], v[156:159], v[194:197], v[106:109]
	v_mfma_f32_16x16x32_bf16 v[94:97], v[148:151], v[202:205], v[94:97]
	v_mfma_f32_16x16x32_bf16 v[90:93], v[156:159], v[202:205], v[90:93]
	v_mfma_f32_16x16x32_bf16 v[78:81], v[148:151], v[228:231], v[78:81]
	v_mfma_f32_16x16x32_bf16 v[74:77], v[156:159], v[228:231], v[74:77]
	v_mfma_f32_16x16x32_bf16 v[118:121], v[166:169], v[182:185], v[118:121]
	v_mfma_f32_16x16x32_bf16 v[114:117], v[174:177], v[182:185], v[114:117]
	v_mfma_f32_16x16x32_bf16 v[102:105], v[166:169], v[190:193], v[102:105]
	v_mfma_f32_16x16x32_bf16 v[98:101], v[174:177], v[190:193], v[98:101]
	v_mfma_f32_16x16x32_bf16 v[86:89], v[166:169], v[198:201], v[86:89]
	v_mfma_f32_16x16x32_bf16 v[82:85], v[174:177], v[198:201], v[82:85]
	v_mfma_f32_16x16x32_bf16 v[70:73], v[166:169], v[224:227], v[70:73]
	v_mfma_f32_16x16x32_bf16 v[66:69], v[174:177], v[224:227], v[66:69]
	v_mfma_f32_16x16x32_bf16 v[118:121], v[170:173], v[186:189], v[118:121]
	v_mfma_f32_16x16x32_bf16 v[114:117], v[178:181], v[186:189], v[114:117]
	v_mfma_f32_16x16x32_bf16 v[102:105], v[170:173], v[194:197], v[102:105]
	v_mfma_f32_16x16x32_bf16 v[98:101], v[178:181], v[194:197], v[98:101]
	v_mfma_f32_16x16x32_bf16 v[86:89], v[170:173], v[202:205], v[86:89]
	v_mfma_f32_16x16x32_bf16 v[82:85], v[178:181], v[202:205], v[82:85]
	v_mfma_f32_16x16x32_bf16 v[70:73], v[170:173], v[228:231], v[70:73]
	v_mfma_f32_16x16x32_bf16 v[66:69], v[178:181], v[228:231], v[66:69]
	s_setprio 0
	s_barrier
; #define PG8_STAGE(bufoff, gbase, voff) do { _Pragma("unroll") for (int _i = 0; _i < 2; ++_i) \
;         __builtin_amdgcn_global_load_lds((const unsigned*)((const char*)(gbase) + (voff)[_i]), (PG8_LAS unsigned*)(lds + (bufoff) + ldsw + _i * 8192), 16, 0, 0); } while (0)
; #define PG8_LDA(dst, b, h) do { _Pragma("unroll") for (int m = 0; m < 4; ++m) _Pragma("unroll") for (int k = 0; k < 2; ++k) dst[m][k] = *(const PG8_LAS bf16x8*)(lds + PG8_SA(b, h) + aoff + m * 2048 + k * 1024); } while (0)
; #define PG8_MMA(ai, bj, At, Bt) do { __builtin_amdgcn_s_setprio(1); _Pragma("unroll") for (int m = 0; m < 4; ++m) _Pragma("unroll") for (int n = 0; n < 2; ++n) _Pragma("unroll") for (int k = 0; k < 2; ++k) \
;         acc[ai][bj][m][n] = __builtin_amdgcn_mfma_f32_16x16x32_bf16(Bt[n][k], At[m][k], acc[ai][bj][m][n], 0, 0, 0); __builtin_amdgcn_s_setprio(0); } while (0)
; #define PG8_WAIT_V(n) asm volatile("s_waitcnt vmcnt(" #n ")" ::: "memory")
; #define PG8_WAIT_L(n) asm volatile("s_waitcnt lgkmcnt(" #n ")" ::: "memory")
; #define PG8_BAR __builtin_amdgcn_s_barrier()
; #define PG8_SCHED __builtin_amdgcn_sched_barrier(0)
; template <class Epi, class Sched, bool ALIGN_EPI = false, bool SP2 = false>
; __device__ __forceinline__ void gemm_phase(PG8_LAS unsigned char* lds, const Gemm g, const Sched& S, const Epi& E) {
;     ...
;             PG8_LDA(At, 1, 1); PG8_STAGE(PG8_SB(1, 0), b3, voffB); PG8_STAGE(PG8_SB(1, 1), b3 + hstep, voffB); PG8_STAGE(PG8_SA(1, 0), a3, voffA);
;             PG8_WAIT_V(8); PG8_WAIT_L(0); PG8_BAR; PG8_MMA(1, 0, At, B0); PG8_MMA(1, 1, At, B1); PG8_BAR; PG8_SCHED;
	s_add_i32 s22, s48, s26
	v_lshl_add_u64 v[138:139], v[138:139], 0, s[86:87]
	s_mov_b32 m0, s22
	ds_read_b128 v[182:185], v164 offset:49152
	ds_read_b128 v[186:189], v164 offset:50176
	ds_read_b128 v[190:193], v164 offset:51200
	ds_read_b128 v[194:197], v164 offset:52224
	ds_read_b128 v[198:201], v164 offset:53248
	ds_read_b128 v[202:205], v164 offset:54272
	ds_read_b128 v[224:227], v164 offset:55296
	ds_read_b128 v[228:231], v164 offset:56320
	global_load_lds_dwordx4 v[138:139], off
	s_add_i32 m0, s22, 0x2000
	s_add_u32 s20, s20, 0x40080
	v_lshl_add_u64 v[138:139], v[140:141], 0, s[86:87]
	s_addc_u32 s21, s21, 0
	s_add_i32 s22, s49, s26
	global_load_lds_dwordx4 v[138:139], off
	v_lshl_add_u64 v[138:139], s[20:21], 0, v[0:1]
	s_mov_b32 m0, s22
	s_nop 0
	global_load_lds_dwordx4 v[138:139], off
	v_lshl_add_u64 v[138:139], s[20:21], 0, v[134:135]
	s_add_i32 m0, s22, 0x2000
	s_nop 0
	global_load_lds_dwordx4 v[138:139], off
	v_lshl_add_u64 v[138:139], v[232:233], 0, s[86:87]
	s_mov_b32 m0, s41
	s_nop 0
	global_load_lds_dwordx4 v[138:139], off
	v_lshl_add_u64 v[138:139], v[234:235], 0, s[86:87]
	s_mov_b32 m0, s42
	s_nop 0
	global_load_lds_dwordx4 v[138:139], off
	s_waitcnt vmcnt(8)
	s_waitcnt lgkmcnt(0)
	s_barrier
	s_setprio 1
	s_waitcnt lgkmcnt(0)
	v_mfma_f32_16x16x32_bf16 v[62:65], v[144:147], v[182:185], v[62:65]
	v_mfma_f32_16x16x32_bf16 v[58:61], v[152:155], v[182:185], v[58:61]
	v_mfma_f32_16x16x32_bf16 v[46:49], v[144:147], v[190:193], v[46:49]
	v_mfma_f32_16x16x32_bf16 v[42:45], v[152:155], v[190:193], v[42:45]
	v_mfma_f32_16x16x32_bf16 v[30:33], v[144:147], v[198:201], v[30:33]
	v_mfma_f32_16x16x32_bf16 v[26:29], v[152:155], v[198:201], v[26:29]
	v_mfma_f32_16x16x32_bf16 v[14:17], v[144:147], v[224:227], v[14:17]
	v_mfma_f32_16x16x32_bf16 v[10:13], v[152:155], v[224:227], v[10:13]
	v_mfma_f32_16x16x32_bf16 v[62:65], v[148:151], v[186:189], v[62:65]
	v_mfma_f32_16x16x32_bf16 v[58:61], v[156:159], v[186:189], v[58:61]
	v_mfma_f32_16x16x32_bf16 v[46:49], v[148:151], v[194:197], v[46:49]
	v_mfma_f32_16x16x32_bf16 v[42:45], v[156:159], v[194:197], v[42:45]
	v_mfma_f32_16x16x32_bf16 v[30:33], v[148:151], v[202:205], v[30:33]
	v_mfma_f32_16x16x32_bf16 v[26:29], v[156:159], v[202:205], v[26:29]
	v_mfma_f32_16x16x32_bf16 v[14:17], v[148:151], v[228:231], v[14:17]
	v_mfma_f32_16x16x32_bf16 v[10:13], v[156:159], v[228:231], v[10:13]
	v_mfma_f32_16x16x32_bf16 v[54:57], v[166:169], v[182:185], v[54:57]
	v_mfma_f32_16x16x32_bf16 v[50:53], v[174:177], v[182:185], v[50:53]
	v_mfma_f32_16x16x32_bf16 v[38:41], v[166:169], v[190:193], v[38:41]
	v_mfma_f32_16x16x32_bf16 v[34:37], v[174:177], v[190:193], v[34:37]
	v_mfma_f32_16x16x32_bf16 v[22:25], v[166:169], v[198:201], v[22:25]
	v_mfma_f32_16x16x32_bf16 v[18:21], v[174:177], v[198:201], v[18:21]
	v_mfma_f32_16x16x32_bf16 v[6:9], v[166:169], v[224:227], v[6:9]
	v_mfma_f32_16x16x32_bf16 v[2:5], v[174:177], v[224:227], v[2:5]
	v_mfma_f32_16x16x32_bf16 v[54:57], v[170:173], v[186:189], v[54:57]
	v_mfma_f32_16x16x32_bf16 v[50:53], v[178:181], v[186:189], v[50:53]
	v_mfma_f32_16x16x32_bf16 v[38:41], v[170:173], v[194:197], v[38:41]
	v_mfma_f32_16x16x32_bf16 v[34:37], v[178:181], v[194:197], v[34:37]
	v_mfma_f32_16x16x32_bf16 v[22:25], v[170:173], v[202:205], v[22:25]
	v_mfma_f32_16x16x32_bf16 v[18:21], v[178:181], v[202:205], v[18:21]
	v_mfma_f32_16x16x32_bf16 v[6:9], v[170:173], v[228:231], v[6:9]
	v_mfma_f32_16x16x32_bf16 v[2:5], v[178:181], v[228:231], v[2:5]
	s_setprio 0
	s_barrier
	s_add_i32 s47, s47, 2
	s_add_u32 s8, s8, 0x100
	s_addc_u32 s9, s9, 0
	s_add_u32 s45, s45, 0x100
	s_addc_u32 s46, s46, 0
	s_cmp_gt_u32 s47, 13
	s_cbranch_scc0 .LBB0_492

; #define PG8_STAGE(bufoff, gbase, voff) do { _Pragma("unroll") for (int _i = 0; _i < 2; ++_i) \
;         __builtin_amdgcn_global_load_lds((const unsigned*)((const char*)(gbase) + (voff)[_i]), (PG8_LAS unsigned*)(lds + (bufoff) + ldsw + _i * 8192), 16, 0, 0); } while (0)
; #define PG8_LDA(dst, b, h) do { _Pragma("unroll") for (int m = 0; m < 4; ++m) _Pragma("unroll") for (int k = 0; k < 2; ++k) dst[m][k] = *(const PG8_LAS bf16x8*)(lds + PG8_SA(b, h) + aoff + m * 2048 + k * 1024); } while (0)
; #define PG8_LDB(dst, b, h) do { _Pragma("unroll") for (int n = 0; n < 2; ++n) _Pragma("unroll") for (int k = 0; k < 2; ++k) dst[n][k] = *(const PG8_LAS bf16x8*)(lds + PG8_SB(b, h) + boff + n * 2048 + k * 1024); } while (0)
; #define PG8_MMA(ai, bj, At, Bt) do { __builtin_amdgcn_s_setprio(1); _Pragma("unroll") for (int m = 0; m < 4; ++m) _Pragma("unroll") for (int n = 0; n < 2; ++n) _Pragma("unroll") for (int k = 0; k < 2; ++k) \
;         acc[ai][bj][m][n] = __builtin_amdgcn_mfma_f32_16x16x32_bf16(Bt[n][k], At[m][k], acc[ai][bj][m][n], 0, 0, 0); __builtin_amdgcn_s_setprio(0); } while (0)
; #define PG8_WAIT_V(n) asm volatile("s_waitcnt vmcnt(" #n ")" ::: "memory")
; #define PG8_WAIT_L(n) asm volatile("s_waitcnt lgkmcnt(" #n ")" ::: "memory")
; #define PG8_BAR __builtin_amdgcn_s_barrier()
; #define PG8_SCHED __builtin_amdgcn_sched_barrier(0)
; template <class Epi, class Sched, bool ALIGN_EPI = false, bool SP2 = false>
; __device__ __forceinline__ void gemm_phase(PG8_LAS unsigned char* lds, const Gemm g, const Sched& S, const Epi& E) {
;     ...
;             PG8_LDB(B0, 0, 0); PG8_LDB(B1, 0, 1); PG8_SCHED; PG8_LDA(At, 0, 0); PG8_STAGE(PG8_SA(1, 1), a1 + hstep, voffA);
;             PG8_WAIT_V(8); PG8_WAIT_L(0); PG8_BAR; PG8_MMA(0, 0, At, B0); PG8_MMA(0, 1, At, B1); PG8_BAR; PG8_SCHED;
;             PG8_LDA(At, 0, 1); PG8_STAGE(PG8_SB(0, 0), b2, voffB); PG8_STAGE(PG8_SB(0, 1), b2 + hstep, voffB); PG8_STAGE(PG8_SA(0, 0), a2, voffA);
.LBB0_891:
	s_add_u32 s18, s16, 0xfffe0080
	s_addc_u32 s19, s17, -1
	s_add_i32 s46, 0, 0x10000
	s_cmp_eq_u32 s45, 4
	s_cselect_b32 s21, s9, s19
	s_cselect_b32 s20, s41, s18
	v_add_u32_e32 v148, s46, v151
	s_cselect_b32 s19, s7, s44
	s_cselect_b32 s18, s42, s43
	s_add_i32 s48, 0, 0x14000
	ds_read_b128 v[138:141], v148
	ds_read_b128 v[144:147], v148 offset:1024
	ds_read_b128 v[154:157], v148 offset:2048
	ds_read_b128 v[158:161], v148 offset:3072
	v_add_u32_e32 v148, s48, v151
	ds_read_b128 v[162:165], v148
	ds_read_b128 v[166:169], v148 offset:1024
	ds_read_b128 v[170:173], v148 offset:2048
	ds_read_b128 v[174:177], v148 offset:3072
	v_lshl_add_u64 v[148:149], s[16:17], 0, v[136:137]
	s_add_i32 m0, s27, 0xc000
	ds_read_b128 v[178:181], v153
	ds_read_b128 v[182:185], v153 offset:1024
	ds_read_b128 v[186:189], v153 offset:2048
	ds_read_b128 v[190:193], v153 offset:3072
	ds_read_b128 v[194:197], v153 offset:4096
	ds_read_b128 v[198:201], v153 offset:5120
	ds_read_b128 v[202:205], v153 offset:6144
	ds_read_b128 v[224:227], v153 offset:7168
	global_load_lds_dwordx4 v[148:149], off
	v_lshl_add_u64 v[148:149], s[16:17], 0, v[142:143]
	s_add_i32 m0, s27, 0xe000
	s_nop 0
	global_load_lds_dwordx4 v[148:149], off
	s_waitcnt vmcnt(8)
	s_waitcnt lgkmcnt(0)
	s_barrier
	s_setprio 1
	s_waitcnt lgkmcnt(0)
	v_mfma_f32_16x16x32_bf16 v[126:129], v[138:141], v[178:181], v[126:129]
	v_mfma_f32_16x16x32_bf16 v[122:125], v[154:157], v[178:181], v[122:125]
	v_mfma_f32_16x16x32_bf16 v[110:113], v[138:141], v[186:189], v[110:113]
	v_mfma_f32_16x16x32_bf16 v[106:109], v[154:157], v[186:189], v[106:109]
	v_mfma_f32_16x16x32_bf16 v[94:97], v[138:141], v[194:197], v[94:97]
	v_mfma_f32_16x16x32_bf16 v[90:93], v[154:157], v[194:197], v[90:93]
	v_mfma_f32_16x16x32_bf16 v[78:81], v[138:141], v[202:205], v[78:81]
	v_mfma_f32_16x16x32_bf16 v[74:77], v[154:157], v[202:205], v[74:77]
	v_mfma_f32_16x16x32_bf16 v[126:129], v[144:147], v[182:185], v[126:129]
	v_mfma_f32_16x16x32_bf16 v[122:125], v[158:161], v[182:185], v[122:125]
	v_mfma_f32_16x16x32_bf16 v[110:113], v[144:147], v[190:193], v[110:113]
	v_mfma_f32_16x16x32_bf16 v[106:109], v[158:161], v[190:193], v[106:109]
	v_mfma_f32_16x16x32_bf16 v[94:97], v[144:147], v[198:201], v[94:97]
	v_mfma_f32_16x16x32_bf16 v[90:93], v[158:161], v[198:201], v[90:93]
	v_mfma_f32_16x16x32_bf16 v[78:81], v[144:147], v[224:227], v[78:81]
	v_mfma_f32_16x16x32_bf16 v[74:77], v[158:161], v[224:227], v[74:77]
	v_mfma_f32_16x16x32_bf16 v[118:121], v[162:165], v[178:181], v[118:121]
	v_mfma_f32_16x16x32_bf16 v[114:117], v[170:173], v[178:181], v[114:117]
	v_mfma_f32_16x16x32_bf16 v[102:105], v[162:165], v[186:189], v[102:105]
	v_mfma_f32_16x16x32_bf16 v[98:101], v[170:173], v[186:189], v[98:101]
	v_mfma_f32_16x16x32_bf16 v[86:89], v[162:165], v[194:197], v[86:89]
	v_mfma_f32_16x16x32_bf16 v[82:85], v[170:173], v[194:197], v[82:85]
	v_mfma_f32_16x16x32_bf16 v[70:73], v[162:165], v[202:205], v[70:73]
	v_mfma_f32_16x16x32_bf16 v[66:69], v[170:173], v[202:205], v[66:69]
	v_mfma_f32_16x16x32_bf16 v[118:121], v[166:169], v[182:185], v[118:121]
	v_mfma_f32_16x16x32_bf16 v[114:117], v[174:177], v[182:185], v[114:117]
	v_mfma_f32_16x16x32_bf16 v[102:105], v[166:169], v[190:193], v[102:105]
	v_mfma_f32_16x16x32_bf16 v[98:101], v[174:177], v[190:193], v[98:101]
	v_mfma_f32_16x16x32_bf16 v[86:89], v[166:169], v[198:201], v[86:89]
	v_mfma_f32_16x16x32_bf16 v[82:85], v[174:177], v[198:201], v[82:85]
	v_mfma_f32_16x16x32_bf16 v[70:73], v[166:169], v[224:227], v[70:73]
	v_mfma_f32_16x16x32_bf16 v[66:69], v[174:177], v[224:227], v[66:69]
	s_setprio 0
	s_barrier
	s_add_i32 s46, s46, s26
	v_lshl_add_u64 v[148:149], s[18:19], 0, v[0:1]
	s_mov_b32 m0, s46
	ds_read_b128 v[178:181], v153 offset:16384
	ds_read_b128 v[182:185], v153 offset:17408
	ds_read_b128 v[186:189], v153 offset:18432
	ds_read_b128 v[190:193], v153 offset:19456
	ds_read_b128 v[194:197], v153 offset:20480
	ds_read_b128 v[198:201], v153 offset:21504
	ds_read_b128 v[202:205], v153 offset:22528
	ds_read_b128 v[224:227], v153 offset:23552
	global_load_lds_dwordx4 v[148:149], off
	s_add_i32 m0, s46, 0x2000
	s_add_u32 s46, s18, 0x20000
	v_lshl_add_u64 v[228:229], s[18:19], 0, v[134:135]
	s_addc_u32 s47, s19, 0
	s_add_i32 s48, s48, s26
	global_load_lds_dwordx4 v[228:229], off
	v_lshl_add_u64 v[230:231], s[46:47], 0, v[0:1]
	s_mov_b32 m0, s48
	v_lshl_add_u64 v[232:233], s[20:21], 0, v[132:133]
	global_load_lds_dwordx4 v[230:231], off
	v_lshl_add_u64 v[230:231], s[46:47], 0, v[134:135]
	s_add_i32 m0, s48, 0x2000
	s_nop 0
	global_load_lds_dwordx4 v[230:231], off
	v_lshl_add_u64 v[230:231], s[20:21], 0, v[130:131]
	s_mov_b32 m0, s27
	s_nop 0
	global_load_lds_dwordx4 v[230:231], off
	s_mov_b32 m0, s28
	s_nop 0
	global_load_lds_dwordx4 v[232:233], off
	s_waitcnt vmcnt(8)
	s_waitcnt lgkmcnt(0)
	s_barrier
; #define PG8_STAGE(bufoff, gbase, voff) do { _Pragma("unroll") for (int _i = 0; _i < 2; ++_i) \
;         __builtin_amdgcn_global_load_lds((const unsigned*)((const char*)(gbase) + (voff)[_i]), (PG8_LAS unsigned*)(lds + (bufoff) + ldsw + _i * 8192), 16, 0, 0); } while (0)
; #define PG8_LDA(dst, b, h) do { _Pragma("unroll") for (int m = 0; m < 4; ++m) _Pragma("unroll") for (int k = 0; k < 2; ++k) dst[m][k] = *(const PG8_LAS bf16x8*)(lds + PG8_SA(b, h) + aoff + m * 2048 + k * 1024); } while (0)
; #define PG8_LDB(dst, b, h) do { _Pragma("unroll") for (int n = 0; n < 2; ++n) _Pragma("unroll") for (int k = 0; k < 2; ++k) dst[n][k] = *(const PG8_LAS bf16x8*)(lds + PG8_SB(b, h) + boff + n * 2048 + k * 1024); } while (0)
; #define PG8_MMA(ai, bj, At, Bt) do { __builtin_amdgcn_s_setprio(1); _Pragma("unroll") for (int m = 0; m < 4; ++m) _Pragma("unroll") for (int n = 0; n < 2; ++n) _Pragma("unroll") for (int k = 0; k < 2; ++k) \
;         acc[ai][bj][m][n] = __builtin_amdgcn_mfma_f32_16x16x32_bf16(Bt[n][k], At[m][k], acc[ai][bj][m][n], 0, 0, 0); __builtin_amdgcn_s_setprio(0); } while (0)
; #define PG8_WAIT_V(n) asm volatile("s_waitcnt vmcnt(" #n ")" ::: "memory")
; #define PG8_WAIT_L(n) asm volatile("s_waitcnt lgkmcnt(" #n ")" ::: "memory")
; #define PG8_BAR __builtin_amdgcn_s_barrier()
; #define PG8_SCHED __builtin_amdgcn_sched_barrier(0)
; template <class Epi, class Sched, bool ALIGN_EPI = false, bool SP2 = false>
; __device__ __forceinline__ void gemm_phase(PG8_LAS unsigned char* lds, const Gemm g, const Sched& S, const Epi& E) {
;     ...
;             PG8_WAIT_V(8); PG8_WAIT_L(0); PG8_BAR; PG8_MMA(1, 0, At, B0); PG8_MMA(1, 1, At, B1); PG8_BAR; PG8_SCHED;
;             PG8_LDB(B0, 1, 0); PG8_LDB(B1, 1, 1); PG8_SCHED; PG8_LDA(At, 1, 0); PG8_STAGE(PG8_SA(0, 1), a2 + hstep, voffA);
;             PG8_WAIT_V(8); PG8_WAIT_L(0); PG8_BAR; PG8_MMA(0, 0, At, B0); PG8_MMA(0, 1, At, B1); PG8_BAR; PG8_SCHED;
	s_setprio 1
	s_waitcnt lgkmcnt(0)
	v_mfma_f32_16x16x32_bf16 v[62:65], v[138:141], v[178:181], v[62:65]
	v_mfma_f32_16x16x32_bf16 v[58:61], v[154:157], v[178:181], v[58:61]
	v_mfma_f32_16x16x32_bf16 v[46:49], v[138:141], v[186:189], v[46:49]
	v_mfma_f32_16x16x32_bf16 v[42:45], v[154:157], v[186:189], v[42:45]
	v_mfma_f32_16x16x32_bf16 v[30:33], v[138:141], v[194:197], v[30:33]
	v_mfma_f32_16x16x32_bf16 v[26:29], v[154:157], v[194:197], v[26:29]
	v_mfma_f32_16x16x32_bf16 v[14:17], v[138:141], v[202:205], v[14:17]
	v_mfma_f32_16x16x32_bf16 v[10:13], v[154:157], v[202:205], v[10:13]
	v_mfma_f32_16x16x32_bf16 v[62:65], v[144:147], v[182:185], v[62:65]
	v_mfma_f32_16x16x32_bf16 v[58:61], v[158:161], v[182:185], v[58:61]
	v_mfma_f32_16x16x32_bf16 v[46:49], v[144:147], v[190:193], v[46:49]
	v_mfma_f32_16x16x32_bf16 v[42:45], v[158:161], v[190:193], v[42:45]
	v_mfma_f32_16x16x32_bf16 v[30:33], v[144:147], v[198:201], v[30:33]
	v_mfma_f32_16x16x32_bf16 v[26:29], v[158:161], v[198:201], v[26:29]
	v_mfma_f32_16x16x32_bf16 v[14:17], v[144:147], v[224:227], v[14:17]
	v_mfma_f32_16x16x32_bf16 v[10:13], v[158:161], v[224:227], v[10:13]
	v_mfma_f32_16x16x32_bf16 v[54:57], v[162:165], v[178:181], v[54:57]
	v_mfma_f32_16x16x32_bf16 v[50:53], v[170:173], v[178:181], v[50:53]
	v_mfma_f32_16x16x32_bf16 v[38:41], v[162:165], v[186:189], v[38:41]
	v_mfma_f32_16x16x32_bf16 v[34:37], v[170:173], v[186:189], v[34:37]
	v_mfma_f32_16x16x32_bf16 v[22:25], v[162:165], v[194:197], v[22:25]
	v_mfma_f32_16x16x32_bf16 v[18:21], v[170:173], v[194:197], v[18:21]
	v_mfma_f32_16x16x32_bf16 v[6:9], v[162:165], v[202:205], v[6:9]
	v_mfma_f32_16x16x32_bf16 v[2:5], v[170:173], v[202:205], v[2:5]
	v_mfma_f32_16x16x32_bf16 v[54:57], v[166:169], v[182:185], v[54:57]
	v_mfma_f32_16x16x32_bf16 v[50:53], v[174:177], v[182:185], v[50:53]
	v_mfma_f32_16x16x32_bf16 v[38:41], v[166:169], v[190:193], v[38:41]
	v_mfma_f32_16x16x32_bf16 v[34:37], v[174:177], v[190:193], v[34:37]
	v_mfma_f32_16x16x32_bf16 v[22:25], v[166:169], v[198:201], v[22:25]
	v_mfma_f32_16x16x32_bf16 v[18:21], v[174:177], v[198:201], v[18:21]
	v_mfma_f32_16x16x32_bf16 v[6:9], v[166:169], v[224:227], v[6:9]
	v_mfma_f32_16x16x32_bf16 v[2:5], v[174:177], v[224:227], v[2:5]
	s_setprio 0
	s_barrier
	s_add_i32 s46, 0, 0x18000
	s_add_i32 s47, 0, 0x1c000
	v_add_u32_e32 v158, s46, v151
	v_add_u32_e32 v174, s47, v151
	ds_read_b128 v[138:141], v158
	ds_read_b128 v[144:147], v158 offset:1024
	ds_read_b128 v[154:157], v158 offset:2048
	ds_read_b128 v[158:161], v158 offset:3072
	ds_read_b128 v[162:165], v174
	ds_read_b128 v[166:169], v174 offset:1024
	ds_read_b128 v[170:173], v174 offset:2048
	ds_read_b128 v[174:177], v174 offset:3072
	s_add_u32 s20, s20, 0x20000
	s_addc_u32 s21, s21, 0
	s_mov_b32 m0, s29
	v_lshl_add_u64 v[234:235], s[20:21], 0, v[130:131]
	ds_read_b128 v[178:181], v153 offset:32768
	ds_read_b128 v[182:185], v153 offset:33792
	ds_read_b128 v[186:189], v153 offset:34816
	ds_read_b128 v[190:193], v153 offset:35840
	ds_read_b128 v[194:197], v153 offset:36864
	ds_read_b128 v[198:201], v153 offset:37888
	ds_read_b128 v[202:205], v153 offset:38912
	ds_read_b128 v[224:227], v153 offset:39936
	global_load_lds_dwordx4 v[234:235], off
	v_lshl_add_u64 v[234:235], s[20:21], 0, v[132:133]
	s_mov_b32 m0, s30
	s_nop 0
	global_load_lds_dwordx4 v[234:235], off
	s_waitcnt vmcnt(8)
	s_waitcnt lgkmcnt(0)
	s_barrier
	s_setprio 1
	s_waitcnt lgkmcnt(0)
	v_mfma_f32_16x16x32_bf16 v[126:129], v[138:141], v[178:181], v[126:129]
	v_mfma_f32_16x16x32_bf16 v[122:125], v[154:157], v[178:181], v[122:125]
	v_mfma_f32_16x16x32_bf16 v[110:113], v[138:141], v[186:189], v[110:113]
	v_mfma_f32_16x16x32_bf16 v[106:109], v[154:157], v[186:189], v[106:109]
	v_mfma_f32_16x16x32_bf16 v[94:97], v[138:141], v[194:197], v[94:97]
	v_mfma_f32_16x16x32_bf16 v[90:93], v[154:157], v[194:197], v[90:93]
	v_mfma_f32_16x16x32_bf16 v[78:81], v[138:141], v[202:205], v[78:81]
	v_mfma_f32_16x16x32_bf16 v[74:77], v[154:157], v[202:205], v[74:77]
	v_mfma_f32_16x16x32_bf16 v[126:129], v[144:147], v[182:185], v[126:129]
	v_mfma_f32_16x16x32_bf16 v[122:125], v[158:161], v[182:185], v[122:125]
	v_mfma_f32_16x16x32_bf16 v[110:113], v[144:147], v[190:193], v[110:113]
	v_mfma_f32_16x16x32_bf16 v[106:109], v[158:161], v[190:193], v[106:109]
	v_mfma_f32_16x16x32_bf16 v[94:97], v[144:147], v[198:201], v[94:97]
	v_mfma_f32_16x16x32_bf16 v[90:93], v[158:161], v[198:201], v[90:93]
	v_mfma_f32_16x16x32_bf16 v[78:81], v[144:147], v[224:227], v[78:81]
	v_mfma_f32_16x16x32_bf16 v[74:77], v[158:161], v[224:227], v[74:77]
	v_mfma_f32_16x16x32_bf16 v[118:121], v[162:165], v[178:181], v[118:121]
	v_mfma_f32_16x16x32_bf16 v[114:117], v[170:173], v[178:181], v[114:117]
	v_mfma_f32_16x16x32_bf16 v[102:105], v[162:165], v[186:189], v[102:105]
	v_mfma_f32_16x16x32_bf16 v[98:101], v[170:173], v[186:189], v[98:101]
	v_mfma_f32_16x16x32_bf16 v[86:89], v[162:165], v[194:197], v[86:89]
	v_mfma_f32_16x16x32_bf16 v[82:85], v[170:173], v[194:197], v[82:85]
	v_mfma_f32_16x16x32_bf16 v[70:73], v[162:165], v[202:205], v[70:73]
	v_mfma_f32_16x16x32_bf16 v[66:69], v[170:173], v[202:205], v[66:69]
	v_mfma_f32_16x16x32_bf16 v[118:121], v[166:169], v[182:185], v[118:121]
	v_mfma_f32_16x16x32_bf16 v[114:117], v[174:177], v[182:185], v[114:117]
	v_mfma_f32_16x16x32_bf16 v[102:105], v[166:169], v[190:193], v[102:105]
	v_mfma_f32_16x16x32_bf16 v[98:101], v[174:177], v[190:193], v[98:101]
	v_mfma_f32_16x16x32_bf16 v[86:89], v[166:169], v[198:201], v[86:89]
	v_mfma_f32_16x16x32_bf16 v[82:85], v[174:177], v[198:201], v[82:85]
	v_mfma_f32_16x16x32_bf16 v[70:73], v[166:169], v[224:227], v[70:73]
	v_mfma_f32_16x16x32_bf16 v[66:69], v[174:177], v[224:227], v[66:69]
	s_setprio 0
	s_barrier
; #define PG8_STAGE(bufoff, gbase, voff) do { _Pragma("unroll") for (int _i = 0; _i < 2; ++_i) \
;         __builtin_amdgcn_global_load_lds((const unsigned*)((const char*)(gbase) + (voff)[_i]), (PG8_LAS unsigned*)(lds + (bufoff) + ldsw + _i * 8192), 16, 0, 0); } while (0)
; #define PG8_LDA(dst, b, h) do { _Pragma("unroll") for (int m = 0; m < 4; ++m) _Pragma("unroll") for (int k = 0; k < 2; ++k) dst[m][k] = *(const PG8_LAS bf16x8*)(lds + PG8_SA(b, h) + aoff + m * 2048 + k * 1024); } while (0)
; #define PG8_MMA(ai, bj, At, Bt) do { __builtin_amdgcn_s_setprio(1); _Pragma("unroll") for (int m = 0; m < 4; ++m) _Pragma("unroll") for (int n = 0; n < 2; ++n) _Pragma("unroll") for (int k = 0; k < 2; ++k) \
;         acc[ai][bj][m][n] = __builtin_amdgcn_mfma_f32_16x16x32_bf16(Bt[n][k], At[m][k], acc[ai][bj][m][n], 0, 0, 0); __builtin_amdgcn_s_setprio(0); } while (0)
; #define PG8_WAIT_V(n) asm volatile("s_waitcnt vmcnt(" #n ")" ::: "memory")
; #define PG8_WAIT_L(n) asm volatile("s_waitcnt lgkmcnt(" #n ")" ::: "memory")
; #define PG8_BAR __builtin_amdgcn_s_barrier()
; #define PG8_SCHED __builtin_amdgcn_sched_barrier(0)
; template <class Epi, class Sched, bool ALIGN_EPI = false, bool SP2 = false>
; __device__ __forceinline__ void gemm_phase(PG8_LAS unsigned char* lds, const Gemm g, const Sched& S, const Epi& E) {
;     ...
;             PG8_LDA(At, 1, 1); PG8_STAGE(PG8_SB(1, 0), b3, voffB); PG8_STAGE(PG8_SB(1, 1), b3 + hstep, voffB); PG8_STAGE(PG8_SA(1, 0), a3, voffA);
;             PG8_WAIT_V(8); PG8_WAIT_L(0); PG8_BAR; PG8_MMA(1, 0, At, B0); PG8_MMA(1, 1, At, B1); PG8_BAR; PG8_SCHED;
;     __device__ __forceinline__ void operator()(const f32x4 (&acc)[2][2][4][2], const Unit& u, int wr, int wc, int fr, int fq) const {
;     ...
;                 const int row = row0 + ai * 128 + m * 16;
; #pragma unroll
;                 for (int bj = 0; bj < 2; ++bj) {
;                     const int c = col0 + bj * 128;
;                     const u32x4 g = *(const u32x4*)(G + (size_t)row * P2W + c);
	s_add_i32 s20, s46, s26
	v_lshl_add_u64 v[148:149], v[148:149], 0, s[86:87]
	s_mov_b32 m0, s20
	ds_read_b128 v[178:181], v153 offset:49152
	ds_read_b128 v[182:185], v153 offset:50176
	ds_read_b128 v[186:189], v153 offset:51200
	ds_read_b128 v[190:193], v153 offset:52224
	ds_read_b128 v[194:197], v153 offset:53248
	ds_read_b128 v[198:201], v153 offset:54272
	ds_read_b128 v[202:205], v153 offset:55296
	ds_read_b128 v[224:227], v153 offset:56320
	global_load_lds_dwordx4 v[148:149], off
	s_add_i32 m0, s20, 0x2000
	s_add_u32 s18, s18, 0x20080
	v_lshl_add_u64 v[148:149], v[228:229], 0, s[86:87]
	s_addc_u32 s19, s19, 0
	s_add_i32 s20, s47, s26
	global_load_lds_dwordx4 v[148:149], off
	v_lshl_add_u64 v[148:149], s[18:19], 0, v[0:1]
	s_mov_b32 m0, s20
	s_nop 0
	global_load_lds_dwordx4 v[148:149], off
	v_lshl_add_u64 v[148:149], s[18:19], 0, v[134:135]
	s_add_i32 m0, s20, 0x2000
	s_nop 0
	global_load_lds_dwordx4 v[148:149], off
	v_lshl_add_u64 v[148:149], v[230:231], 0, s[86:87]
	s_mov_b32 m0, s31
	s_nop 0
	global_load_lds_dwordx4 v[148:149], off
	v_lshl_add_u64 v[148:149], v[232:233], 0, s[86:87]
	s_mov_b32 m0, s38
	s_nop 0
	global_load_lds_dwordx4 v[148:149], off
	s_waitcnt vmcnt(8)
	s_waitcnt lgkmcnt(0)
	s_barrier
	s_setprio 1
	s_waitcnt lgkmcnt(0)
	v_mfma_f32_16x16x32_bf16 v[62:65], v[138:141], v[178:181], v[62:65]
	v_mfma_f32_16x16x32_bf16 v[58:61], v[154:157], v[178:181], v[58:61]
	v_mfma_f32_16x16x32_bf16 v[46:49], v[138:141], v[186:189], v[46:49]
	v_mfma_f32_16x16x32_bf16 v[42:45], v[154:157], v[186:189], v[42:45]
	v_mfma_f32_16x16x32_bf16 v[30:33], v[138:141], v[194:197], v[30:33]
	v_mfma_f32_16x16x32_bf16 v[26:29], v[154:157], v[194:197], v[26:29]
	v_mfma_f32_16x16x32_bf16 v[14:17], v[138:141], v[202:205], v[14:17]
	v_mfma_f32_16x16x32_bf16 v[10:13], v[154:157], v[202:205], v[10:13]
	v_mfma_f32_16x16x32_bf16 v[62:65], v[144:147], v[182:185], v[62:65]
	v_mfma_f32_16x16x32_bf16 v[58:61], v[158:161], v[182:185], v[58:61]
	v_mfma_f32_16x16x32_bf16 v[46:49], v[144:147], v[190:193], v[46:49]
	v_mfma_f32_16x16x32_bf16 v[42:45], v[158:161], v[190:193], v[42:45]
	v_mfma_f32_16x16x32_bf16 v[30:33], v[144:147], v[198:201], v[30:33]
	v_mfma_f32_16x16x32_bf16 v[26:29], v[158:161], v[198:201], v[26:29]
	v_mfma_f32_16x16x32_bf16 v[14:17], v[144:147], v[224:227], v[14:17]
	v_mfma_f32_16x16x32_bf16 v[10:13], v[158:161], v[224:227], v[10:13]
	v_mfma_f32_16x16x32_bf16 v[54:57], v[162:165], v[178:181], v[54:57]
	v_mfma_f32_16x16x32_bf16 v[50:53], v[170:173], v[178:181], v[50:53]
	v_mfma_f32_16x16x32_bf16 v[38:41], v[162:165], v[186:189], v[38:41]
	v_mfma_f32_16x16x32_bf16 v[34:37], v[170:173], v[186:189], v[34:37]
	v_mfma_f32_16x16x32_bf16 v[22:25], v[162:165], v[194:197], v[22:25]
	v_mfma_f32_16x16x32_bf16 v[18:21], v[170:173], v[194:197], v[18:21]
	v_mfma_f32_16x16x32_bf16 v[6:9], v[162:165], v[202:205], v[6:9]
	v_mfma_f32_16x16x32_bf16 v[2:5], v[170:173], v[202:205], v[2:5]
	v_mfma_f32_16x16x32_bf16 v[54:57], v[166:169], v[182:185], v[54:57]
	v_mfma_f32_16x16x32_bf16 v[50:53], v[174:177], v[182:185], v[50:53]
	v_mfma_f32_16x16x32_bf16 v[38:41], v[166:169], v[190:193], v[38:41]
	v_mfma_f32_16x16x32_bf16 v[34:37], v[174:177], v[190:193], v[34:37]
	v_mfma_f32_16x16x32_bf16 v[22:25], v[166:169], v[198:201], v[22:25]
	v_mfma_f32_16x16x32_bf16 v[18:21], v[174:177], v[198:201], v[18:21]
	v_mfma_f32_16x16x32_bf16 v[6:9], v[166:169], v[224:227], v[6:9]
	v_mfma_f32_16x16x32_bf16 v[2:5], v[174:177], v[224:227], v[2:5]
	s_setprio 0
	s_barrier
	s_add_i32 s45, s45, 2
	s_add_u32 s16, s16, 0x100
	s_addc_u32 s17, s17, 0
	s_add_u32 s43, s43, 0x100
	s_addc_u32 s44, s44, 0
	s_cmp_gt_u32 s45, 5
	s_cbranch_scc0 .LBB0_891
	v_lshl_add_u32 v140, s14, 8, v150
	v_lshl_or_b32 v141, s15, 8, v152
	v_mul_lo_u32 v138, v140, s83
	v_lshlrev_b32_e32 v139, 11, v140
	v_lshl_add_u32 v138, v141, 1, v138
	v_lshl_add_u32 v139, v141, 1, v139
	global_load_dwordx4 v[144:147], v138, s[74:75]
	global_load_dwordx4 v[156:159], v138, s[74:75] offset:256
	v_add_u32_e32 v140, 0x1a000, v138
	global_load_dwordx4 v[160:163], v140, s[74:75]
	global_load_dwordx4 v[164:167], v140, s[74:75] offset:256
	v_add_u32_e32 v140, 0x34000, v138
	global_load_dwordx4 v[168:171], v140, s[74:75]
	global_load_dwordx4 v[172:175], v140, s[74:75] offset:256
	v_add_u32_e32 v140, 0x4e000, v138
	global_load_dwordx4 v[176:179], v140, s[74:75]
	global_load_dwordx4 v[180:183], v140, s[74:75] offset:256
	v_add_u32_e32 v140, 0xd0000, v138
	global_load_dwordx4 v[184:187], v140, s[74:75]
	global_load_dwordx4 v[188:191], v140, s[74:75] offset:256
	v_add_u32_e32 v140, 0xea000, v138
	global_load_dwordx4 v[192:195], v140, s[74:75]
	global_load_dwordx4 v[196:199], v140, s[74:75] offset:256
	v_add_u32_e32 v140, 0x104000, v138
	global_load_dwordx4 v[200:203], v140, s[74:75]
	global_load_dwordx4 v[224:227], v140, s[74:75] offset:256
	v_add_u32_e32 v140, 0x11e000, v138
	global_load_dwordx4 v[228:231], v140, s[74:75]
	global_load_dwordx4 v[232:235], v140, s[74:75] offset:256
	s_and_b64 vcc, exec, s[4:5]
	s_cbranch_vccz .LBB0_894
	s_barrier

; #define PG8_STAGE(bufoff, gbase, voff) do { _Pragma("unroll") for (int _i = 0; _i < 2; ++_i) \
;         __builtin_amdgcn_global_load_lds((const unsigned*)((const char*)(gbase) + (voff)[_i]), (PG8_LAS unsigned*)(lds + (bufoff) + ldsw + _i * 8192), 16, 0, 0); } while (0)
; #define PG8_LDA(dst, b, h) do { _Pragma("unroll") for (int m = 0; m < 4; ++m) _Pragma("unroll") for (int k = 0; k < 2; ++k) dst[m][k] = *(const PG8_LAS bf16x8*)(lds + PG8_SA(b, h) + aoff + m * 2048 + k * 1024); } while (0)
; #define PG8_LDB(dst, b, h) do { _Pragma("unroll") for (int n = 0; n < 2; ++n) _Pragma("unroll") for (int k = 0; k < 2; ++k) dst[n][k] = *(const PG8_LAS bf16x8*)(lds + PG8_SB(b, h) + boff + n * 2048 + k * 1024); } while (0)
; #define PG8_MMA(ai, bj, At, Bt) do { __builtin_amdgcn_s_setprio(1); _Pragma("unroll") for (int m = 0; m < 4; ++m) _Pragma("unroll") for (int n = 0; n < 2; ++n) _Pragma("unroll") for (int k = 0; k < 2; ++k) \
;         acc[ai][bj][m][n] = __builtin_amdgcn_mfma_f32_16x16x32_bf16(Bt[n][k], At[m][k], acc[ai][bj][m][n], 0, 0, 0); __builtin_amdgcn_s_setprio(0); } while (0)
; #define PG8_WAIT_V(n) asm volatile("s_waitcnt vmcnt(" #n ")" ::: "memory")
; #define PG8_WAIT_L(n) asm volatile("s_waitcnt lgkmcnt(" #n ")" ::: "memory")
; #define PG8_BAR __builtin_amdgcn_s_barrier()
; #define PG8_SCHED __builtin_amdgcn_sched_barrier(0)
; template <class Epi, class Sched, bool ALIGN_EPI = false, bool SP2 = false>
; __device__ __forceinline__ void gemm_phase(PG8_LAS unsigned char* lds, const Gemm g, const Sched& S, const Epi& E) {
;     ...
;             PG8_LDB(B0, 0, 0); PG8_LDB(B1, 0, 1); PG8_SCHED; PG8_LDA(At, 0, 0); PG8_STAGE(PG8_SA(1, 1), a1 + hstep, voffA);
;             PG8_WAIT_V(8); PG8_WAIT_L(0); PG8_BAR; PG8_MMA(0, 0, At, B0); PG8_MMA(0, 1, At, B1); PG8_BAR; PG8_SCHED;
;             PG8_LDA(At, 0, 1); PG8_STAGE(PG8_SB(0, 0), b2, voffB); PG8_STAGE(PG8_SB(0, 1), b2 + hstep, voffB); PG8_STAGE(PG8_SA(0, 0), a2, voffA);
.LBB0_919:
	s_add_u32 s12, s10, 0x100
	s_addc_u32 s13, s11, 0
	s_add_i32 s44, 0, 0x10000
	s_cmp_eq_u32 s43, 16
	s_cselect_b32 s17, s5, s13
	s_cselect_b32 s16, s4, s12
	v_add_u32_e32 v148, s44, v151
	s_cselect_b32 s15, s9, s42
	s_cselect_b32 s14, s8, s41
	s_add_i32 s45, 0, 0x14000
	ds_read_b128 v[138:141], v148
	ds_read_b128 v[144:147], v148 offset:1024
	ds_read_b128 v[154:157], v148 offset:2048
	ds_read_b128 v[158:161], v148 offset:3072
	v_add_u32_e32 v148, s45, v151
	ds_read_b128 v[162:165], v148
	ds_read_b128 v[166:169], v148 offset:1024
	ds_read_b128 v[170:173], v148 offset:2048
	ds_read_b128 v[174:177], v148 offset:3072
	v_lshl_add_u64 v[148:149], s[10:11], 0, v[136:137]
	s_add_i32 m0, s23, 0xc000
	ds_read_b128 v[178:181], v153
	ds_read_b128 v[182:185], v153 offset:1024
	ds_read_b128 v[186:189], v153 offset:2048
	ds_read_b128 v[190:193], v153 offset:3072
	ds_read_b128 v[194:197], v153 offset:4096
	ds_read_b128 v[198:201], v153 offset:5120
	ds_read_b128 v[202:205], v153 offset:6144
	ds_read_b128 v[224:227], v153 offset:7168
	global_load_lds_dwordx4 v[148:149], off
	v_lshl_add_u64 v[148:149], s[10:11], 0, v[142:143]
	s_add_i32 m0, s23, 0xe000
	s_nop 0
	global_load_lds_dwordx4 v[148:149], off
	s_waitcnt vmcnt(8)
	s_waitcnt lgkmcnt(0)
	s_barrier
	s_setprio 1
	s_waitcnt lgkmcnt(0)
	v_mfma_f32_16x16x32_bf16 v[126:129], v[138:141], v[178:181], v[126:129]
	v_mfma_f32_16x16x32_bf16 v[122:125], v[154:157], v[178:181], v[122:125]
	v_mfma_f32_16x16x32_bf16 v[110:113], v[138:141], v[186:189], v[110:113]
	v_mfma_f32_16x16x32_bf16 v[106:109], v[154:157], v[186:189], v[106:109]
	v_mfma_f32_16x16x32_bf16 v[94:97], v[138:141], v[194:197], v[94:97]
	v_mfma_f32_16x16x32_bf16 v[90:93], v[154:157], v[194:197], v[90:93]
	v_mfma_f32_16x16x32_bf16 v[78:81], v[138:141], v[202:205], v[78:81]
	v_mfma_f32_16x16x32_bf16 v[74:77], v[154:157], v[202:205], v[74:77]
	v_mfma_f32_16x16x32_bf16 v[126:129], v[144:147], v[182:185], v[126:129]
	v_mfma_f32_16x16x32_bf16 v[122:125], v[158:161], v[182:185], v[122:125]
	v_mfma_f32_16x16x32_bf16 v[110:113], v[144:147], v[190:193], v[110:113]
	v_mfma_f32_16x16x32_bf16 v[106:109], v[158:161], v[190:193], v[106:109]
	v_mfma_f32_16x16x32_bf16 v[94:97], v[144:147], v[198:201], v[94:97]
	v_mfma_f32_16x16x32_bf16 v[90:93], v[158:161], v[198:201], v[90:93]
	v_mfma_f32_16x16x32_bf16 v[78:81], v[144:147], v[224:227], v[78:81]
	v_mfma_f32_16x16x32_bf16 v[74:77], v[158:161], v[224:227], v[74:77]
	v_mfma_f32_16x16x32_bf16 v[118:121], v[162:165], v[178:181], v[118:121]
	v_mfma_f32_16x16x32_bf16 v[114:117], v[170:173], v[178:181], v[114:117]
	v_mfma_f32_16x16x32_bf16 v[102:105], v[162:165], v[186:189], v[102:105]
	v_mfma_f32_16x16x32_bf16 v[98:101], v[170:173], v[186:189], v[98:101]
	v_mfma_f32_16x16x32_bf16 v[86:89], v[162:165], v[194:197], v[86:89]
	v_mfma_f32_16x16x32_bf16 v[82:85], v[170:173], v[194:197], v[82:85]
	v_mfma_f32_16x16x32_bf16 v[70:73], v[162:165], v[202:205], v[70:73]
	v_mfma_f32_16x16x32_bf16 v[66:69], v[170:173], v[202:205], v[66:69]
	v_mfma_f32_16x16x32_bf16 v[118:121], v[166:169], v[182:185], v[118:121]
	v_mfma_f32_16x16x32_bf16 v[114:117], v[174:177], v[182:185], v[114:117]
	v_mfma_f32_16x16x32_bf16 v[102:105], v[166:169], v[190:193], v[102:105]
	v_mfma_f32_16x16x32_bf16 v[98:101], v[174:177], v[190:193], v[98:101]
	v_mfma_f32_16x16x32_bf16 v[86:89], v[166:169], v[198:201], v[86:89]
	v_mfma_f32_16x16x32_bf16 v[82:85], v[174:177], v[198:201], v[82:85]
	v_mfma_f32_16x16x32_bf16 v[70:73], v[166:169], v[224:227], v[70:73]
	v_mfma_f32_16x16x32_bf16 v[66:69], v[174:177], v[224:227], v[66:69]
	s_setprio 0
	s_barrier
	s_add_i32 s10, s44, s20
	v_lshl_add_u64 v[148:149], s[14:15], 0, v[0:1]
	s_mov_b32 m0, s10
	ds_read_b128 v[178:181], v153 offset:16384
	ds_read_b128 v[182:185], v153 offset:17408
	ds_read_b128 v[186:189], v153 offset:18432
	ds_read_b128 v[190:193], v153 offset:19456
	ds_read_b128 v[194:197], v153 offset:20480
	ds_read_b128 v[198:201], v153 offset:21504
	ds_read_b128 v[202:205], v153 offset:22528
	ds_read_b128 v[224:227], v153 offset:23552
	global_load_lds_dwordx4 v[148:149], off
	s_add_i32 m0, s10, 0x2000
	s_add_u32 s10, s14, 0x50000
	v_lshl_add_u64 v[228:229], s[14:15], 0, v[134:135]
	s_addc_u32 s11, s15, 0
	s_add_i32 s44, s45, s20
	global_load_lds_dwordx4 v[228:229], off
	v_lshl_add_u64 v[230:231], s[10:11], 0, v[0:1]
	s_mov_b32 m0, s44
	v_lshl_add_u64 v[232:233], s[16:17], 0, v[132:133]
	global_load_lds_dwordx4 v[230:231], off
	v_lshl_add_u64 v[230:231], s[10:11], 0, v[134:135]
	s_add_i32 m0, s44, 0x2000
	s_nop 0
	global_load_lds_dwordx4 v[230:231], off
	v_lshl_add_u64 v[230:231], s[16:17], 0, v[130:131]
	s_mov_b32 m0, s23
	s_nop 0
	global_load_lds_dwordx4 v[230:231], off
	s_mov_b32 m0, s24
	s_nop 0
	global_load_lds_dwordx4 v[232:233], off
	s_waitcnt vmcnt(8)
	s_waitcnt lgkmcnt(0)
	s_barrier
; #define PG8_STAGE(bufoff, gbase, voff) do { _Pragma("unroll") for (int _i = 0; _i < 2; ++_i) \
;         __builtin_amdgcn_global_load_lds((const unsigned*)((const char*)(gbase) + (voff)[_i]), (PG8_LAS unsigned*)(lds + (bufoff) + ldsw + _i * 8192), 16, 0, 0); } while (0)
; #define PG8_LDA(dst, b, h) do { _Pragma("unroll") for (int m = 0; m < 4; ++m) _Pragma("unroll") for (int k = 0; k < 2; ++k) dst[m][k] = *(const PG8_LAS bf16x8*)(lds + PG8_SA(b, h) + aoff + m * 2048 + k * 1024); } while (0)
; #define PG8_LDB(dst, b, h) do { _Pragma("unroll") for (int n = 0; n < 2; ++n) _Pragma("unroll") for (int k = 0; k < 2; ++k) dst[n][k] = *(const PG8_LAS bf16x8*)(lds + PG8_SB(b, h) + boff + n * 2048 + k * 1024); } while (0)
; #define PG8_MMA(ai, bj, At, Bt) do { __builtin_amdgcn_s_setprio(1); _Pragma("unroll") for (int m = 0; m < 4; ++m) _Pragma("unroll") for (int n = 0; n < 2; ++n) _Pragma("unroll") for (int k = 0; k < 2; ++k) \
;         acc[ai][bj][m][n] = __builtin_amdgcn_mfma_f32_16x16x32_bf16(Bt[n][k], At[m][k], acc[ai][bj][m][n], 0, 0, 0); __builtin_amdgcn_s_setprio(0); } while (0)
; #define PG8_WAIT_V(n) asm volatile("s_waitcnt vmcnt(" #n ")" ::: "memory")
; #define PG8_WAIT_L(n) asm volatile("s_waitcnt lgkmcnt(" #n ")" ::: "memory")
; #define PG8_BAR __builtin_amdgcn_s_barrier()
; #define PG8_SCHED __builtin_amdgcn_sched_barrier(0)
; template <class Epi, class Sched, bool ALIGN_EPI = false, bool SP2 = false>
; __device__ __forceinline__ void gemm_phase(PG8_LAS unsigned char* lds, const Gemm g, const Sched& S, const Epi& E) {
;     ...
;             PG8_WAIT_V(8); PG8_WAIT_L(0); PG8_BAR; PG8_MMA(1, 0, At, B0); PG8_MMA(1, 1, At, B1); PG8_BAR; PG8_SCHED;
;             PG8_LDB(B0, 1, 0); PG8_LDB(B1, 1, 1); PG8_SCHED; PG8_LDA(At, 1, 0); PG8_STAGE(PG8_SA(0, 1), a2 + hstep, voffA);
;             PG8_WAIT_V(8); PG8_WAIT_L(0); PG8_BAR; PG8_MMA(0, 0, At, B0); PG8_MMA(0, 1, At, B1); PG8_BAR; PG8_SCHED;
	s_setprio 1
	s_waitcnt lgkmcnt(0)
	v_mfma_f32_16x16x32_bf16 v[62:65], v[138:141], v[178:181], v[62:65]
	v_mfma_f32_16x16x32_bf16 v[58:61], v[154:157], v[178:181], v[58:61]
	v_mfma_f32_16x16x32_bf16 v[46:49], v[138:141], v[186:189], v[46:49]
	v_mfma_f32_16x16x32_bf16 v[42:45], v[154:157], v[186:189], v[42:45]
	v_mfma_f32_16x16x32_bf16 v[30:33], v[138:141], v[194:197], v[30:33]
	v_mfma_f32_16x16x32_bf16 v[26:29], v[154:157], v[194:197], v[26:29]
	v_mfma_f32_16x16x32_bf16 v[14:17], v[138:141], v[202:205], v[14:17]
	v_mfma_f32_16x16x32_bf16 v[10:13], v[154:157], v[202:205], v[10:13]
	v_mfma_f32_16x16x32_bf16 v[62:65], v[144:147], v[182:185], v[62:65]
	v_mfma_f32_16x16x32_bf16 v[58:61], v[158:161], v[182:185], v[58:61]
	v_mfma_f32_16x16x32_bf16 v[46:49], v[144:147], v[190:193], v[46:49]
	v_mfma_f32_16x16x32_bf16 v[42:45], v[158:161], v[190:193], v[42:45]
	v_mfma_f32_16x16x32_bf16 v[30:33], v[144:147], v[198:201], v[30:33]
	v_mfma_f32_16x16x32_bf16 v[26:29], v[158:161], v[198:201], v[26:29]
	v_mfma_f32_16x16x32_bf16 v[14:17], v[144:147], v[224:227], v[14:17]
	v_mfma_f32_16x16x32_bf16 v[10:13], v[158:161], v[224:227], v[10:13]
	v_mfma_f32_16x16x32_bf16 v[54:57], v[162:165], v[178:181], v[54:57]
	v_mfma_f32_16x16x32_bf16 v[50:53], v[170:173], v[178:181], v[50:53]
	v_mfma_f32_16x16x32_bf16 v[38:41], v[162:165], v[186:189], v[38:41]
	v_mfma_f32_16x16x32_bf16 v[34:37], v[170:173], v[186:189], v[34:37]
	v_mfma_f32_16x16x32_bf16 v[22:25], v[162:165], v[194:197], v[22:25]
	v_mfma_f32_16x16x32_bf16 v[18:21], v[170:173], v[194:197], v[18:21]
	v_mfma_f32_16x16x32_bf16 v[6:9], v[162:165], v[202:205], v[6:9]
	v_mfma_f32_16x16x32_bf16 v[2:5], v[170:173], v[202:205], v[2:5]
	v_mfma_f32_16x16x32_bf16 v[54:57], v[166:169], v[182:185], v[54:57]
	v_mfma_f32_16x16x32_bf16 v[50:53], v[174:177], v[182:185], v[50:53]
	v_mfma_f32_16x16x32_bf16 v[38:41], v[166:169], v[190:193], v[38:41]
	v_mfma_f32_16x16x32_bf16 v[34:37], v[174:177], v[190:193], v[34:37]
	v_mfma_f32_16x16x32_bf16 v[22:25], v[166:169], v[198:201], v[22:25]
	v_mfma_f32_16x16x32_bf16 v[18:21], v[174:177], v[198:201], v[18:21]
	v_mfma_f32_16x16x32_bf16 v[6:9], v[166:169], v[224:227], v[6:9]
	v_mfma_f32_16x16x32_bf16 v[2:5], v[174:177], v[224:227], v[2:5]
	s_setprio 0
	s_barrier
	s_add_i32 s44, 0, 0x18000
	s_add_i32 s45, 0, 0x1c000
	v_add_u32_e32 v158, s44, v151
	v_add_u32_e32 v174, s45, v151
	ds_read_b128 v[138:141], v158
	ds_read_b128 v[144:147], v158 offset:1024
	ds_read_b128 v[154:157], v158 offset:2048
	ds_read_b128 v[158:161], v158 offset:3072
	ds_read_b128 v[162:165], v174
	ds_read_b128 v[166:169], v174 offset:1024
	ds_read_b128 v[170:173], v174 offset:2048
	ds_read_b128 v[174:177], v174 offset:3072
	s_add_u32 s10, s16, 0x50000
	s_addc_u32 s11, s17, 0
	s_mov_b32 m0, s25
	v_lshl_add_u64 v[234:235], s[10:11], 0, v[130:131]
	ds_read_b128 v[178:181], v153 offset:32768
	ds_read_b128 v[182:185], v153 offset:33792
	ds_read_b128 v[186:189], v153 offset:34816
	ds_read_b128 v[190:193], v153 offset:35840
	ds_read_b128 v[194:197], v153 offset:36864
	ds_read_b128 v[198:201], v153 offset:37888
	ds_read_b128 v[202:205], v153 offset:38912
	ds_read_b128 v[224:227], v153 offset:39936
	global_load_lds_dwordx4 v[234:235], off
	v_lshl_add_u64 v[234:235], s[10:11], 0, v[132:133]
	s_mov_b32 m0, s26
	s_nop 0
	global_load_lds_dwordx4 v[234:235], off
	s_waitcnt vmcnt(8)
	s_waitcnt lgkmcnt(0)
	s_barrier
	s_setprio 1
	s_waitcnt lgkmcnt(0)
	v_mfma_f32_16x16x32_bf16 v[126:129], v[138:141], v[178:181], v[126:129]
	v_mfma_f32_16x16x32_bf16 v[122:125], v[154:157], v[178:181], v[122:125]
	v_mfma_f32_16x16x32_bf16 v[110:113], v[138:141], v[186:189], v[110:113]
	v_mfma_f32_16x16x32_bf16 v[106:109], v[154:157], v[186:189], v[106:109]
	v_mfma_f32_16x16x32_bf16 v[94:97], v[138:141], v[194:197], v[94:97]
	v_mfma_f32_16x16x32_bf16 v[90:93], v[154:157], v[194:197], v[90:93]
	v_mfma_f32_16x16x32_bf16 v[78:81], v[138:141], v[202:205], v[78:81]
	v_mfma_f32_16x16x32_bf16 v[74:77], v[154:157], v[202:205], v[74:77]
	v_mfma_f32_16x16x32_bf16 v[126:129], v[144:147], v[182:185], v[126:129]
	v_mfma_f32_16x16x32_bf16 v[122:125], v[158:161], v[182:185], v[122:125]
	v_mfma_f32_16x16x32_bf16 v[110:113], v[144:147], v[190:193], v[110:113]
	v_mfma_f32_16x16x32_bf16 v[106:109], v[158:161], v[190:193], v[106:109]
	v_mfma_f32_16x16x32_bf16 v[94:97], v[144:147], v[198:201], v[94:97]
	v_mfma_f32_16x16x32_bf16 v[90:93], v[158:161], v[198:201], v[90:93]
	v_mfma_f32_16x16x32_bf16 v[78:81], v[144:147], v[224:227], v[78:81]
	v_mfma_f32_16x16x32_bf16 v[74:77], v[158:161], v[224:227], v[74:77]
	v_mfma_f32_16x16x32_bf16 v[118:121], v[162:165], v[178:181], v[118:121]
	v_mfma_f32_16x16x32_bf16 v[114:117], v[170:173], v[178:181], v[114:117]
	v_mfma_f32_16x16x32_bf16 v[102:105], v[162:165], v[186:189], v[102:105]
	v_mfma_f32_16x16x32_bf16 v[98:101], v[170:173], v[186:189], v[98:101]
	v_mfma_f32_16x16x32_bf16 v[86:89], v[162:165], v[194:197], v[86:89]
	v_mfma_f32_16x16x32_bf16 v[82:85], v[170:173], v[194:197], v[82:85]
	v_mfma_f32_16x16x32_bf16 v[70:73], v[162:165], v[202:205], v[70:73]
	v_mfma_f32_16x16x32_bf16 v[66:69], v[170:173], v[202:205], v[66:69]
	v_mfma_f32_16x16x32_bf16 v[118:121], v[166:169], v[182:185], v[118:121]
	v_mfma_f32_16x16x32_bf16 v[114:117], v[174:177], v[182:185], v[114:117]
	v_mfma_f32_16x16x32_bf16 v[102:105], v[166:169], v[190:193], v[102:105]
	v_mfma_f32_16x16x32_bf16 v[98:101], v[174:177], v[190:193], v[98:101]
	v_mfma_f32_16x16x32_bf16 v[86:89], v[166:169], v[198:201], v[86:89]
	v_mfma_f32_16x16x32_bf16 v[82:85], v[174:177], v[198:201], v[82:85]
	v_mfma_f32_16x16x32_bf16 v[70:73], v[166:169], v[224:227], v[70:73]
	v_mfma_f32_16x16x32_bf16 v[66:69], v[174:177], v[224:227], v[66:69]
	s_setprio 0
	s_barrier
; #define PG8_STAGE(bufoff, gbase, voff) do { _Pragma("unroll") for (int _i = 0; _i < 2; ++_i) \
;         __builtin_amdgcn_global_load_lds((const unsigned*)((const char*)(gbase) + (voff)[_i]), (PG8_LAS unsigned*)(lds + (bufoff) + ldsw + _i * 8192), 16, 0, 0); } while (0)
; #define PG8_LDA(dst, b, h) do { _Pragma("unroll") for (int m = 0; m < 4; ++m) _Pragma("unroll") for (int k = 0; k < 2; ++k) dst[m][k] = *(const PG8_LAS bf16x8*)(lds + PG8_SA(b, h) + aoff + m * 2048 + k * 1024); } while (0)
; #define PG8_MMA(ai, bj, At, Bt) do { __builtin_amdgcn_s_setprio(1); _Pragma("unroll") for (int m = 0; m < 4; ++m) _Pragma("unroll") for (int n = 0; n < 2; ++n) _Pragma("unroll") for (int k = 0; k < 2; ++k) \
;         acc[ai][bj][m][n] = __builtin_amdgcn_mfma_f32_16x16x32_bf16(Bt[n][k], At[m][k], acc[ai][bj][m][n], 0, 0, 0); __builtin_amdgcn_s_setprio(0); } while (0)
; #define PG8_WAIT_V(n) asm volatile("s_waitcnt vmcnt(" #n ")" ::: "memory")
; #define PG8_WAIT_L(n) asm volatile("s_waitcnt lgkmcnt(" #n ")" ::: "memory")
; #define PG8_BAR __builtin_amdgcn_s_barrier()
; #define PG8_SCHED __builtin_amdgcn_sched_barrier(0)
; template <class Epi, class Sched, bool ALIGN_EPI = false, bool SP2 = false>
; __device__ __forceinline__ void gemm_phase(PG8_LAS unsigned char* lds, const Gemm g, const Sched& S, const Epi& E) {
;     ...
;             PG8_LDA(At, 1, 1); PG8_STAGE(PG8_SB(1, 0), b3, voffB); PG8_STAGE(PG8_SB(1, 1), b3 + hstep, voffB); PG8_STAGE(PG8_SA(1, 0), a3, voffA);
;             PG8_WAIT_V(8); PG8_WAIT_L(0); PG8_BAR; PG8_MMA(1, 0, At, B0); PG8_MMA(1, 1, At, B1); PG8_BAR; PG8_SCHED;
;     __device__ __forceinline__ void operator()(const f32x4 (&acc)[2][2][4][2], const Unit& u, int wr, int wc, int fr, int fq) const {
;     ...
;                 const int row = row0 + ai * 128 + m * 16;
; #pragma unroll
;                 for (int bj = 0; bj < 2; ++bj) {
;                     const int c = col0 + bj * 128;
;                     const u32x4 g = *(const u32x4*)(G + (size_t)row * P2W + c);
;                     const u32x4 t = *(const u32x4*)(T + (size_t)row * D + c);
	s_add_i32 s10, s44, s20
	v_lshl_add_u64 v[148:149], v[148:149], 0, s[86:87]
	s_mov_b32 m0, s10
	ds_read_b128 v[178:181], v153 offset:49152
	ds_read_b128 v[182:185], v153 offset:50176
	ds_read_b128 v[186:189], v153 offset:51200
	ds_read_b128 v[190:193], v153 offset:52224
	ds_read_b128 v[194:197], v153 offset:53248
	ds_read_b128 v[198:201], v153 offset:54272
	ds_read_b128 v[202:205], v153 offset:55296
	ds_read_b128 v[224:227], v153 offset:56320
	global_load_lds_dwordx4 v[148:149], off
	s_add_i32 m0, s10, 0x2000
	s_add_u32 s10, s14, 0x50080
	v_lshl_add_u64 v[148:149], v[228:229], 0, s[86:87]
	s_addc_u32 s11, s15, 0
	s_add_i32 s14, s45, s20
	global_load_lds_dwordx4 v[148:149], off
	v_lshl_add_u64 v[148:149], s[10:11], 0, v[0:1]
	s_mov_b32 m0, s14
	s_nop 0
	global_load_lds_dwordx4 v[148:149], off
	v_lshl_add_u64 v[148:149], s[10:11], 0, v[134:135]
	s_add_i32 m0, s14, 0x2000
	s_nop 0
	global_load_lds_dwordx4 v[148:149], off
	v_lshl_add_u64 v[148:149], v[230:231], 0, s[86:87]
	s_mov_b32 m0, s27
	s_nop 0
	global_load_lds_dwordx4 v[148:149], off
	v_lshl_add_u64 v[148:149], v[232:233], 0, s[86:87]
	s_mov_b32 m0, s28
	s_nop 0
	global_load_lds_dwordx4 v[148:149], off
	s_waitcnt vmcnt(8)
	s_waitcnt lgkmcnt(0)
	s_barrier
	s_setprio 1
	s_waitcnt lgkmcnt(0)
	v_mfma_f32_16x16x32_bf16 v[62:65], v[138:141], v[178:181], v[62:65]
	v_mfma_f32_16x16x32_bf16 v[58:61], v[154:157], v[178:181], v[58:61]
	v_mfma_f32_16x16x32_bf16 v[46:49], v[138:141], v[186:189], v[46:49]
	v_mfma_f32_16x16x32_bf16 v[42:45], v[154:157], v[186:189], v[42:45]
	v_mfma_f32_16x16x32_bf16 v[30:33], v[138:141], v[194:197], v[30:33]
	v_mfma_f32_16x16x32_bf16 v[26:29], v[154:157], v[194:197], v[26:29]
	v_mfma_f32_16x16x32_bf16 v[14:17], v[138:141], v[202:205], v[14:17]
	v_mfma_f32_16x16x32_bf16 v[10:13], v[154:157], v[202:205], v[10:13]
	v_mfma_f32_16x16x32_bf16 v[62:65], v[144:147], v[182:185], v[62:65]
	v_mfma_f32_16x16x32_bf16 v[58:61], v[158:161], v[182:185], v[58:61]
	v_mfma_f32_16x16x32_bf16 v[46:49], v[144:147], v[190:193], v[46:49]
	v_mfma_f32_16x16x32_bf16 v[42:45], v[158:161], v[190:193], v[42:45]
	v_mfma_f32_16x16x32_bf16 v[30:33], v[144:147], v[198:201], v[30:33]
	v_mfma_f32_16x16x32_bf16 v[26:29], v[158:161], v[198:201], v[26:29]
	v_mfma_f32_16x16x32_bf16 v[14:17], v[144:147], v[224:227], v[14:17]
	v_mfma_f32_16x16x32_bf16 v[10:13], v[158:161], v[224:227], v[10:13]
	v_mfma_f32_16x16x32_bf16 v[54:57], v[162:165], v[178:181], v[54:57]
	v_mfma_f32_16x16x32_bf16 v[50:53], v[170:173], v[178:181], v[50:53]
	v_mfma_f32_16x16x32_bf16 v[38:41], v[162:165], v[186:189], v[38:41]
	v_mfma_f32_16x16x32_bf16 v[34:37], v[170:173], v[186:189], v[34:37]
	v_mfma_f32_16x16x32_bf16 v[22:25], v[162:165], v[194:197], v[22:25]
	v_mfma_f32_16x16x32_bf16 v[18:21], v[170:173], v[194:197], v[18:21]
	v_mfma_f32_16x16x32_bf16 v[6:9], v[162:165], v[202:205], v[6:9]
	v_mfma_f32_16x16x32_bf16 v[2:5], v[170:173], v[202:205], v[2:5]
	v_mfma_f32_16x16x32_bf16 v[54:57], v[166:169], v[182:185], v[54:57]
	v_mfma_f32_16x16x32_bf16 v[50:53], v[174:177], v[182:185], v[50:53]
	v_mfma_f32_16x16x32_bf16 v[38:41], v[166:169], v[190:193], v[38:41]
	v_mfma_f32_16x16x32_bf16 v[34:37], v[174:177], v[190:193], v[34:37]
	v_mfma_f32_16x16x32_bf16 v[22:25], v[166:169], v[198:201], v[22:25]
	v_mfma_f32_16x16x32_bf16 v[18:21], v[174:177], v[198:201], v[18:21]
	v_mfma_f32_16x16x32_bf16 v[6:9], v[166:169], v[224:227], v[6:9]
	v_mfma_f32_16x16x32_bf16 v[2:5], v[174:177], v[224:227], v[2:5]
	s_setprio 0
	s_barrier
	s_add_i32 s43, s43, 2
	s_add_u32 s41, s41, 0x100
	s_addc_u32 s42, s42, 0
	s_cmp_gt_u32 s43, 17
	s_mov_b64 s[10:11], s[12:13]
	s_cbranch_scc0 .LBB0_919
	v_lshl_add_u32 v140, s38, 8, v150
	v_lshl_or_b32 v141, s39, 8, v152
	v_mul_lo_u32 v138, v140, s83
	v_lshlrev_b32_e32 v139, 11, v140
	v_lshl_add_u32 v138, v141, 1, v138
	v_lshl_add_u32 v139, v141, 1, v139
	global_load_dwordx4 v[144:147], v138, s[72:73]
	global_load_dwordx4 v[156:159], v139, s[36:37]
	global_load_dwordx4 v[160:163], v138, s[72:73] offset:256
	global_load_dwordx4 v[164:167], v139, s[36:37] offset:256
	v_add_u32_e32 v140, 0x1a000, v138
	v_add_u32_e32 v141, 0x8000, v139
	global_load_dwordx4 v[168:171], v140, s[72:73]
	global_load_dwordx4 v[172:175], v141, s[36:37]
	global_load_dwordx4 v[176:179], v140, s[72:73] offset:256
	global_load_dwordx4 v[180:183], v141, s[36:37] offset:256
	v_add_u32_e32 v140, 0x34000, v138
	v_add_u32_e32 v141, 0x10000, v139
	global_load_dwordx4 v[184:187], v140, s[72:73]
	global_load_dwordx4 v[188:191], v141, s[36:37]
	global_load_dwordx4 v[192:195], v140, s[72:73] offset:256
	global_load_dwordx4 v[196:199], v141, s[36:37] offset:256
	v_add_u32_e32 v140, 0x4e000, v138
	v_add_u32_e32 v141, 0x18000, v139
	global_load_dwordx4 v[200:203], v140, s[72:73]
	global_load_dwordx4 v[224:227], v141, s[36:37]
	global_load_dwordx4 v[228:231], v140, s[72:73] offset:256
	global_load_dwordx4 v[232:235], v141, s[36:37] offset:256
	s_and_b64 vcc, exec, s[6:7]
	s_cbranch_vccz .LBB0_922
	s_barrier

; #define PG8_STAGE(bufoff, gbase, voff) do { _Pragma("unroll") for (int _i = 0; _i < 2; ++_i) \
;         __builtin_amdgcn_global_load_lds((const unsigned*)((const char*)(gbase) + (voff)[_i]), (PG8_LAS unsigned*)(lds + (bufoff) + ldsw + _i * 8192), 16, 0, 0); } while (0)
; #define PG8_LDA(dst, b, h) do { _Pragma("unroll") for (int m = 0; m < 4; ++m) _Pragma("unroll") for (int k = 0; k < 2; ++k) dst[m][k] = *(const PG8_LAS bf16x8*)(lds + PG8_SA(b, h) + aoff + m * 2048 + k * 1024); } while (0)
; #define PG8_LDB(dst, b, h) do { _Pragma("unroll") for (int n = 0; n < 2; ++n) _Pragma("unroll") for (int k = 0; k < 2; ++k) dst[n][k] = *(const PG8_LAS bf16x8*)(lds + PG8_SB(b, h) + boff + n * 2048 + k * 1024); } while (0)
; #define PG8_MMA(ai, bj, At, Bt) do { __builtin_amdgcn_s_setprio(1); _Pragma("unroll") for (int m = 0; m < 4; ++m) _Pragma("unroll") for (int n = 0; n < 2; ++n) _Pragma("unroll") for (int k = 0; k < 2; ++k) \
;         acc[ai][bj][m][n] = __builtin_amdgcn_mfma_f32_16x16x32_bf16(Bt[n][k], At[m][k], acc[ai][bj][m][n], 0, 0, 0); __builtin_amdgcn_s_setprio(0); } while (0)
; #define PG8_WAIT_V(n) asm volatile("s_waitcnt vmcnt(" #n ")" ::: "memory")
; #define PG8_WAIT_L(n) asm volatile("s_waitcnt lgkmcnt(" #n ")" ::: "memory")
; #define PG8_BAR __builtin_amdgcn_s_barrier()
; #define PG8_SCHED __builtin_amdgcn_sched_barrier(0)
; template <class Epi, class Sched, bool ALIGN_EPI = false, bool SP2 = false>
; __device__ __forceinline__ void gemm_phase(PG8_LAS unsigned char* lds, const Gemm g, const Sched& S, const Epi& E) {
;     ...
;             PG8_LDB(B0, 0, 0); PG8_LDB(B1, 0, 1); PG8_SCHED; PG8_LDA(At, 0, 0); PG8_STAGE(PG8_SA(1, 1), a1 + hstep, voffA);
;             PG8_WAIT_V(8); PG8_WAIT_L(0); PG8_BAR; PG8_MMA(0, 0, At, B0); PG8_MMA(0, 1, At, B1); PG8_BAR; PG8_SCHED;
;             PG8_LDA(At, 0, 1); PG8_STAGE(PG8_SB(0, 0), b2, voffB); PG8_STAGE(PG8_SB(0, 1), b2 + hstep, voffB); PG8_STAGE(PG8_SA(0, 0), a2, voffA);
.LBB0_1050:
	s_add_u32 s24, s22, 0xfffc0080
	s_addc_u32 s25, s23, -1
	s_add_i32 s51, 0, 0x10000
	s_cmp_eq_u32 s50, 12
	s_cselect_b32 s27, s13, s25
	s_cselect_b32 s26, s19, s24
	s_cselect_b32 s25, s11, s49
	s_cselect_b32 s24, s21, s48
	s_add_i32 s55, 0, 0x14000
	v_add_u32_e32 v156, s51, v149
	v_add_u32_e32 v172, s55, v149
	ds_read_b128 v[138:141], v156
	ds_read_b128 v[144:147], v156 offset:1024
	ds_read_b128 v[152:155], v156 offset:2048
	ds_read_b128 v[156:159], v156 offset:3072
	ds_read_b128 v[160:163], v172
	ds_read_b128 v[164:167], v172 offset:1024
	ds_read_b128 v[168:171], v172 offset:2048
	ds_read_b128 v[172:175], v172 offset:3072
	v_lshl_add_u64 v[204:205], s[22:23], 0, v[136:137]
	s_add_i32 m0, s38, 0xc000
	ds_read_b128 v[176:179], v151
	ds_read_b128 v[180:183], v151 offset:1024
	ds_read_b128 v[184:187], v151 offset:2048
	ds_read_b128 v[188:191], v151 offset:3072
	ds_read_b128 v[192:195], v151 offset:4096
	ds_read_b128 v[196:199], v151 offset:5120
	ds_read_b128 v[200:203], v151 offset:6144
	ds_read_b128 v[224:227], v151 offset:7168
	global_load_lds_dwordx4 v[204:205], off
	v_lshl_add_u64 v[204:205], s[22:23], 0, v[142:143]
	s_add_i32 m0, s38, 0xe000
	s_nop 0
	global_load_lds_dwordx4 v[204:205], off
	s_waitcnt vmcnt(8)
	s_waitcnt lgkmcnt(0)
	s_barrier
	s_setprio 1
	s_waitcnt lgkmcnt(0)
	v_mfma_f32_16x16x32_bf16 v[126:129], v[138:141], v[176:179], v[126:129]
	v_mfma_f32_16x16x32_bf16 v[122:125], v[152:155], v[176:179], v[122:125]
	v_mfma_f32_16x16x32_bf16 v[110:113], v[138:141], v[184:187], v[110:113]
	v_mfma_f32_16x16x32_bf16 v[106:109], v[152:155], v[184:187], v[106:109]
	v_mfma_f32_16x16x32_bf16 v[94:97], v[138:141], v[192:195], v[94:97]
	v_mfma_f32_16x16x32_bf16 v[90:93], v[152:155], v[192:195], v[90:93]
	v_mfma_f32_16x16x32_bf16 v[78:81], v[138:141], v[200:203], v[78:81]
	v_mfma_f32_16x16x32_bf16 v[74:77], v[152:155], v[200:203], v[74:77]
	v_mfma_f32_16x16x32_bf16 v[126:129], v[144:147], v[180:183], v[126:129]
	v_mfma_f32_16x16x32_bf16 v[122:125], v[156:159], v[180:183], v[122:125]
	v_mfma_f32_16x16x32_bf16 v[110:113], v[144:147], v[188:191], v[110:113]
	v_mfma_f32_16x16x32_bf16 v[106:109], v[156:159], v[188:191], v[106:109]
	v_mfma_f32_16x16x32_bf16 v[94:97], v[144:147], v[196:199], v[94:97]
	v_mfma_f32_16x16x32_bf16 v[90:93], v[156:159], v[196:199], v[90:93]
	v_mfma_f32_16x16x32_bf16 v[78:81], v[144:147], v[224:227], v[78:81]
	v_mfma_f32_16x16x32_bf16 v[74:77], v[156:159], v[224:227], v[74:77]
	v_mfma_f32_16x16x32_bf16 v[118:121], v[160:163], v[176:179], v[118:121]
	v_mfma_f32_16x16x32_bf16 v[114:117], v[168:171], v[176:179], v[114:117]
	v_mfma_f32_16x16x32_bf16 v[102:105], v[160:163], v[184:187], v[102:105]
	v_mfma_f32_16x16x32_bf16 v[98:101], v[168:171], v[184:187], v[98:101]
	v_mfma_f32_16x16x32_bf16 v[86:89], v[160:163], v[192:195], v[86:89]
	v_mfma_f32_16x16x32_bf16 v[82:85], v[168:171], v[192:195], v[82:85]
	v_mfma_f32_16x16x32_bf16 v[70:73], v[160:163], v[200:203], v[70:73]
	v_mfma_f32_16x16x32_bf16 v[66:69], v[168:171], v[200:203], v[66:69]
	v_mfma_f32_16x16x32_bf16 v[118:121], v[164:167], v[180:183], v[118:121]
	v_mfma_f32_16x16x32_bf16 v[114:117], v[172:175], v[180:183], v[114:117]
	v_mfma_f32_16x16x32_bf16 v[102:105], v[164:167], v[188:191], v[102:105]
	v_mfma_f32_16x16x32_bf16 v[98:101], v[172:175], v[188:191], v[98:101]
	v_mfma_f32_16x16x32_bf16 v[86:89], v[164:167], v[196:199], v[86:89]
	v_mfma_f32_16x16x32_bf16 v[82:85], v[172:175], v[196:199], v[82:85]
	v_mfma_f32_16x16x32_bf16 v[70:73], v[164:167], v[224:227], v[70:73]
	v_mfma_f32_16x16x32_bf16 v[66:69], v[172:175], v[224:227], v[66:69]
	s_setprio 0
	s_barrier
	s_add_i32 s51, s51, s31
	v_lshl_add_u64 v[204:205], s[24:25], 0, v[0:1]
	s_mov_b32 m0, s51
	ds_read_b128 v[176:179], v151 offset:16384
	ds_read_b128 v[180:183], v151 offset:17408
	ds_read_b128 v[184:187], v151 offset:18432
	ds_read_b128 v[188:191], v151 offset:19456
	ds_read_b128 v[192:195], v151 offset:20480
	ds_read_b128 v[196:199], v151 offset:21504
	ds_read_b128 v[200:203], v151 offset:22528
	ds_read_b128 v[224:227], v151 offset:23552
	global_load_lds_dwordx4 v[204:205], off
	s_add_i32 m0, s51, 0x2000
	s_add_u32 s52, s24, 0x40000
	v_lshl_add_u64 v[228:229], s[24:25], 0, v[134:135]
	s_addc_u32 s53, s25, 0
	s_add_i32 s51, s55, s31
	global_load_lds_dwordx4 v[228:229], off
	v_lshl_add_u64 v[230:231], s[52:53], 0, v[0:1]
	s_mov_b32 m0, s51
	v_lshl_add_u64 v[232:233], s[26:27], 0, v[132:133]
	global_load_lds_dwordx4 v[230:231], off
	v_lshl_add_u64 v[230:231], s[52:53], 0, v[134:135]
	s_add_i32 m0, s51, 0x2000
	s_nop 0
	global_load_lds_dwordx4 v[230:231], off
	v_lshl_add_u64 v[230:231], s[26:27], 0, v[130:131]
	s_mov_b32 m0, s38
	s_nop 0
	global_load_lds_dwordx4 v[230:231], off
	s_mov_b32 m0, s39
	s_nop 0
	global_load_lds_dwordx4 v[232:233], off
	s_waitcnt vmcnt(8)
	s_waitcnt lgkmcnt(0)
	s_barrier
; #define PG8_STAGE(bufoff, gbase, voff) do { _Pragma("unroll") for (int _i = 0; _i < 2; ++_i) \
;         __builtin_amdgcn_global_load_lds((const unsigned*)((const char*)(gbase) + (voff)[_i]), (PG8_LAS unsigned*)(lds + (bufoff) + ldsw + _i * 8192), 16, 0, 0); } while (0)
; #define PG8_LDA(dst, b, h) do { _Pragma("unroll") for (int m = 0; m < 4; ++m) _Pragma("unroll") for (int k = 0; k < 2; ++k) dst[m][k] = *(const PG8_LAS bf16x8*)(lds + PG8_SA(b, h) + aoff + m * 2048 + k * 1024); } while (0)
; #define PG8_LDB(dst, b, h) do { _Pragma("unroll") for (int n = 0; n < 2; ++n) _Pragma("unroll") for (int k = 0; k < 2; ++k) dst[n][k] = *(const PG8_LAS bf16x8*)(lds + PG8_SB(b, h) + boff + n * 2048 + k * 1024); } while (0)
; #define PG8_MMA(ai, bj, At, Bt) do { __builtin_amdgcn_s_setprio(1); _Pragma("unroll") for (int m = 0; m < 4; ++m) _Pragma("unroll") for (int n = 0; n < 2; ++n) _Pragma("unroll") for (int k = 0; k < 2; ++k) \
;         acc[ai][bj][m][n] = __builtin_amdgcn_mfma_f32_16x16x32_bf16(Bt[n][k], At[m][k], acc[ai][bj][m][n], 0, 0, 0); __builtin_amdgcn_s_setprio(0); } while (0)
; #define PG8_WAIT_V(n) asm volatile("s_waitcnt vmcnt(" #n ")" ::: "memory")
; #define PG8_WAIT_L(n) asm volatile("s_waitcnt lgkmcnt(" #n ")" ::: "memory")
; #define PG8_BAR __builtin_amdgcn_s_barrier()
; #define PG8_SCHED __builtin_amdgcn_sched_barrier(0)
; template <class Epi, class Sched, bool ALIGN_EPI = false, bool SP2 = false>
; __device__ __forceinline__ void gemm_phase(PG8_LAS unsigned char* lds, const Gemm g, const Sched& S, const Epi& E) {
;     ...
;             PG8_WAIT_V(8); PG8_WAIT_L(0); PG8_BAR; PG8_MMA(1, 0, At, B0); PG8_MMA(1, 1, At, B1); PG8_BAR; PG8_SCHED;
;             PG8_LDB(B0, 1, 0); PG8_LDB(B1, 1, 1); PG8_SCHED; PG8_LDA(At, 1, 0); PG8_STAGE(PG8_SA(0, 1), a2 + hstep, voffA);
;             PG8_WAIT_V(8); PG8_WAIT_L(0); PG8_BAR; PG8_MMA(0, 0, At, B0); PG8_MMA(0, 1, At, B1); PG8_BAR; PG8_SCHED;
	s_setprio 1
	s_waitcnt lgkmcnt(0)
	v_mfma_f32_16x16x32_bf16 v[62:65], v[138:141], v[176:179], v[62:65]
	v_mfma_f32_16x16x32_bf16 v[58:61], v[152:155], v[176:179], v[58:61]
	v_mfma_f32_16x16x32_bf16 v[46:49], v[138:141], v[184:187], v[46:49]
	v_mfma_f32_16x16x32_bf16 v[42:45], v[152:155], v[184:187], v[42:45]
	v_mfma_f32_16x16x32_bf16 v[30:33], v[138:141], v[192:195], v[30:33]
	v_mfma_f32_16x16x32_bf16 v[26:29], v[152:155], v[192:195], v[26:29]
	v_mfma_f32_16x16x32_bf16 v[14:17], v[138:141], v[200:203], v[14:17]
	v_mfma_f32_16x16x32_bf16 v[10:13], v[152:155], v[200:203], v[10:13]
	v_mfma_f32_16x16x32_bf16 v[62:65], v[144:147], v[180:183], v[62:65]
	v_mfma_f32_16x16x32_bf16 v[58:61], v[156:159], v[180:183], v[58:61]
	v_mfma_f32_16x16x32_bf16 v[46:49], v[144:147], v[188:191], v[46:49]
	v_mfma_f32_16x16x32_bf16 v[42:45], v[156:159], v[188:191], v[42:45]
	v_mfma_f32_16x16x32_bf16 v[30:33], v[144:147], v[196:199], v[30:33]
	v_mfma_f32_16x16x32_bf16 v[26:29], v[156:159], v[196:199], v[26:29]
	v_mfma_f32_16x16x32_bf16 v[14:17], v[144:147], v[224:227], v[14:17]
	v_mfma_f32_16x16x32_bf16 v[10:13], v[156:159], v[224:227], v[10:13]
	v_mfma_f32_16x16x32_bf16 v[54:57], v[160:163], v[176:179], v[54:57]
	v_mfma_f32_16x16x32_bf16 v[50:53], v[168:171], v[176:179], v[50:53]
	v_mfma_f32_16x16x32_bf16 v[38:41], v[160:163], v[184:187], v[38:41]
	v_mfma_f32_16x16x32_bf16 v[34:37], v[168:171], v[184:187], v[34:37]
	v_mfma_f32_16x16x32_bf16 v[22:25], v[160:163], v[192:195], v[22:25]
	v_mfma_f32_16x16x32_bf16 v[18:21], v[168:171], v[192:195], v[18:21]
	v_mfma_f32_16x16x32_bf16 v[6:9], v[160:163], v[200:203], v[6:9]
	v_mfma_f32_16x16x32_bf16 v[2:5], v[168:171], v[200:203], v[2:5]
	v_mfma_f32_16x16x32_bf16 v[54:57], v[164:167], v[180:183], v[54:57]
	v_mfma_f32_16x16x32_bf16 v[50:53], v[172:175], v[180:183], v[50:53]
	v_mfma_f32_16x16x32_bf16 v[38:41], v[164:167], v[188:191], v[38:41]
	v_mfma_f32_16x16x32_bf16 v[34:37], v[172:175], v[188:191], v[34:37]
	v_mfma_f32_16x16x32_bf16 v[22:25], v[164:167], v[196:199], v[22:25]
	v_mfma_f32_16x16x32_bf16 v[18:21], v[172:175], v[196:199], v[18:21]
	v_mfma_f32_16x16x32_bf16 v[6:9], v[164:167], v[224:227], v[6:9]
	v_mfma_f32_16x16x32_bf16 v[2:5], v[172:175], v[224:227], v[2:5]
	s_setprio 0
	s_barrier
	s_add_i32 s51, 0, 0x18000
	s_add_i32 s52, 0, 0x1c000
	v_add_u32_e32 v156, s51, v149
	v_add_u32_e32 v172, s52, v149
	ds_read_b128 v[138:141], v156
	ds_read_b128 v[144:147], v156 offset:1024
	ds_read_b128 v[152:155], v156 offset:2048
	ds_read_b128 v[156:159], v156 offset:3072
	ds_read_b128 v[160:163], v172
	ds_read_b128 v[164:167], v172 offset:1024
	ds_read_b128 v[168:171], v172 offset:2048
	ds_read_b128 v[172:175], v172 offset:3072
	s_add_u32 s26, s26, 0x40000
	s_addc_u32 s27, s27, 0
	s_mov_b32 m0, s41
	v_lshl_add_u64 v[234:235], s[26:27], 0, v[130:131]
	ds_read_b128 v[176:179], v151 offset:32768
	ds_read_b128 v[180:183], v151 offset:33792
	ds_read_b128 v[184:187], v151 offset:34816
	ds_read_b128 v[188:191], v151 offset:35840
	ds_read_b128 v[192:195], v151 offset:36864
	ds_read_b128 v[196:199], v151 offset:37888
	ds_read_b128 v[200:203], v151 offset:38912
	ds_read_b128 v[224:227], v151 offset:39936
	global_load_lds_dwordx4 v[234:235], off
	v_lshl_add_u64 v[234:235], s[26:27], 0, v[132:133]
	s_mov_b32 m0, s42
	s_nop 0
	global_load_lds_dwordx4 v[234:235], off
	s_waitcnt vmcnt(8)
	s_waitcnt lgkmcnt(0)
	s_barrier
	s_setprio 1
	s_waitcnt lgkmcnt(0)
	v_mfma_f32_16x16x32_bf16 v[126:129], v[138:141], v[176:179], v[126:129]
	v_mfma_f32_16x16x32_bf16 v[122:125], v[152:155], v[176:179], v[122:125]
	v_mfma_f32_16x16x32_bf16 v[110:113], v[138:141], v[184:187], v[110:113]
	v_mfma_f32_16x16x32_bf16 v[106:109], v[152:155], v[184:187], v[106:109]
	v_mfma_f32_16x16x32_bf16 v[94:97], v[138:141], v[192:195], v[94:97]
	v_mfma_f32_16x16x32_bf16 v[90:93], v[152:155], v[192:195], v[90:93]
	v_mfma_f32_16x16x32_bf16 v[78:81], v[138:141], v[200:203], v[78:81]
	v_mfma_f32_16x16x32_bf16 v[74:77], v[152:155], v[200:203], v[74:77]
	v_mfma_f32_16x16x32_bf16 v[126:129], v[144:147], v[180:183], v[126:129]
	v_mfma_f32_16x16x32_bf16 v[122:125], v[156:159], v[180:183], v[122:125]
	v_mfma_f32_16x16x32_bf16 v[110:113], v[144:147], v[188:191], v[110:113]
	v_mfma_f32_16x16x32_bf16 v[106:109], v[156:159], v[188:191], v[106:109]
	v_mfma_f32_16x16x32_bf16 v[94:97], v[144:147], v[196:199], v[94:97]
	v_mfma_f32_16x16x32_bf16 v[90:93], v[156:159], v[196:199], v[90:93]
	v_mfma_f32_16x16x32_bf16 v[78:81], v[144:147], v[224:227], v[78:81]
	v_mfma_f32_16x16x32_bf16 v[74:77], v[156:159], v[224:227], v[74:77]
	v_mfma_f32_16x16x32_bf16 v[118:121], v[160:163], v[176:179], v[118:121]
	v_mfma_f32_16x16x32_bf16 v[114:117], v[168:171], v[176:179], v[114:117]
	v_mfma_f32_16x16x32_bf16 v[102:105], v[160:163], v[184:187], v[102:105]
	v_mfma_f32_16x16x32_bf16 v[98:101], v[168:171], v[184:187], v[98:101]
	v_mfma_f32_16x16x32_bf16 v[86:89], v[160:163], v[192:195], v[86:89]
	v_mfma_f32_16x16x32_bf16 v[82:85], v[168:171], v[192:195], v[82:85]
	v_mfma_f32_16x16x32_bf16 v[70:73], v[160:163], v[200:203], v[70:73]
	v_mfma_f32_16x16x32_bf16 v[66:69], v[168:171], v[200:203], v[66:69]
	v_mfma_f32_16x16x32_bf16 v[118:121], v[164:167], v[180:183], v[118:121]
	v_mfma_f32_16x16x32_bf16 v[114:117], v[172:175], v[180:183], v[114:117]
	v_mfma_f32_16x16x32_bf16 v[102:105], v[164:167], v[188:191], v[102:105]
	v_mfma_f32_16x16x32_bf16 v[98:101], v[172:175], v[188:191], v[98:101]
	v_mfma_f32_16x16x32_bf16 v[86:89], v[164:167], v[196:199], v[86:89]
	v_mfma_f32_16x16x32_bf16 v[82:85], v[172:175], v[196:199], v[82:85]
	v_mfma_f32_16x16x32_bf16 v[70:73], v[164:167], v[224:227], v[70:73]
	v_mfma_f32_16x16x32_bf16 v[66:69], v[172:175], v[224:227], v[66:69]
	s_setprio 0
	s_barrier
; #define PG8_STAGE(bufoff, gbase, voff) do { _Pragma("unroll") for (int _i = 0; _i < 2; ++_i) \
;         __builtin_amdgcn_global_load_lds((const unsigned*)((const char*)(gbase) + (voff)[_i]), (PG8_LAS unsigned*)(lds + (bufoff) + ldsw + _i * 8192), 16, 0, 0); } while (0)
; #define PG8_LDA(dst, b, h) do { _Pragma("unroll") for (int m = 0; m < 4; ++m) _Pragma("unroll") for (int k = 0; k < 2; ++k) dst[m][k] = *(const PG8_LAS bf16x8*)(lds + PG8_SA(b, h) + aoff + m * 2048 + k * 1024); } while (0)
; #define PG8_MMA(ai, bj, At, Bt) do { __builtin_amdgcn_s_setprio(1); _Pragma("unroll") for (int m = 0; m < 4; ++m) _Pragma("unroll") for (int n = 0; n < 2; ++n) _Pragma("unroll") for (int k = 0; k < 2; ++k) \
;         acc[ai][bj][m][n] = __builtin_amdgcn_mfma_f32_16x16x32_bf16(Bt[n][k], At[m][k], acc[ai][bj][m][n], 0, 0, 0); __builtin_amdgcn_s_setprio(0); } while (0)
; #define PG8_WAIT_V(n) asm volatile("s_waitcnt vmcnt(" #n ")" ::: "memory")
; #define PG8_WAIT_L(n) asm volatile("s_waitcnt lgkmcnt(" #n ")" ::: "memory")
; #define PG8_BAR __builtin_amdgcn_s_barrier()
; #define PG8_SCHED __builtin_amdgcn_sched_barrier(0)
; template <class Epi, class Sched, bool ALIGN_EPI = false, bool SP2 = false>
; __device__ __forceinline__ void gemm_phase(PG8_LAS unsigned char* lds, const Gemm g, const Sched& S, const Epi& E) {
;     ...
;             PG8_LDA(At, 1, 1); PG8_STAGE(PG8_SB(1, 0), b3, voffB); PG8_STAGE(PG8_SB(1, 1), b3 + hstep, voffB); PG8_STAGE(PG8_SA(1, 0), a3, voffA);
;             PG8_WAIT_V(8); PG8_WAIT_L(0); PG8_BAR; PG8_MMA(1, 0, At, B0); PG8_MMA(1, 1, At, B1); PG8_BAR; PG8_SCHED;
;     __device__ __forceinline__ void operator()(const f32x4 (&acc)[2][2][4][2], const Unit& u, int wr, int wc, int fr, int fq) const {
;     ...
;                 const int row = row0 + ai * 128 + m * 16; float p = 0.f;
; #pragma unroll
;                 for (int bj = 0; bj < 2; ++bj) {
;                     const size_t off = (size_t)row * D + col0 + bj * 128;
;                     const u32x4 xx = *(const u32x4*)(xb + off);
	s_add_i32 s26, s51, s31
	v_lshl_add_u64 v[204:205], v[204:205], 0, s[86:87]
	s_mov_b32 m0, s26
	ds_read_b128 v[176:179], v151 offset:49152
	ds_read_b128 v[180:183], v151 offset:50176
	ds_read_b128 v[184:187], v151 offset:51200
	ds_read_b128 v[188:191], v151 offset:52224
	ds_read_b128 v[192:195], v151 offset:53248
	ds_read_b128 v[196:199], v151 offset:54272
	ds_read_b128 v[200:203], v151 offset:55296
	ds_read_b128 v[224:227], v151 offset:56320
	global_load_lds_dwordx4 v[204:205], off
	s_add_i32 m0, s26, 0x2000
	s_add_u32 s24, s24, 0x40080
	v_lshl_add_u64 v[204:205], v[228:229], 0, s[86:87]
	s_addc_u32 s25, s25, 0
	s_add_i32 s26, s52, s31
	global_load_lds_dwordx4 v[204:205], off
	v_lshl_add_u64 v[204:205], s[24:25], 0, v[0:1]
	s_mov_b32 m0, s26
	s_nop 0
	global_load_lds_dwordx4 v[204:205], off
	v_lshl_add_u64 v[204:205], s[24:25], 0, v[134:135]
	s_add_i32 m0, s26, 0x2000
	s_nop 0
	global_load_lds_dwordx4 v[204:205], off
	v_lshl_add_u64 v[204:205], v[230:231], 0, s[86:87]
	s_mov_b32 m0, s44
	s_nop 0
	global_load_lds_dwordx4 v[204:205], off
	v_lshl_add_u64 v[204:205], v[232:233], 0, s[86:87]
	s_mov_b32 m0, s45
	s_nop 0
	global_load_lds_dwordx4 v[204:205], off
	s_waitcnt vmcnt(8)
	s_waitcnt lgkmcnt(0)
	s_barrier
	s_setprio 1
	s_waitcnt lgkmcnt(0)
	v_mfma_f32_16x16x32_bf16 v[62:65], v[138:141], v[176:179], v[62:65]
	v_mfma_f32_16x16x32_bf16 v[58:61], v[152:155], v[176:179], v[58:61]
	v_mfma_f32_16x16x32_bf16 v[46:49], v[138:141], v[184:187], v[46:49]
	v_mfma_f32_16x16x32_bf16 v[42:45], v[152:155], v[184:187], v[42:45]
	v_mfma_f32_16x16x32_bf16 v[30:33], v[138:141], v[192:195], v[30:33]
	v_mfma_f32_16x16x32_bf16 v[26:29], v[152:155], v[192:195], v[26:29]
	v_mfma_f32_16x16x32_bf16 v[14:17], v[138:141], v[200:203], v[14:17]
	v_mfma_f32_16x16x32_bf16 v[10:13], v[152:155], v[200:203], v[10:13]
	v_mfma_f32_16x16x32_bf16 v[62:65], v[144:147], v[180:183], v[62:65]
	v_mfma_f32_16x16x32_bf16 v[58:61], v[156:159], v[180:183], v[58:61]
	v_mfma_f32_16x16x32_bf16 v[46:49], v[144:147], v[188:191], v[46:49]
	v_mfma_f32_16x16x32_bf16 v[42:45], v[156:159], v[188:191], v[42:45]
	v_mfma_f32_16x16x32_bf16 v[30:33], v[144:147], v[196:199], v[30:33]
	v_mfma_f32_16x16x32_bf16 v[26:29], v[156:159], v[196:199], v[26:29]
	v_mfma_f32_16x16x32_bf16 v[14:17], v[144:147], v[224:227], v[14:17]
	v_mfma_f32_16x16x32_bf16 v[10:13], v[156:159], v[224:227], v[10:13]
	v_mfma_f32_16x16x32_bf16 v[54:57], v[160:163], v[176:179], v[54:57]
	v_mfma_f32_16x16x32_bf16 v[50:53], v[168:171], v[176:179], v[50:53]
	v_mfma_f32_16x16x32_bf16 v[38:41], v[160:163], v[184:187], v[38:41]
	v_mfma_f32_16x16x32_bf16 v[34:37], v[168:171], v[184:187], v[34:37]
	v_mfma_f32_16x16x32_bf16 v[22:25], v[160:163], v[192:195], v[22:25]
	v_mfma_f32_16x16x32_bf16 v[18:21], v[168:171], v[192:195], v[18:21]
	v_mfma_f32_16x16x32_bf16 v[6:9], v[160:163], v[200:203], v[6:9]
	v_mfma_f32_16x16x32_bf16 v[2:5], v[168:171], v[200:203], v[2:5]
	v_mfma_f32_16x16x32_bf16 v[54:57], v[164:167], v[180:183], v[54:57]
	v_mfma_f32_16x16x32_bf16 v[50:53], v[172:175], v[180:183], v[50:53]
	v_mfma_f32_16x16x32_bf16 v[38:41], v[164:167], v[188:191], v[38:41]
	v_mfma_f32_16x16x32_bf16 v[34:37], v[172:175], v[188:191], v[34:37]
	v_mfma_f32_16x16x32_bf16 v[22:25], v[164:167], v[196:199], v[22:25]
	v_mfma_f32_16x16x32_bf16 v[18:21], v[172:175], v[196:199], v[18:21]
	v_mfma_f32_16x16x32_bf16 v[6:9], v[164:167], v[224:227], v[6:9]
	v_mfma_f32_16x16x32_bf16 v[2:5], v[172:175], v[224:227], v[2:5]
	s_setprio 0
	s_barrier
	s_add_i32 s50, s50, 2
	s_add_u32 s22, s22, 0x100
	s_addc_u32 s23, s23, 0
	s_add_u32 s48, s48, 0x100
	s_addc_u32 s49, s49, 0
	s_cmp_gt_u32 s50, 13
	s_cbranch_scc0 .LBB0_1050
	v_lshl_add_u32 v138, s20, 8, v148
	v_lshl_or_b32 v139, s18, 8, v150
	v_lshlrev_b32_e32 v138, 11, v138
	v_lshl_add_u32 v138, v139, 1, v138
	global_load_dwordx4 v[152:155], v138, s[34:35]
	global_load_dwordx4 v[156:159], v138, s[34:35] offset:256
	v_add_u32_e32 v139, 0x8000, v138
	global_load_dwordx4 v[160:163], v139, s[34:35]
	global_load_dwordx4 v[164:167], v139, s[34:35] offset:256
	v_add_u32_e32 v139, 0x10000, v138
	global_load_dwordx4 v[168:171], v139, s[34:35]
	global_load_dwordx4 v[172:175], v139, s[34:35] offset:256
	v_add_u32_e32 v139, 0x18000, v138
	global_load_dwordx4 v[176:179], v139, s[34:35]
	global_load_dwordx4 v[180:183], v139, s[34:35] offset:256
	v_add_u32_e32 v139, 0x40000, v138
	global_load_dwordx4 v[184:187], v139, s[34:35]
	global_load_dwordx4 v[188:191], v139, s[34:35] offset:256
	v_add_u32_e32 v139, 0x48000, v138
	global_load_dwordx4 v[192:195], v139, s[34:35]
	global_load_dwordx4 v[196:199], v139, s[34:35] offset:256
	v_add_u32_e32 v139, 0x50000, v138
	global_load_dwordx4 v[200:203], v139, s[34:35]
	global_load_dwordx4 v[224:227], v139, s[34:35] offset:256
	v_add_u32_e32 v139, 0x58000, v138
	global_load_dwordx4 v[228:231], v139, s[34:35]
	global_load_dwordx4 v[232:235], v139, s[34:35] offset:256
	s_and_b64 vcc, exec, s[8:9]
	s_cbranch_vccz .LBB0_1053
	s_barrier
